# H2 + lgkmcnt(11) before the last four ds_reads of each 16-read segment (keeps at most 15 LDS reads outstanding)
# speedup vs baseline: 1.0069x; 1.0018x over previous
; #define PG8_STAGE(bufoff, gbase, voff) do { _Pragma("unroll") for (int _i = 0; _i < 2; ++_i) \
;         __builtin_amdgcn_global_load_lds((const unsigned*)((const char*)(gbase) + (voff)[_i]), (PG8_LAS unsigned*)(lds + (bufoff) + ldsw + _i * 8192), 16, 0, 0); } while (0)
; #define PG8_LDA(dst, b, h) do { _Pragma("unroll") for (int m = 0; m < 4; ++m) _Pragma("unroll") for (int k = 0; k < 2; ++k) dst[m][k] = *(const PG8_LAS bf16x8*)(lds + PG8_SA(b, h) + aoff + m * 2048 + k * 1024); } while (0)
; #define PG8_LDB(dst, b, h) do { _Pragma("unroll") for (int n = 0; n < 2; ++n) _Pragma("unroll") for (int k = 0; k < 2; ++k) dst[n][k] = *(const PG8_LAS bf16x8*)(lds + PG8_SB(b, h) + boff + n * 2048 + k * 1024); } while (0)
; #define PG8_WAIT_V(n) asm volatile("s_waitcnt vmcnt(" #n ")" ::: "memory")
; #define PG8_WAIT_L(n) asm volatile("s_waitcnt lgkmcnt(" #n ")" ::: "memory")
; #define PG8_BAR __builtin_amdgcn_s_barrier()
; #define PG8_SCHED __builtin_amdgcn_sched_barrier(0)
; template <class Epi, class Sched>
; __device__ __forceinline__ void gemm_phase(PG8_LAS unsigned char* lds, const Gemm g, const Sched& S, const Epi& E) {
;     ...
;     for (;;) {
;         const bool has_next = S.next(ui + 1, nxt);
;         const char* nA = has_next ? (const char*)g.A + (size_t)nxt.pm * tstep : cA; const char* nB = has_next ? (const char*)g.Bt + (size_t)nxt.pn * tstep : cB;
;         for (int t = 0; t < nt; t += 2) {
;             const bool last = (t == nt - 2);
;             const char* a1 = cA + (size_t)(t + 1) * kstep;
;             const char* a2 = last ? nA : cA + (size_t)(t + 2) * kstep; const char* b2 = last ? nB : cB + (size_t)(t + 2) * kstep;
;             const char* a3 = a2 + kstep; const char* b3 = b2 + kstep;
;             if (last && has_next) S.a_ready(nxt);
;             PG8_LDB(B0, 0, 0); PG8_SCHED; PG8_LDA(At, 0, 0); PG8_STAGE(PG8_SA(1, 1), a1 + hstep, voffA);
;             PG8_WAIT_L(8); PG8_BAR; PG8_WAIT_L(0); PG8_MMA(0, 0, At, B0); PG8_BAR; PG8_SCHED;
;             PG8_LDB(B1, 0, 1); PG8_STAGE(PG8_SB(0, 0), b2, voffB);
;             PG8_BAR; PG8_WAIT_L(0); PG8_MMA(0, 1, At, B1); PG8_BAR;
;             PG8_LDA(At, 0, 1); PG8_STAGE(PG8_SA(0, 0), a2, voffA);
;             PG8_BAR; PG8_WAIT_L(0); PG8_MMA(1, 0, At, B0); PG8_BAR; PG8_SCHED;
;             PG8_STAGE(PG8_SB(0, 1), b2 + hstep, voffB);
;             PG8_WAIT_V(6); PG8_BAR; PG8_MMA(1, 1, At, B1); PG8_BAR;
.LBB0_234:
	s_ashr_i32 s49, s48, 31
	v_cmp_lt_i64_e32 vcc, s[50:51], v[152:153]
	s_lshl_b64 s[50:51], s[48:49], 20
	s_add_u32 s50, s76, s50
	s_addc_u32 s51, s77, s51
	s_and_b64 s[64:65], vcc, exec
	s_cselect_b32 s0, s51, s69
	s_cselect_b32 s5, s50, s68
	s_ashr_i32 s47, s46, 31
	s_lshl_b64 s[64:65], s[46:47], 20
	s_add_u32 s64, s58, s64
	s_addc_u32 s65, s59, s65
	s_and_b64 s[72:73], vcc, exec
	s_cselect_b32 s47, s65, s71
	s_cselect_b32 s49, s64, s70
	s_add_u32 s68, s68, 0x80080
	s_addc_u32 s69, s69, 0
	s_add_u32 s97, s70, 0x100
	s_addc_u32 vcc_lo, s71, 0
	s_mov_b32 vcc_hi, -2
	s_setprio 0
	ds_read_b128 v[128:131], v162
	ds_read_b128 v[132:135], v162 offset:1024
	ds_read_b128 v[154:157], v162 offset:2048
	ds_read_b128 v[166:169], v162 offset:3072
	ds_read_b128 v[170:173], v163
	ds_read_b128 v[174:177], v163 offset:1024
	ds_read_b128 v[178:181], v163 offset:2048
	ds_read_b128 v[182:185], v163 offset:3072
	ds_read_b128 v[186:189], v163 offset:4096
	ds_read_b128 v[190:193], v163 offset:5120
	ds_read_b128 v[194:197], v163 offset:6144
	ds_read_b128 v[198:201], v163 offset:7168
	s_waitcnt lgkmcnt(11)
	ds_read_b128 v[202:205], v164
	ds_read_b128 v[206:209], v164 offset:1024
	ds_read_b128 v[210:213], v164 offset:2048
	ds_read_b128 v[214:217], v164 offset:3072
	s_add_u32 s10, s68, 0xfff80080
	s_addc_u32 s11, s69, -1
	s_cmp_eq_u32 vcc_hi, 28
	s_cselect_b32 s73, s0, s11
	s_cselect_b32 s72, s5, s10
	s_cselect_b32 s71, s47, vcc_lo
	s_cselect_b32 s70, s49, s97
	v_lshl_add_u64 v[158:159], s[68:69], 0, v[148:149]
	s_add_i32 m0, s67, 0xc000
	s_nop 0
	global_load_lds_dwordx4 v[158:159], off
	v_lshl_add_u64 v[158:159], s[68:69], 0, v[150:151]
	s_add_i32 m0, s67, 0xe000
	s_nop 0
	global_load_lds_dwordx4 v[158:159], off
	s_waitcnt vmcnt(8)
	s_waitcnt lgkmcnt(0)
	s_setprio 1
	s_barrier
	v_mfma_f32_16x16x32_bf16 v[124:127], v[128:131], v[170:173], 0
	v_mfma_f32_16x16x32_bf16 v[120:123], v[154:157], v[170:173], 0
	v_mfma_f32_16x16x32_bf16 v[116:119], v[128:131], v[178:181], 0
	v_mfma_f32_16x16x32_bf16 v[112:115], v[154:157], v[178:181], 0
	v_mfma_f32_16x16x32_bf16 v[108:111], v[128:131], v[186:189], 0
	v_mfma_f32_16x16x32_bf16 v[104:107], v[154:157], v[186:189], 0
	v_mfma_f32_16x16x32_bf16 v[100:103], v[128:131], v[194:197], 0
	v_mfma_f32_16x16x32_bf16 v[96:99], v[154:157], v[194:197], 0
	v_mfma_f32_16x16x32_bf16 v[124:127], v[132:135], v[174:177], v[124:127]
	v_mfma_f32_16x16x32_bf16 v[120:123], v[166:169], v[174:177], v[120:123]
	v_mfma_f32_16x16x32_bf16 v[116:119], v[132:135], v[182:185], v[116:119]
	v_mfma_f32_16x16x32_bf16 v[112:115], v[166:169], v[182:185], v[112:115]
	v_mfma_f32_16x16x32_bf16 v[108:111], v[132:135], v[190:193], v[108:111]
	v_mfma_f32_16x16x32_bf16 v[104:107], v[166:169], v[190:193], v[104:107]
	v_mfma_f32_16x16x32_bf16 v[100:103], v[132:135], v[198:201], v[100:103]
	v_mfma_f32_16x16x32_bf16 v[96:99], v[166:169], v[198:201], v[96:99]
	v_mfma_f32_16x16x32_bf16 v[60:63], v[202:205], v[170:173], 0
	v_mfma_f32_16x16x32_bf16 v[56:59], v[210:213], v[170:173], 0
	v_mfma_f32_16x16x32_bf16 v[52:55], v[202:205], v[178:181], 0
	v_mfma_f32_16x16x32_bf16 v[48:51], v[210:213], v[178:181], 0
	v_mfma_f32_16x16x32_bf16 v[44:47], v[202:205], v[186:189], 0
	v_mfma_f32_16x16x32_bf16 v[40:43], v[210:213], v[186:189], 0
	v_mfma_f32_16x16x32_bf16 v[36:39], v[202:205], v[194:197], 0
	v_mfma_f32_16x16x32_bf16 v[32:35], v[210:213], v[194:197], 0
	v_mfma_f32_16x16x32_bf16 v[60:63], v[206:209], v[174:177], v[60:63]
	v_mfma_f32_16x16x32_bf16 v[56:59], v[214:217], v[174:177], v[56:59]
	v_mfma_f32_16x16x32_bf16 v[52:55], v[206:209], v[182:185], v[52:55]
	v_mfma_f32_16x16x32_bf16 v[48:51], v[214:217], v[182:185], v[48:51]
	v_mfma_f32_16x16x32_bf16 v[44:47], v[206:209], v[190:193], v[44:47]
	v_mfma_f32_16x16x32_bf16 v[40:43], v[214:217], v[190:193], v[40:43]
	v_mfma_f32_16x16x32_bf16 v[36:39], v[206:209], v[198:201], v[36:39]
	v_mfma_f32_16x16x32_bf16 v[32:35], v[214:217], v[198:201], v[32:35]
	s_barrier
	s_setprio 0
	ds_read_b128 v[170:173], v163 offset:16384
	ds_read_b128 v[174:177], v163 offset:17408
	ds_read_b128 v[178:181], v163 offset:18432
	ds_read_b128 v[182:185], v163 offset:19456
	ds_read_b128 v[186:189], v163 offset:20480
	ds_read_b128 v[190:193], v163 offset:21504
	ds_read_b128 v[194:197], v163 offset:22528
	ds_read_b128 v[198:201], v163 offset:23552
	s_add_i32 s10, s90, s78
	v_lshl_add_u64 v[158:159], s[70:71], 0, v[138:139]
	s_mov_b32 m0, s10
	s_nop 0
	global_load_lds_dwordx4 v[158:159], off
	v_lshl_add_u64 v[218:219], s[70:71], 0, v[142:143]
	s_add_i32 m0, s10, 0x2000
	s_nop 0
	global_load_lds_dwordx4 v[218:219], off
	s_mov_b32 m0, s67
	v_lshl_add_u64 v[220:221], s[72:73], 0, v[136:137]
	global_load_lds_dwordx4 v[220:221], off
	v_lshl_add_u64 v[222:223], s[72:73], 0, v[140:141]
	s_mov_b32 m0, s79
	s_nop 0
	global_load_lds_dwordx4 v[222:223], off
	s_add_u32 s10, s70, 0x80000
	s_addc_u32 s11, s71, 0
	s_add_i32 s33, s91, s78
	v_lshl_add_u64 v[224:225], s[10:11], 0, v[138:139]
	s_mov_b32 m0, s33
	s_nop 0
	global_load_lds_dwordx4 v[224:225], off
	v_lshl_add_u64 v[224:225], s[10:11], 0, v[142:143]
	s_add_i32 m0, s33, 0x2000
	s_nop 0
	global_load_lds_dwordx4 v[224:225], off
	s_waitcnt vmcnt(8)
	s_waitcnt lgkmcnt(0)
	s_setprio 1
	s_barrier
; #define PG8_STAGE(bufoff, gbase, voff) do { _Pragma("unroll") for (int _i = 0; _i < 2; ++_i) \
;         __builtin_amdgcn_global_load_lds((const unsigned*)((const char*)(gbase) + (voff)[_i]), (PG8_LAS unsigned*)(lds + (bufoff) + ldsw + _i * 8192), 16, 0, 0); } while (0)
; #define PG8_LDA(dst, b, h) do { _Pragma("unroll") for (int m = 0; m < 4; ++m) _Pragma("unroll") for (int k = 0; k < 2; ++k) dst[m][k] = *(const PG8_LAS bf16x8*)(lds + PG8_SA(b, h) + aoff + m * 2048 + k * 1024); } while (0)
; #define PG8_LDB(dst, b, h) do { _Pragma("unroll") for (int n = 0; n < 2; ++n) _Pragma("unroll") for (int k = 0; k < 2; ++k) dst[n][k] = *(const PG8_LAS bf16x8*)(lds + PG8_SB(b, h) + boff + n * 2048 + k * 1024); } while (0)
; #define PG8_MMA(ai, bj, At, Bt) do { __builtin_amdgcn_s_setprio(1); _Pragma("unroll") for (int m = 0; m < 4; ++m) _Pragma("unroll") for (int n = 0; n < 2; ++n) _Pragma("unroll") for (int k = 0; k < 2; ++k) \
;         acc[ai][bj][m][n] = __builtin_amdgcn_mfma_f32_16x16x32_bf16(Bt[n][k], At[m][k], acc[ai][bj][m][n], 0, 0, 0); __builtin_amdgcn_s_setprio(0); } while (0)
; #define PG8_WAIT_V(n) asm volatile("s_waitcnt vmcnt(" #n ")" ::: "memory")
; #define PG8_WAIT_L(n) asm volatile("s_waitcnt lgkmcnt(" #n ")" ::: "memory")
; #define PG8_BAR __builtin_amdgcn_s_barrier()
; #define PG8_SCHED __builtin_amdgcn_sched_barrier(0)
; template <class Epi, class Sched>
; __device__ __forceinline__ void gemm_phase(PG8_LAS unsigned char* lds, const Gemm g, const Sched& S, const Epi& E) {
;     ...
;             PG8_BAR; PG8_WAIT_L(0); PG8_MMA(1, 0, At, B0); PG8_BAR; PG8_SCHED;
;             PG8_STAGE(PG8_SB(0, 1), b2 + hstep, voffB);
;             PG8_WAIT_V(6); PG8_BAR; PG8_MMA(1, 1, At, B1); PG8_BAR;
;             PG8_LDB(B0, 1, 0); PG8_SCHED; PG8_LDA(At, 1, 0); PG8_STAGE(PG8_SA(0, 1), a2 + hstep, voffA);
;             PG8_WAIT_L(8); PG8_BAR; PG8_WAIT_L(0); PG8_MMA(0, 0, At, B0); PG8_BAR; PG8_SCHED;
;             PG8_LDB(B1, 1, 1); PG8_STAGE(PG8_SB(1, 0), b3, voffB);
;             PG8_BAR; PG8_WAIT_L(0); PG8_MMA(0, 1, At, B1); PG8_BAR;
;             PG8_LDA(At, 1, 1); PG8_STAGE(PG8_SA(1, 0), a3, voffA);
;             PG8_BAR; PG8_WAIT_L(0); PG8_MMA(1, 0, At, B0); PG8_BAR; PG8_SCHED;
	v_mfma_f32_16x16x32_bf16 v[92:95], v[128:131], v[170:173], 0
	v_mfma_f32_16x16x32_bf16 v[88:91], v[154:157], v[170:173], 0
	v_mfma_f32_16x16x32_bf16 v[84:87], v[128:131], v[178:181], 0
	v_mfma_f32_16x16x32_bf16 v[80:83], v[154:157], v[178:181], 0
	v_mfma_f32_16x16x32_bf16 v[76:79], v[128:131], v[186:189], 0
	v_mfma_f32_16x16x32_bf16 v[72:75], v[154:157], v[186:189], 0
	v_mfma_f32_16x16x32_bf16 v[68:71], v[128:131], v[194:197], 0
	v_mfma_f32_16x16x32_bf16 v[64:67], v[154:157], v[194:197], 0
	s_add_i32 s33, 0, 0x18000
	v_add_u32_e32 v144, s33, v160
	v_mfma_f32_16x16x32_bf16 v[92:95], v[132:135], v[174:177], v[92:95]
	v_mfma_f32_16x16x32_bf16 v[88:91], v[166:169], v[174:177], v[88:91]
	v_mfma_f32_16x16x32_bf16 v[84:87], v[132:135], v[182:185], v[84:87]
	v_mfma_f32_16x16x32_bf16 v[80:83], v[166:169], v[182:185], v[80:83]
	v_mfma_f32_16x16x32_bf16 v[76:79], v[132:135], v[190:193], v[76:79]
	v_mfma_f32_16x16x32_bf16 v[72:75], v[166:169], v[190:193], v[72:75]
	v_mfma_f32_16x16x32_bf16 v[68:71], v[132:135], v[198:201], v[68:71]
	v_mfma_f32_16x16x32_bf16 v[64:67], v[166:169], v[198:201], v[64:67]
	v_mfma_f32_16x16x32_bf16 v[28:31], v[202:205], v[170:173], 0
	v_mfma_f32_16x16x32_bf16 v[24:27], v[210:213], v[170:173], 0
	v_mfma_f32_16x16x32_bf16 v[20:23], v[202:205], v[178:181], 0
	v_mfma_f32_16x16x32_bf16 v[16:19], v[210:213], v[178:181], 0
	v_mfma_f32_16x16x32_bf16 v[12:15], v[202:205], v[186:189], 0
	v_mfma_f32_16x16x32_bf16 v[8:11], v[210:213], v[186:189], 0
	v_mfma_f32_16x16x32_bf16 v[4:7], v[202:205], v[194:197], 0
	v_mfma_f32_16x16x32_bf16 v[0:3], v[210:213], v[194:197], 0
	v_mfma_f32_16x16x32_bf16 v[28:31], v[206:209], v[174:177], v[28:31]
	v_mfma_f32_16x16x32_bf16 v[24:27], v[214:217], v[174:177], v[24:27]
	v_mfma_f32_16x16x32_bf16 v[20:23], v[206:209], v[182:185], v[20:23]
	v_mfma_f32_16x16x32_bf16 v[16:19], v[214:217], v[182:185], v[16:19]
	v_mfma_f32_16x16x32_bf16 v[12:15], v[206:209], v[190:193], v[12:15]
	v_mfma_f32_16x16x32_bf16 v[8:11], v[214:217], v[190:193], v[8:11]
	v_mfma_f32_16x16x32_bf16 v[4:7], v[206:209], v[198:201], v[4:7]
	v_mfma_f32_16x16x32_bf16 v[0:3], v[214:217], v[198:201], v[0:3]
	s_barrier
	s_setprio 0
	ds_read_b128 v[128:131], v162 offset:32768
	ds_read_b128 v[132:135], v162 offset:33792
	ds_read_b128 v[154:157], v162 offset:34816
	ds_read_b128 v[166:169], v162 offset:35840
	ds_read_b128 v[170:173], v163 offset:32768
	ds_read_b128 v[174:177], v163 offset:33792
	ds_read_b128 v[178:181], v163 offset:34816
	ds_read_b128 v[182:185], v163 offset:35840
	ds_read_b128 v[186:189], v163 offset:36864
	ds_read_b128 v[190:193], v163 offset:37888
	ds_read_b128 v[194:197], v163 offset:38912
	ds_read_b128 v[198:201], v163 offset:39936
	s_waitcnt lgkmcnt(11)
	ds_read_b128 v[202:205], v164 offset:32768
	ds_read_b128 v[206:209], v164 offset:33792
	ds_read_b128 v[210:213], v164 offset:34816
	ds_read_b128 v[214:217], v164 offset:35840
	s_add_u32 s10, s72, 0x80000
	s_addc_u32 s11, s73, 0
	s_mov_b32 m0, s80
	v_lshl_add_u64 v[224:225], s[10:11], 0, v[136:137]
	global_load_lds_dwordx4 v[224:225], off
	v_lshl_add_u64 v[224:225], s[10:11], 0, v[140:141]
	s_mov_b32 m0, s81
	s_nop 0
	global_load_lds_dwordx4 v[224:225], off
	s_waitcnt vmcnt(8)
	s_waitcnt lgkmcnt(0)
	s_setprio 1
	s_barrier
	v_mfma_f32_16x16x32_bf16 v[124:127], v[128:131], v[170:173], v[124:127]
	v_mfma_f32_16x16x32_bf16 v[120:123], v[154:157], v[170:173], v[120:123]
	v_mfma_f32_16x16x32_bf16 v[116:119], v[128:131], v[178:181], v[116:119]
	v_mfma_f32_16x16x32_bf16 v[112:115], v[154:157], v[178:181], v[112:115]
	v_mfma_f32_16x16x32_bf16 v[108:111], v[128:131], v[186:189], v[108:111]
	v_mfma_f32_16x16x32_bf16 v[104:107], v[154:157], v[186:189], v[104:107]
	v_mfma_f32_16x16x32_bf16 v[100:103], v[128:131], v[194:197], v[100:103]
	v_mfma_f32_16x16x32_bf16 v[96:99], v[154:157], v[194:197], v[96:99]
	v_mfma_f32_16x16x32_bf16 v[124:127], v[132:135], v[174:177], v[124:127]
	v_mfma_f32_16x16x32_bf16 v[120:123], v[166:169], v[174:177], v[120:123]
	v_mfma_f32_16x16x32_bf16 v[116:119], v[132:135], v[182:185], v[116:119]
	v_mfma_f32_16x16x32_bf16 v[112:115], v[166:169], v[182:185], v[112:115]
	v_mfma_f32_16x16x32_bf16 v[108:111], v[132:135], v[190:193], v[108:111]
	v_mfma_f32_16x16x32_bf16 v[104:107], v[166:169], v[190:193], v[104:107]
	v_mfma_f32_16x16x32_bf16 v[100:103], v[132:135], v[198:201], v[100:103]
	v_mfma_f32_16x16x32_bf16 v[96:99], v[166:169], v[198:201], v[96:99]
	v_mfma_f32_16x16x32_bf16 v[60:63], v[202:205], v[170:173], v[60:63]
	v_mfma_f32_16x16x32_bf16 v[56:59], v[210:213], v[170:173], v[56:59]
	v_mfma_f32_16x16x32_bf16 v[52:55], v[202:205], v[178:181], v[52:55]
	v_mfma_f32_16x16x32_bf16 v[48:51], v[210:213], v[178:181], v[48:51]
	v_mfma_f32_16x16x32_bf16 v[44:47], v[202:205], v[186:189], v[44:47]
	v_mfma_f32_16x16x32_bf16 v[40:43], v[210:213], v[186:189], v[40:43]
	v_mfma_f32_16x16x32_bf16 v[36:39], v[202:205], v[194:197], v[36:39]
	v_mfma_f32_16x16x32_bf16 v[32:35], v[210:213], v[194:197], v[32:35]
	v_mfma_f32_16x16x32_bf16 v[60:63], v[206:209], v[174:177], v[60:63]
	v_mfma_f32_16x16x32_bf16 v[56:59], v[214:217], v[174:177], v[56:59]
	v_mfma_f32_16x16x32_bf16 v[52:55], v[206:209], v[182:185], v[52:55]
	v_mfma_f32_16x16x32_bf16 v[48:51], v[214:217], v[182:185], v[48:51]
	v_mfma_f32_16x16x32_bf16 v[44:47], v[206:209], v[190:193], v[44:47]
	v_mfma_f32_16x16x32_bf16 v[40:43], v[214:217], v[190:193], v[40:43]
	v_mfma_f32_16x16x32_bf16 v[36:39], v[206:209], v[198:201], v[36:39]
	v_mfma_f32_16x16x32_bf16 v[32:35], v[214:217], v[198:201], v[32:35]
	s_barrier
; #define PG8_STAGE(bufoff, gbase, voff) do { _Pragma("unroll") for (int _i = 0; _i < 2; ++_i) \
;         __builtin_amdgcn_global_load_lds((const unsigned*)((const char*)(gbase) + (voff)[_i]), (PG8_LAS unsigned*)(lds + (bufoff) + ldsw + _i * 8192), 16, 0, 0); } while (0)
; #define PG8_LDA(dst, b, h) do { _Pragma("unroll") for (int m = 0; m < 4; ++m) _Pragma("unroll") for (int k = 0; k < 2; ++k) dst[m][k] = *(const PG8_LAS bf16x8*)(lds + PG8_SA(b, h) + aoff + m * 2048 + k * 1024); } while (0)
; #define PG8_LDB(dst, b, h) do { _Pragma("unroll") for (int n = 0; n < 2; ++n) _Pragma("unroll") for (int k = 0; k < 2; ++k) dst[n][k] = *(const PG8_LAS bf16x8*)(lds + PG8_SB(b, h) + boff + n * 2048 + k * 1024); } while (0)
; #define PG8_WAIT_V(n) asm volatile("s_waitcnt vmcnt(" #n ")" ::: "memory")
; #define PG8_WAIT_L(n) asm volatile("s_waitcnt lgkmcnt(" #n ")" ::: "memory")
; #define PG8_BAR __builtin_amdgcn_s_barrier()
; #define PG8_SCHED __builtin_amdgcn_sched_barrier(0)
; template <class Epi, class Sched>
; __device__ __forceinline__ void gemm_phase(PG8_LAS unsigned char* lds, const Gemm g, const Sched& S, const Epi& E) {
;     ...
;             PG8_LDB(B0, 0, 0); PG8_SCHED; PG8_LDA(At, 0, 0); PG8_STAGE(PG8_SA(1, 1), a1 + hstep, voffA);
;             PG8_WAIT_L(8); PG8_BAR; PG8_WAIT_L(0); PG8_MMA(0, 0, At, B0); PG8_BAR; PG8_SCHED;
;             PG8_LDB(B1, 0, 1); PG8_STAGE(PG8_SB(0, 0), b2, voffB);
;             PG8_BAR; PG8_WAIT_L(0); PG8_MMA(0, 1, At, B1); PG8_BAR;
;             PG8_LDA(At, 0, 1); PG8_STAGE(PG8_SA(0, 0), a2, voffA);
;             PG8_BAR; PG8_WAIT_L(0); PG8_MMA(1, 0, At, B0); PG8_BAR; PG8_SCHED;
;             PG8_STAGE(PG8_SB(0, 1), b2 + hstep, voffB);
;             PG8_WAIT_V(6); PG8_BAR; PG8_MMA(1, 1, At, B1); PG8_BAR;
;             PG8_LDB(B0, 1, 0); PG8_SCHED; PG8_LDA(At, 1, 0); PG8_STAGE(PG8_SA(0, 1), a2 + hstep, voffA);
;             PG8_WAIT_L(8); PG8_BAR; PG8_WAIT_L(0); PG8_MMA(0, 0, At, B0); PG8_BAR; PG8_SCHED;
;             PG8_LDB(B1, 1, 1); PG8_STAGE(PG8_SB(1, 0), b3, voffB);
;             PG8_BAR; PG8_WAIT_L(0); PG8_MMA(0, 1, At, B1); PG8_BAR;
;             PG8_LDA(At, 1, 1); PG8_STAGE(PG8_SA(1, 0), a3, voffA);
;             PG8_BAR; PG8_WAIT_L(0); PG8_MMA(1, 0, At, B0); PG8_BAR; PG8_SCHED;
;             PG8_STAGE(PG8_SB(1, 1), b3 + hstep, voffB);
;             PG8_WAIT_V(6); PG8_BAR; PG8_MMA(1, 1, At, B1); PG8_BAR;
	s_setprio 0
	ds_read_b128 v[170:173], v163 offset:49152
	ds_read_b128 v[174:177], v163 offset:50176
	ds_read_b128 v[178:181], v163 offset:51200
	ds_read_b128 v[182:185], v163 offset:52224
	ds_read_b128 v[186:189], v163 offset:53248
	ds_read_b128 v[190:193], v163 offset:54272
	ds_read_b128 v[194:197], v163 offset:55296
	ds_read_b128 v[198:201], v163 offset:56320
	s_add_i32 s72, 0, 0x1c000
	s_add_i32 s10, s33, s78
	v_add_u32_e32 v144, s72, v160
	v_lshl_add_u64 v[158:159], v[158:159], 0, s[26:27]
	s_mov_b32 m0, s10
	s_nop 0
	global_load_lds_dwordx4 v[158:159], off
	v_lshl_add_u64 v[158:159], v[218:219], 0, s[26:27]
	s_add_i32 m0, s10, 0x2000
	s_nop 0
	global_load_lds_dwordx4 v[158:159], off
	s_mov_b32 m0, s84
	v_lshl_add_u64 v[158:159], v[220:221], 0, s[26:27]
	global_load_lds_dwordx4 v[158:159], off
	v_lshl_add_u64 v[158:159], v[222:223], 0, s[26:27]
	s_mov_b32 m0, s85
	s_nop 0
	global_load_lds_dwordx4 v[158:159], off
	s_add_u32 s10, s70, 0x80080
	s_addc_u32 s11, s71, 0
	s_add_i32 s33, s72, s78
	v_lshl_add_u64 v[224:225], s[10:11], 0, v[138:139]
	s_mov_b32 m0, s33
	s_nop 0
	global_load_lds_dwordx4 v[224:225], off
	v_lshl_add_u64 v[224:225], s[10:11], 0, v[142:143]
	s_add_i32 m0, s33, 0x2000
	s_nop 0
	global_load_lds_dwordx4 v[224:225], off
	s_waitcnt vmcnt(8)
	s_waitcnt lgkmcnt(0)
	s_setprio 1
	s_barrier
	v_mfma_f32_16x16x32_bf16 v[92:95], v[128:131], v[170:173], v[92:95]
	v_mfma_f32_16x16x32_bf16 v[88:91], v[154:157], v[170:173], v[88:91]
	v_mfma_f32_16x16x32_bf16 v[84:87], v[128:131], v[178:181], v[84:87]
	v_mfma_f32_16x16x32_bf16 v[80:83], v[154:157], v[178:181], v[80:83]
	v_mfma_f32_16x16x32_bf16 v[76:79], v[128:131], v[186:189], v[76:79]
	v_mfma_f32_16x16x32_bf16 v[72:75], v[154:157], v[186:189], v[72:75]
	v_mfma_f32_16x16x32_bf16 v[68:71], v[128:131], v[194:197], v[68:71]
	v_mfma_f32_16x16x32_bf16 v[64:67], v[154:157], v[194:197], v[64:67]
	s_add_i32 vcc_hi, vcc_hi, 2
	s_add_u32 s68, s68, 0x100
	s_addc_u32 s69, s69, 0
	s_add_u32 s97, s97, 0x100
	s_addc_u32 vcc_lo, vcc_lo, 0
	s_cmp_gt_u32 vcc_hi, 29
	v_mfma_f32_16x16x32_bf16 v[92:95], v[132:135], v[174:177], v[92:95]
	v_mfma_f32_16x16x32_bf16 v[88:91], v[166:169], v[174:177], v[88:91]
	v_mfma_f32_16x16x32_bf16 v[84:87], v[132:135], v[182:185], v[84:87]
	v_mfma_f32_16x16x32_bf16 v[80:83], v[166:169], v[182:185], v[80:83]
	v_mfma_f32_16x16x32_bf16 v[76:79], v[132:135], v[190:193], v[76:79]
	v_mfma_f32_16x16x32_bf16 v[72:75], v[166:169], v[190:193], v[72:75]
	v_mfma_f32_16x16x32_bf16 v[68:71], v[132:135], v[198:201], v[68:71]
	v_mfma_f32_16x16x32_bf16 v[64:67], v[166:169], v[198:201], v[64:67]
	v_mfma_f32_16x16x32_bf16 v[28:31], v[202:205], v[170:173], v[28:31]
	v_mfma_f32_16x16x32_bf16 v[24:27], v[210:213], v[170:173], v[24:27]
	v_mfma_f32_16x16x32_bf16 v[20:23], v[202:205], v[178:181], v[20:23]
	v_mfma_f32_16x16x32_bf16 v[16:19], v[210:213], v[178:181], v[16:19]
	v_mfma_f32_16x16x32_bf16 v[12:15], v[202:205], v[186:189], v[12:15]
	v_mfma_f32_16x16x32_bf16 v[8:11], v[210:213], v[186:189], v[8:11]
	v_mfma_f32_16x16x32_bf16 v[4:7], v[202:205], v[194:197], v[4:7]
	v_mfma_f32_16x16x32_bf16 v[0:3], v[210:213], v[194:197], v[0:3]
	v_mfma_f32_16x16x32_bf16 v[28:31], v[206:209], v[174:177], v[28:31]
	v_mfma_f32_16x16x32_bf16 v[24:27], v[214:217], v[174:177], v[24:27]
	v_mfma_f32_16x16x32_bf16 v[20:23], v[206:209], v[182:185], v[20:23]
	v_mfma_f32_16x16x32_bf16 v[16:19], v[214:217], v[182:185], v[16:19]
	v_mfma_f32_16x16x32_bf16 v[12:15], v[206:209], v[190:193], v[12:15]
	v_mfma_f32_16x16x32_bf16 v[8:11], v[214:217], v[190:193], v[8:11]
	v_mfma_f32_16x16x32_bf16 v[4:7], v[206:209], v[198:201], v[4:7]
	v_mfma_f32_16x16x32_bf16 v[0:3], v[214:217], v[198:201], v[0:3]
	s_barrier
.LBB0_235:
	s_setprio 0
	ds_read_b128 v[128:131], v162
	ds_read_b128 v[132:135], v162 offset:1024
	ds_read_b128 v[154:157], v162 offset:2048
	ds_read_b128 v[166:169], v162 offset:3072
	ds_read_b128 v[170:173], v163
	ds_read_b128 v[174:177], v163 offset:1024
	ds_read_b128 v[178:181], v163 offset:2048
	ds_read_b128 v[182:185], v163 offset:3072
	ds_read_b128 v[186:189], v163 offset:4096
	ds_read_b128 v[190:193], v163 offset:5120
	ds_read_b128 v[194:197], v163 offset:6144
	ds_read_b128 v[198:201], v163 offset:7168
	s_waitcnt lgkmcnt(11)
	ds_read_b128 v[202:205], v164
	ds_read_b128 v[206:209], v164 offset:1024
	ds_read_b128 v[210:213], v164 offset:2048
	ds_read_b128 v[214:217], v164 offset:3072
	s_add_u32 s10, s68, 0xfff80080
	s_addc_u32 s11, s69, -1
	s_cmp_eq_u32 vcc_hi, 28
	s_cselect_b32 s73, s0, s11
	s_cselect_b32 s72, s5, s10
	s_cselect_b32 s71, s47, vcc_lo
	s_cselect_b32 s70, s49, s97
	v_lshl_add_u64 v[158:159], s[68:69], 0, v[148:149]
	s_add_i32 m0, s67, 0xc000
	s_nop 0
	global_load_lds_dwordx4 v[158:159], off
	v_lshl_add_u64 v[158:159], s[68:69], 0, v[150:151]
	s_add_i32 m0, s67, 0xe000
	s_nop 0
	global_load_lds_dwordx4 v[158:159], off
	s_waitcnt vmcnt(8)
	s_waitcnt lgkmcnt(0)
	s_setprio 1
	s_barrier
; #define PG8_STAGE(bufoff, gbase, voff) do { _Pragma("unroll") for (int _i = 0; _i < 2; ++_i) \
;         __builtin_amdgcn_global_load_lds((const unsigned*)((const char*)(gbase) + (voff)[_i]), (PG8_LAS unsigned*)(lds + (bufoff) + ldsw + _i * 8192), 16, 0, 0); } while (0)
; #define PG8_LDA(dst, b, h) do { _Pragma("unroll") for (int m = 0; m < 4; ++m) _Pragma("unroll") for (int k = 0; k < 2; ++k) dst[m][k] = *(const PG8_LAS bf16x8*)(lds + PG8_SA(b, h) + aoff + m * 2048 + k * 1024); } while (0)
; #define PG8_LDB(dst, b, h) do { _Pragma("unroll") for (int n = 0; n < 2; ++n) _Pragma("unroll") for (int k = 0; k < 2; ++k) dst[n][k] = *(const PG8_LAS bf16x8*)(lds + PG8_SB(b, h) + boff + n * 2048 + k * 1024); } while (0)
; #define PG8_WAIT_V(n) asm volatile("s_waitcnt vmcnt(" #n ")" ::: "memory")
; #define PG8_WAIT_L(n) asm volatile("s_waitcnt lgkmcnt(" #n ")" ::: "memory")
; #define PG8_BAR __builtin_amdgcn_s_barrier()
; #define PG8_SCHED __builtin_amdgcn_sched_barrier(0)
; template <class Epi, class Sched>
; __device__ __forceinline__ void gemm_phase(PG8_LAS unsigned char* lds, const Gemm g, const Sched& S, const Epi& E) {
;     ...
;             PG8_LDB(B0, 0, 0); PG8_SCHED; PG8_LDA(At, 0, 0); PG8_STAGE(PG8_SA(1, 1), a1 + hstep, voffA);
;             PG8_WAIT_L(8); PG8_BAR; PG8_WAIT_L(0); PG8_MMA(0, 0, At, B0); PG8_BAR; PG8_SCHED;
;             PG8_LDB(B1, 0, 1); PG8_STAGE(PG8_SB(0, 0), b2, voffB);
;             PG8_BAR; PG8_WAIT_L(0); PG8_MMA(0, 1, At, B1); PG8_BAR;
;             PG8_LDA(At, 0, 1); PG8_STAGE(PG8_SA(0, 0), a2, voffA);
;             PG8_BAR; PG8_WAIT_L(0); PG8_MMA(1, 0, At, B0); PG8_BAR; PG8_SCHED;
;             PG8_STAGE(PG8_SB(0, 1), b2 + hstep, voffB);
;             PG8_WAIT_V(6); PG8_BAR; PG8_MMA(1, 1, At, B1); PG8_BAR;
;             PG8_LDB(B0, 1, 0); PG8_SCHED; PG8_LDA(At, 1, 0); PG8_STAGE(PG8_SA(0, 1), a2 + hstep, voffA);
;             PG8_WAIT_L(8); PG8_BAR; PG8_WAIT_L(0); PG8_MMA(0, 0, At, B0); PG8_BAR; PG8_SCHED;
;             PG8_LDB(B1, 1, 1); PG8_STAGE(PG8_SB(1, 0), b3, voffB);
;             PG8_BAR; PG8_WAIT_L(0); PG8_MMA(0, 1, At, B1); PG8_BAR;
;             PG8_LDA(At, 1, 1); PG8_STAGE(PG8_SA(1, 0), a3, voffA);
;             PG8_BAR; PG8_WAIT_L(0); PG8_MMA(1, 0, At, B0); PG8_BAR; PG8_SCHED;
;             PG8_STAGE(PG8_SB(1, 1), b3 + hstep, voffB);
;             PG8_WAIT_V(6); PG8_BAR; PG8_MMA(1, 1, At, B1); PG8_BAR;
	v_mfma_f32_16x16x32_bf16 v[124:127], v[128:131], v[170:173], v[124:127]
	v_mfma_f32_16x16x32_bf16 v[120:123], v[154:157], v[170:173], v[120:123]
	v_mfma_f32_16x16x32_bf16 v[116:119], v[128:131], v[178:181], v[116:119]
	v_mfma_f32_16x16x32_bf16 v[112:115], v[154:157], v[178:181], v[112:115]
	v_mfma_f32_16x16x32_bf16 v[108:111], v[128:131], v[186:189], v[108:111]
	v_mfma_f32_16x16x32_bf16 v[104:107], v[154:157], v[186:189], v[104:107]
	v_mfma_f32_16x16x32_bf16 v[100:103], v[128:131], v[194:197], v[100:103]
	v_mfma_f32_16x16x32_bf16 v[96:99], v[154:157], v[194:197], v[96:99]
	v_mfma_f32_16x16x32_bf16 v[124:127], v[132:135], v[174:177], v[124:127]
	v_mfma_f32_16x16x32_bf16 v[120:123], v[166:169], v[174:177], v[120:123]
	v_mfma_f32_16x16x32_bf16 v[116:119], v[132:135], v[182:185], v[116:119]
	v_mfma_f32_16x16x32_bf16 v[112:115], v[166:169], v[182:185], v[112:115]
	v_mfma_f32_16x16x32_bf16 v[108:111], v[132:135], v[190:193], v[108:111]
	v_mfma_f32_16x16x32_bf16 v[104:107], v[166:169], v[190:193], v[104:107]
	v_mfma_f32_16x16x32_bf16 v[100:103], v[132:135], v[198:201], v[100:103]
	v_mfma_f32_16x16x32_bf16 v[96:99], v[166:169], v[198:201], v[96:99]
	v_mfma_f32_16x16x32_bf16 v[60:63], v[202:205], v[170:173], v[60:63]
	v_mfma_f32_16x16x32_bf16 v[56:59], v[210:213], v[170:173], v[56:59]
	v_mfma_f32_16x16x32_bf16 v[52:55], v[202:205], v[178:181], v[52:55]
	v_mfma_f32_16x16x32_bf16 v[48:51], v[210:213], v[178:181], v[48:51]
	v_mfma_f32_16x16x32_bf16 v[44:47], v[202:205], v[186:189], v[44:47]
	v_mfma_f32_16x16x32_bf16 v[40:43], v[210:213], v[186:189], v[40:43]
	v_mfma_f32_16x16x32_bf16 v[36:39], v[202:205], v[194:197], v[36:39]
	v_mfma_f32_16x16x32_bf16 v[32:35], v[210:213], v[194:197], v[32:35]
	v_mfma_f32_16x16x32_bf16 v[60:63], v[206:209], v[174:177], v[60:63]
	v_mfma_f32_16x16x32_bf16 v[56:59], v[214:217], v[174:177], v[56:59]
	v_mfma_f32_16x16x32_bf16 v[52:55], v[206:209], v[182:185], v[52:55]
	v_mfma_f32_16x16x32_bf16 v[48:51], v[214:217], v[182:185], v[48:51]
	v_mfma_f32_16x16x32_bf16 v[44:47], v[206:209], v[190:193], v[44:47]
	v_mfma_f32_16x16x32_bf16 v[40:43], v[214:217], v[190:193], v[40:43]
	v_mfma_f32_16x16x32_bf16 v[36:39], v[206:209], v[198:201], v[36:39]
	v_mfma_f32_16x16x32_bf16 v[32:35], v[214:217], v[198:201], v[32:35]
	s_barrier
	s_setprio 0
	ds_read_b128 v[170:173], v163 offset:16384
	ds_read_b128 v[174:177], v163 offset:17408
	ds_read_b128 v[178:181], v163 offset:18432
	ds_read_b128 v[182:185], v163 offset:19456
	ds_read_b128 v[186:189], v163 offset:20480
	ds_read_b128 v[190:193], v163 offset:21504
	ds_read_b128 v[194:197], v163 offset:22528
	ds_read_b128 v[198:201], v163 offset:23552
	s_add_i32 s10, s90, s78
	v_lshl_add_u64 v[158:159], s[70:71], 0, v[138:139]
	s_mov_b32 m0, s10
	s_nop 0
	global_load_lds_dwordx4 v[158:159], off
	v_lshl_add_u64 v[218:219], s[70:71], 0, v[142:143]
	s_add_i32 m0, s10, 0x2000
	s_nop 0
	global_load_lds_dwordx4 v[218:219], off
	s_mov_b32 m0, s67
	v_lshl_add_u64 v[220:221], s[72:73], 0, v[136:137]
	global_load_lds_dwordx4 v[220:221], off
	v_lshl_add_u64 v[222:223], s[72:73], 0, v[140:141]
	s_mov_b32 m0, s79
	s_nop 0
	global_load_lds_dwordx4 v[222:223], off
	s_add_u32 s10, s70, 0x80000
	s_addc_u32 s11, s71, 0
	s_add_i32 s33, s91, s78
	v_lshl_add_u64 v[224:225], s[10:11], 0, v[138:139]
	s_mov_b32 m0, s33
	s_nop 0
	global_load_lds_dwordx4 v[224:225], off
	v_lshl_add_u64 v[224:225], s[10:11], 0, v[142:143]
	s_add_i32 m0, s33, 0x2000
	s_nop 0
	global_load_lds_dwordx4 v[224:225], off
	s_waitcnt vmcnt(8)
	s_waitcnt lgkmcnt(0)
	s_setprio 1
	s_barrier
	v_mfma_f32_16x16x32_bf16 v[92:95], v[128:131], v[170:173], v[92:95]
	v_mfma_f32_16x16x32_bf16 v[88:91], v[154:157], v[170:173], v[88:91]
	v_mfma_f32_16x16x32_bf16 v[84:87], v[128:131], v[178:181], v[84:87]
	v_mfma_f32_16x16x32_bf16 v[80:83], v[154:157], v[178:181], v[80:83]
	v_mfma_f32_16x16x32_bf16 v[76:79], v[128:131], v[186:189], v[76:79]
	v_mfma_f32_16x16x32_bf16 v[72:75], v[154:157], v[186:189], v[72:75]
	v_mfma_f32_16x16x32_bf16 v[68:71], v[128:131], v[194:197], v[68:71]
	v_mfma_f32_16x16x32_bf16 v[64:67], v[154:157], v[194:197], v[64:67]
	s_add_i32 s33, 0, 0x18000
	v_add_u32_e32 v144, s33, v160
	v_mfma_f32_16x16x32_bf16 v[92:95], v[132:135], v[174:177], v[92:95]
	v_mfma_f32_16x16x32_bf16 v[88:91], v[166:169], v[174:177], v[88:91]
	v_mfma_f32_16x16x32_bf16 v[84:87], v[132:135], v[182:185], v[84:87]
	v_mfma_f32_16x16x32_bf16 v[80:83], v[166:169], v[182:185], v[80:83]
	v_mfma_f32_16x16x32_bf16 v[76:79], v[132:135], v[190:193], v[76:79]
	v_mfma_f32_16x16x32_bf16 v[72:75], v[166:169], v[190:193], v[72:75]
	v_mfma_f32_16x16x32_bf16 v[68:71], v[132:135], v[198:201], v[68:71]
	v_mfma_f32_16x16x32_bf16 v[64:67], v[166:169], v[198:201], v[64:67]
	v_mfma_f32_16x16x32_bf16 v[28:31], v[202:205], v[170:173], v[28:31]
	v_mfma_f32_16x16x32_bf16 v[24:27], v[210:213], v[170:173], v[24:27]
	v_mfma_f32_16x16x32_bf16 v[20:23], v[202:205], v[178:181], v[20:23]
	v_mfma_f32_16x16x32_bf16 v[16:19], v[210:213], v[178:181], v[16:19]
	v_mfma_f32_16x16x32_bf16 v[12:15], v[202:205], v[186:189], v[12:15]
	v_mfma_f32_16x16x32_bf16 v[8:11], v[210:213], v[186:189], v[8:11]
	v_mfma_f32_16x16x32_bf16 v[4:7], v[202:205], v[194:197], v[4:7]
	v_mfma_f32_16x16x32_bf16 v[0:3], v[210:213], v[194:197], v[0:3]
	v_mfma_f32_16x16x32_bf16 v[28:31], v[206:209], v[174:177], v[28:31]
	v_mfma_f32_16x16x32_bf16 v[24:27], v[214:217], v[174:177], v[24:27]
	v_mfma_f32_16x16x32_bf16 v[20:23], v[206:209], v[182:185], v[20:23]
	v_mfma_f32_16x16x32_bf16 v[16:19], v[214:217], v[182:185], v[16:19]
	v_mfma_f32_16x16x32_bf16 v[12:15], v[206:209], v[190:193], v[12:15]
	v_mfma_f32_16x16x32_bf16 v[8:11], v[214:217], v[190:193], v[8:11]
	v_mfma_f32_16x16x32_bf16 v[4:7], v[206:209], v[198:201], v[4:7]
	v_mfma_f32_16x16x32_bf16 v[0:3], v[214:217], v[198:201], v[0:3]
	s_barrier
; #define PG8_STAGE(bufoff, gbase, voff) do { _Pragma("unroll") for (int _i = 0; _i < 2; ++_i) \
;         __builtin_amdgcn_global_load_lds((const unsigned*)((const char*)(gbase) + (voff)[_i]), (PG8_LAS unsigned*)(lds + (bufoff) + ldsw + _i * 8192), 16, 0, 0); } while (0)
; #define PG8_LDA(dst, b, h) do { _Pragma("unroll") for (int m = 0; m < 4; ++m) _Pragma("unroll") for (int k = 0; k < 2; ++k) dst[m][k] = *(const PG8_LAS bf16x8*)(lds + PG8_SA(b, h) + aoff + m * 2048 + k * 1024); } while (0)
; #define PG8_LDB(dst, b, h) do { _Pragma("unroll") for (int n = 0; n < 2; ++n) _Pragma("unroll") for (int k = 0; k < 2; ++k) dst[n][k] = *(const PG8_LAS bf16x8*)(lds + PG8_SB(b, h) + boff + n * 2048 + k * 1024); } while (0)
; #define PG8_WAIT_V(n) asm volatile("s_waitcnt vmcnt(" #n ")" ::: "memory")
; #define PG8_WAIT_L(n) asm volatile("s_waitcnt lgkmcnt(" #n ")" ::: "memory")
; #define PG8_BAR __builtin_amdgcn_s_barrier()
; #define PG8_SCHED __builtin_amdgcn_sched_barrier(0)
; template <class Epi, class Sched>
; __device__ __forceinline__ void gemm_phase(PG8_LAS unsigned char* lds, const Gemm g, const Sched& S, const Epi& E) {
;     ...
;             PG8_LDB(B0, 0, 0); PG8_SCHED; PG8_LDA(At, 0, 0); PG8_STAGE(PG8_SA(1, 1), a1 + hstep, voffA);
;             PG8_WAIT_L(8); PG8_BAR; PG8_WAIT_L(0); PG8_MMA(0, 0, At, B0); PG8_BAR; PG8_SCHED;
;             PG8_LDB(B1, 0, 1); PG8_STAGE(PG8_SB(0, 0), b2, voffB);
;             PG8_BAR; PG8_WAIT_L(0); PG8_MMA(0, 1, At, B1); PG8_BAR;
;             PG8_LDA(At, 0, 1); PG8_STAGE(PG8_SA(0, 0), a2, voffA);
;             PG8_BAR; PG8_WAIT_L(0); PG8_MMA(1, 0, At, B0); PG8_BAR; PG8_SCHED;
;             PG8_STAGE(PG8_SB(0, 1), b2 + hstep, voffB);
;             PG8_WAIT_V(6); PG8_BAR; PG8_MMA(1, 1, At, B1); PG8_BAR;
;             PG8_LDB(B0, 1, 0); PG8_SCHED; PG8_LDA(At, 1, 0); PG8_STAGE(PG8_SA(0, 1), a2 + hstep, voffA);
;             PG8_WAIT_L(8); PG8_BAR; PG8_WAIT_L(0); PG8_MMA(0, 0, At, B0); PG8_BAR; PG8_SCHED;
;             PG8_LDB(B1, 1, 1); PG8_STAGE(PG8_SB(1, 0), b3, voffB);
;             PG8_BAR; PG8_WAIT_L(0); PG8_MMA(0, 1, At, B1); PG8_BAR;
;             PG8_LDA(At, 1, 1); PG8_STAGE(PG8_SA(1, 0), a3, voffA);
;             PG8_BAR; PG8_WAIT_L(0); PG8_MMA(1, 0, At, B0); PG8_BAR; PG8_SCHED;
;             PG8_STAGE(PG8_SB(1, 1), b3 + hstep, voffB);
;             PG8_WAIT_V(6); PG8_BAR; PG8_MMA(1, 1, At, B1); PG8_BAR;
	s_setprio 0
	ds_read_b128 v[128:131], v162 offset:32768
	ds_read_b128 v[132:135], v162 offset:33792
	ds_read_b128 v[154:157], v162 offset:34816
	ds_read_b128 v[166:169], v162 offset:35840
	ds_read_b128 v[170:173], v163 offset:32768
	ds_read_b128 v[174:177], v163 offset:33792
	ds_read_b128 v[178:181], v163 offset:34816
	ds_read_b128 v[182:185], v163 offset:35840
	ds_read_b128 v[186:189], v163 offset:36864
	ds_read_b128 v[190:193], v163 offset:37888
	ds_read_b128 v[194:197], v163 offset:38912
	ds_read_b128 v[198:201], v163 offset:39936
	s_waitcnt lgkmcnt(11)
	ds_read_b128 v[202:205], v164 offset:32768
	ds_read_b128 v[206:209], v164 offset:33792
	ds_read_b128 v[210:213], v164 offset:34816
	ds_read_b128 v[214:217], v164 offset:35840
	s_add_u32 s10, s72, 0x80000
	s_addc_u32 s11, s73, 0
	s_mov_b32 m0, s80
	v_lshl_add_u64 v[224:225], s[10:11], 0, v[136:137]
	global_load_lds_dwordx4 v[224:225], off
	v_lshl_add_u64 v[224:225], s[10:11], 0, v[140:141]
	s_mov_b32 m0, s81
	s_nop 0
	global_load_lds_dwordx4 v[224:225], off
	s_waitcnt vmcnt(8)
	s_waitcnt lgkmcnt(0)
	s_setprio 1
	s_barrier
	v_mfma_f32_16x16x32_bf16 v[124:127], v[128:131], v[170:173], v[124:127]
	v_mfma_f32_16x16x32_bf16 v[120:123], v[154:157], v[170:173], v[120:123]
	v_mfma_f32_16x16x32_bf16 v[116:119], v[128:131], v[178:181], v[116:119]
	v_mfma_f32_16x16x32_bf16 v[112:115], v[154:157], v[178:181], v[112:115]
	v_mfma_f32_16x16x32_bf16 v[108:111], v[128:131], v[186:189], v[108:111]
	v_mfma_f32_16x16x32_bf16 v[104:107], v[154:157], v[186:189], v[104:107]
	v_mfma_f32_16x16x32_bf16 v[100:103], v[128:131], v[194:197], v[100:103]
	v_mfma_f32_16x16x32_bf16 v[96:99], v[154:157], v[194:197], v[96:99]
	v_mfma_f32_16x16x32_bf16 v[124:127], v[132:135], v[174:177], v[124:127]
	v_mfma_f32_16x16x32_bf16 v[120:123], v[166:169], v[174:177], v[120:123]
	v_mfma_f32_16x16x32_bf16 v[116:119], v[132:135], v[182:185], v[116:119]
	v_mfma_f32_16x16x32_bf16 v[112:115], v[166:169], v[182:185], v[112:115]
	v_mfma_f32_16x16x32_bf16 v[108:111], v[132:135], v[190:193], v[108:111]
	v_mfma_f32_16x16x32_bf16 v[104:107], v[166:169], v[190:193], v[104:107]
	v_mfma_f32_16x16x32_bf16 v[100:103], v[132:135], v[198:201], v[100:103]
	v_mfma_f32_16x16x32_bf16 v[96:99], v[166:169], v[198:201], v[96:99]
	v_mfma_f32_16x16x32_bf16 v[60:63], v[202:205], v[170:173], v[60:63]
	v_mfma_f32_16x16x32_bf16 v[56:59], v[210:213], v[170:173], v[56:59]
	v_mfma_f32_16x16x32_bf16 v[52:55], v[202:205], v[178:181], v[52:55]
	v_mfma_f32_16x16x32_bf16 v[48:51], v[210:213], v[178:181], v[48:51]
	v_mfma_f32_16x16x32_bf16 v[44:47], v[202:205], v[186:189], v[44:47]
	v_mfma_f32_16x16x32_bf16 v[40:43], v[210:213], v[186:189], v[40:43]
	v_mfma_f32_16x16x32_bf16 v[36:39], v[202:205], v[194:197], v[36:39]
	v_mfma_f32_16x16x32_bf16 v[32:35], v[210:213], v[194:197], v[32:35]
	v_mfma_f32_16x16x32_bf16 v[60:63], v[206:209], v[174:177], v[60:63]
	v_mfma_f32_16x16x32_bf16 v[56:59], v[214:217], v[174:177], v[56:59]
	v_mfma_f32_16x16x32_bf16 v[52:55], v[206:209], v[182:185], v[52:55]
	v_mfma_f32_16x16x32_bf16 v[48:51], v[214:217], v[182:185], v[48:51]
	v_mfma_f32_16x16x32_bf16 v[44:47], v[206:209], v[190:193], v[44:47]
	v_mfma_f32_16x16x32_bf16 v[40:43], v[214:217], v[190:193], v[40:43]
	v_mfma_f32_16x16x32_bf16 v[36:39], v[206:209], v[198:201], v[36:39]
	v_mfma_f32_16x16x32_bf16 v[32:35], v[214:217], v[198:201], v[32:35]
	s_barrier
	s_setprio 0
	ds_read_b128 v[170:173], v163 offset:49152
	ds_read_b128 v[174:177], v163 offset:50176
	ds_read_b128 v[178:181], v163 offset:51200
	ds_read_b128 v[182:185], v163 offset:52224
	ds_read_b128 v[186:189], v163 offset:53248
	ds_read_b128 v[190:193], v163 offset:54272
	ds_read_b128 v[194:197], v163 offset:55296
	ds_read_b128 v[198:201], v163 offset:56320
	s_add_i32 s72, 0, 0x1c000
	s_add_i32 s10, s33, s78
	v_add_u32_e32 v144, s72, v160
	v_lshl_add_u64 v[158:159], v[158:159], 0, s[26:27]
	s_mov_b32 m0, s10
	s_nop 0
	global_load_lds_dwordx4 v[158:159], off
	v_lshl_add_u64 v[158:159], v[218:219], 0, s[26:27]
	s_add_i32 m0, s10, 0x2000
	s_nop 0
	global_load_lds_dwordx4 v[158:159], off
	s_mov_b32 m0, s84
	v_lshl_add_u64 v[158:159], v[220:221], 0, s[26:27]
	global_load_lds_dwordx4 v[158:159], off
	v_lshl_add_u64 v[158:159], v[222:223], 0, s[26:27]
	s_mov_b32 m0, s85
	s_nop 0
	global_load_lds_dwordx4 v[158:159], off
	s_add_u32 s10, s70, 0x80080
	s_addc_u32 s11, s71, 0
	s_add_i32 s33, s72, s78
	v_lshl_add_u64 v[224:225], s[10:11], 0, v[138:139]
	s_mov_b32 m0, s33
	s_nop 0
	global_load_lds_dwordx4 v[224:225], off
	v_lshl_add_u64 v[224:225], s[10:11], 0, v[142:143]
	s_add_i32 m0, s33, 0x2000
	s_nop 0
	global_load_lds_dwordx4 v[224:225], off
	s_waitcnt vmcnt(8)
	s_waitcnt lgkmcnt(0)
	s_setprio 1
	s_barrier
; #define PG8_STAGE(bufoff, gbase, voff) do { _Pragma("unroll") for (int _i = 0; _i < 2; ++_i) \
;         __builtin_amdgcn_global_load_lds((const unsigned*)((const char*)(gbase) + (voff)[_i]), (PG8_LAS unsigned*)(lds + (bufoff) + ldsw + _i * 8192), 16, 0, 0); } while (0)
; #define PG8_WAIT_V(n) asm volatile("s_waitcnt vmcnt(" #n ")" ::: "memory")
; #define PG8_WAIT_L(n) asm volatile("s_waitcnt lgkmcnt(" #n ")" ::: "memory")
; template <class Epi, class Sched>
; __device__ __forceinline__ void gemm_phase(PG8_LAS unsigned char* lds, const Gemm g, const Sched& S, const Epi& E) {
;     ...
;             PG8_BAR; PG8_WAIT_L(0); PG8_MMA(1, 0, At, B0); PG8_BAR; PG8_SCHED;
;             PG8_STAGE(PG8_SB(1, 1), b3 + hstep, voffB);
;             PG8_WAIT_V(6); PG8_BAR; PG8_MMA(1, 1, At, B1); PG8_BAR;
;         }
;         E(acc, cur, wr, wc, fr, fq); S.done(cur);
;         if (!has_next) break;
;     __device__ __forceinline__ void operator()(const AccT& acc, const pg8::Unit& u, int wr, int wc, int fr, int fq) const {
;         const int row0 = u.pm * 256 + wr * 64 + fr, cl = wc * 32 + 8 * fq, pn = u.pn;
;         if (pn < 8) {
; #pragma unroll
;             for (int bj = 0; bj < 2; ++bj) {
;                 const int col = pn * 256 + bj * 128 + cl;
;                 const f32x4 l0 = *(const f32x4*)(lb + col), l1 = *(const f32x4*)(lb + col + 4);
; #pragma unroll
;                 for (int ai = 0; ai < 2; ++ai)
; #pragma unroll
;                     for (int m = 0; m < 4; ++m) {
;                         const f32x4 a = acc[ai][bj][m][0], b = acc[ai][bj][m][1]; float g[8];
; #pragma unroll
;                         for (int j = 0; j < 4; ++j) { g[j] = (1.f - l0[j]) * __builtin_amdgcn_rcpf(1.f + __expf(a[j])); g[4 + j] = (1.f - l1[j]) * __builtin_amdgcn_rcpf(1.f + __expf(b[j])); }
;                         u32x4 w; w.x = pk_h2(g[0], g[1]); w.y = pk_h2(g[2], g[3]); w.z = pk_h2(g[4], g[5]); w.w = pk_h2(g[6], g[7]);
;                         *(u32x4*)(G + (size_t)(row0 + ai * 128 + m * 16) * 2048 + col) = w;
;                     }
;             }
;         } else if (pn < 24) {
;             if (u.pm >= 128 && pn >= 12) return;
;             const int ty = (pn - 8) >> 2; bf16_t* base = V + (ty == 0 ? (size_t)0 : (size_t)TALL * HW + (size_t)(ty - 1) * T * HW);
;             const bool act = (ty == 1);
;             const int colt = (pn - 8 - 4 * ty) * 256;
	v_mfma_f32_16x16x32_bf16 v[92:95], v[128:131], v[170:173], v[92:95]
	v_mfma_f32_16x16x32_bf16 v[88:91], v[154:157], v[170:173], v[88:91]
	v_mfma_f32_16x16x32_bf16 v[84:87], v[128:131], v[178:181], v[84:87]
	v_mfma_f32_16x16x32_bf16 v[80:83], v[154:157], v[178:181], v[80:83]
	v_mfma_f32_16x16x32_bf16 v[76:79], v[128:131], v[186:189], v[76:79]
	v_mfma_f32_16x16x32_bf16 v[72:75], v[154:157], v[186:189], v[72:75]
	v_mfma_f32_16x16x32_bf16 v[68:71], v[128:131], v[194:197], v[68:71]
	v_mfma_f32_16x16x32_bf16 v[64:67], v[154:157], v[194:197], v[64:67]
	s_add_i32 vcc_hi, vcc_hi, 2
	s_add_u32 s68, s68, 0x100
	s_addc_u32 s69, s69, 0
	s_add_u32 s97, s97, 0x100
	s_addc_u32 vcc_lo, vcc_lo, 0
	s_cmp_gt_u32 vcc_hi, 29
	v_mfma_f32_16x16x32_bf16 v[92:95], v[132:135], v[174:177], v[92:95]
	v_mfma_f32_16x16x32_bf16 v[88:91], v[166:169], v[174:177], v[88:91]
	v_mfma_f32_16x16x32_bf16 v[84:87], v[132:135], v[182:185], v[84:87]
	v_mfma_f32_16x16x32_bf16 v[80:83], v[166:169], v[182:185], v[80:83]
	v_mfma_f32_16x16x32_bf16 v[76:79], v[132:135], v[190:193], v[76:79]
	v_mfma_f32_16x16x32_bf16 v[72:75], v[166:169], v[190:193], v[72:75]
	v_mfma_f32_16x16x32_bf16 v[68:71], v[132:135], v[198:201], v[68:71]
	v_mfma_f32_16x16x32_bf16 v[64:67], v[166:169], v[198:201], v[64:67]
	v_mfma_f32_16x16x32_bf16 v[28:31], v[202:205], v[170:173], v[28:31]
	v_mfma_f32_16x16x32_bf16 v[24:27], v[210:213], v[170:173], v[24:27]
	v_mfma_f32_16x16x32_bf16 v[20:23], v[202:205], v[178:181], v[20:23]
	v_mfma_f32_16x16x32_bf16 v[16:19], v[210:213], v[178:181], v[16:19]
	v_mfma_f32_16x16x32_bf16 v[12:15], v[202:205], v[186:189], v[12:15]
	v_mfma_f32_16x16x32_bf16 v[8:11], v[210:213], v[186:189], v[8:11]
	v_mfma_f32_16x16x32_bf16 v[4:7], v[202:205], v[194:197], v[4:7]
	v_mfma_f32_16x16x32_bf16 v[0:3], v[210:213], v[194:197], v[0:3]
	v_mfma_f32_16x16x32_bf16 v[28:31], v[206:209], v[174:177], v[28:31]
	v_mfma_f32_16x16x32_bf16 v[24:27], v[214:217], v[174:177], v[24:27]
	v_mfma_f32_16x16x32_bf16 v[20:23], v[206:209], v[182:185], v[20:23]
	v_mfma_f32_16x16x32_bf16 v[16:19], v[214:217], v[182:185], v[16:19]
	v_mfma_f32_16x16x32_bf16 v[12:15], v[206:209], v[190:193], v[12:15]
	v_mfma_f32_16x16x32_bf16 v[8:11], v[214:217], v[190:193], v[8:11]
	v_mfma_f32_16x16x32_bf16 v[4:7], v[206:209], v[198:201], v[4:7]
	v_mfma_f32_16x16x32_bf16 v[0:3], v[214:217], v[198:201], v[0:3]
	s_barrier
	s_cbranch_scc0 .LBB0_235
	s_setprio 0
	v_lshl_add_u32 v154, s4, 8, v147
	s_cmp_gt_i32 s66, 7
	s_mov_b64 s[68:69], -1
	s_cbranch_scc0 .LBB0_277
	s_cmpk_gt_i32 s4, 0x7f
	s_cselect_b64 s[68:69], -1, 0
	s_cmpk_lt_i32 s4, 0x80
	s_cselect_b64 s[70:71], -1, 0
	s_cmp_gt_u32 s66, 23
	s_mov_b64 s[4:5], -1
	s_cbranch_scc0 .LBB0_241
	s_andn2_b64 vcc, exec, s[70:71]
	s_cbranch_vccnz .LBB0_240
; __device__ __forceinline__ unsigned cvt_pk_bf16(float lo, float hi) { const bf16v2_t v = __builtin_convertvector((f32x2){lo, hi}, bf16v2_t); return __builtin_bit_cast(unsigned, v); }
;     __device__ __forceinline__ void operator()(const AccT& acc, const pg8::Unit& u, int wr, int wc, int fr, int fq) const {
;     ...
;         } else {
;             if (u.pm >= 128) return;
;             const int col = (pn - 24) * 128 + cl;
; #pragma unroll
;             for (int ai = 0; ai < 2; ++ai)
; #pragma unroll
;                 for (int m = 0; m < 4; ++m) {
;                     const f32x4 a = acc[ai][0][m][0] * acc[ai][1][m][0], b = acc[ai][0][m][1] * acc[ai][1][m][1];
;                     u32x4 w; w.x = cvt_pk_bf16(a[0], a[1]); w.y = cvt_pk_bf16(a[2], a[3]); w.z = cvt_pk_bf16(b[0], b[1]); w.w = cvt_pk_bf16(b[2], b[3]);
;                     *(u32x4*)(P + (size_t)(row0 + ai * 128 + m * 16) * 1024 + col) = w;
;                 }
	v_pk_mul_f32 v[130:131], v[126:127], v[62:63]
	v_pk_mul_f32 v[128:129], v[124:125], v[60:61]
	v_pk_mul_f32 v[132:133], v[122:123], v[58:59]
	v_ashrrev_i32_e32 v155, 31, v154
	v_lshl_add_u32 v144, s66, 7, v161
	v_pk_mul_f32 v[134:135], v[120:121], v[56:57]
	v_cvt_pk_bf16_f32 v128, v128, v129
	v_cvt_pk_bf16_f32 v129, v130, v131
	v_cvt_pk_bf16_f32 v131, v132, v133
	v_lshlrev_b64 v[132:133], 11, v[154:155]
	v_cvt_pk_bf16_f32 v130, v134, v135
	v_lshl_add_u64 v[132:133], s[8:9], 0, v[132:133]
	v_lshlrev_b64 v[134:135], 1, v[144:145]
	v_lshl_add_u64 v[132:133], v[132:133], 0, v[134:135]
	global_store_dwordx4 v[132:133], v[128:131], off
	v_pk_mul_f32 v[156:157], v[114:115], v[50:51]
	v_pk_mul_f32 v[158:159], v[112:113], v[48:49]
	v_pk_mul_f32 v[130:131], v[118:119], v[54:55]
	v_pk_mul_f32 v[128:129], v[116:117], v[52:53]
	s_mov_b32 s0, 0x40000
	v_cvt_pk_bf16_f32 v128, v128, v129
	v_cvt_pk_bf16_f32 v129, v130, v131
	v_cvt_pk_bf16_f32 v131, v156, v157
	v_or_b32_e32 v156, 16, v154
	v_ashrrev_i32_e32 v157, 31, v156
	v_lshlrev_b64 v[156:157], 11, v[156:157]
	v_lshl_add_u64 v[156:157], s[8:9], 0, v[156:157]
	v_cvt_pk_bf16_f32 v130, v158, v159
	v_lshl_add_u64 v[156:157], v[156:157], 0, v[134:135]
	global_store_dwordx4 v[156:157], v[128:131], off
	v_pk_mul_f32 v[156:157], v[106:107], v[42:43]
	v_pk_mul_f32 v[158:159], v[104:105], v[40:41]
	v_pk_mul_f32 v[130:131], v[110:111], v[46:47]
	v_pk_mul_f32 v[128:129], v[108:109], v[44:45]
	s_nop 0
	v_cvt_pk_bf16_f32 v128, v128, v129
	v_cvt_pk_bf16_f32 v129, v130, v131
	v_cvt_pk_bf16_f32 v131, v156, v157
	v_or_b32_e32 v156, 32, v154
	v_ashrrev_i32_e32 v157, 31, v156
	v_lshlrev_b64 v[156:157], 11, v[156:157]
	v_lshl_add_u64 v[156:157], s[8:9], 0, v[156:157]
	v_cvt_pk_bf16_f32 v130, v158, v159
	v_lshl_add_u64 v[156:157], v[156:157], 0, v[134:135]
	global_store_dwordx4 v[156:157], v[128:131], off
	v_pk_mul_f32 v[156:157], v[98:99], v[34:35]
	v_pk_mul_f32 v[158:159], v[96:97], v[32:33]
	v_pk_mul_f32 v[130:131], v[102:103], v[38:39]
	v_pk_mul_f32 v[128:129], v[100:101], v[36:37]
	s_nop 0
	v_cvt_pk_bf16_f32 v128, v128, v129
	v_cvt_pk_bf16_f32 v129, v130, v131
	v_cvt_pk_bf16_f32 v131, v156, v157
	v_or_b32_e32 v156, 48, v154
	v_ashrrev_i32_e32 v157, 31, v156
	v_lshlrev_b64 v[156:157], 11, v[156:157]
	v_lshl_add_u64 v[156:157], s[8:9], 0, v[156:157]
	v_cvt_pk_bf16_f32 v130, v158, v159
	v_lshl_add_u64 v[134:135], v[156:157], 0, v[134:135]
	global_store_dwordx4 v[134:135], v[128:131], off
	v_pk_mul_f32 v[134:135], v[90:91], v[26:27]
	v_pk_mul_f32 v[156:157], v[88:89], v[24:25]
	v_pk_mul_f32 v[130:131], v[94:95], v[30:31]
	v_pk_mul_f32 v[128:129], v[92:93], v[28:29]
	s_nop 0
	v_cvt_pk_bf16_f32 v128, v128, v129
	v_cvt_pk_bf16_f32 v129, v130, v131
	v_cvt_pk_bf16_f32 v131, v134, v135
	v_add_co_u32_e32 v134, vcc, s0, v132
	v_cvt_pk_bf16_f32 v130, v156, v157
	s_nop 0
	v_addc_co_u32_e32 v135, vcc, 0, v133, vcc
	global_store_dwordx4 v[134:135], v[128:131], off
	v_pk_mul_f32 v[134:135], v[82:83], v[18:19]
	s_mov_b32 s0, 0x48000
	v_pk_mul_f32 v[130:131], v[86:87], v[22:23]
	v_pk_mul_f32 v[128:129], v[84:85], v[20:21]
	v_pk_mul_f32 v[156:157], v[80:81], v[16:17]
	v_cvt_pk_bf16_f32 v128, v128, v129
	v_cvt_pk_bf16_f32 v129, v130, v131
	v_cvt_pk_bf16_f32 v131, v134, v135
	v_add_co_u32_e32 v134, vcc, s0, v132
	v_cvt_pk_bf16_f32 v130, v156, v157
	s_nop 0
	v_addc_co_u32_e32 v135, vcc, 0, v133, vcc
	global_store_dwordx4 v[134:135], v[128:131], off
	v_pk_mul_f32 v[134:135], v[74:75], v[10:11]
	s_mov_b32 s0, 0x50000
	v_pk_mul_f32 v[130:131], v[78:79], v[14:15]
	v_pk_mul_f32 v[128:129], v[76:77], v[12:13]
	v_pk_mul_f32 v[156:157], v[72:73], v[8:9]
	v_cvt_pk_bf16_f32 v128, v128, v129
	v_cvt_pk_bf16_f32 v129, v130, v131
	v_cvt_pk_bf16_f32 v131, v134, v135
	v_add_co_u32_e32 v134, vcc, s0, v132
	v_cvt_pk_bf16_f32 v130, v156, v157
	s_nop 0
	v_addc_co_u32_e32 v135, vcc, 0, v133, vcc
	global_store_dwordx4 v[134:135], v[128:131], off
	v_pk_mul_f32 v[134:135], v[66:67], v[2:3]
	v_pk_mul_f32 v[156:157], v[64:65], v[0:1]
	v_pk_mul_f32 v[130:131], v[70:71], v[6:7]
	v_pk_mul_f32 v[128:129], v[68:69], v[4:5]
	v_add_co_u32_e32 v132, vcc, 0x58000, v132
	v_cvt_pk_bf16_f32 v128, v128, v129
	v_cvt_pk_bf16_f32 v129, v130, v131
	v_cvt_pk_bf16_f32 v130, v156, v157
	v_cvt_pk_bf16_f32 v131, v134, v135
	v_addc_co_u32_e32 v133, vcc, 0, v133, vcc
	global_store_dwordx4 v[132:133], v[128:131], off

; #define PG8_STAGE(bufoff, gbase, voff) do { _Pragma("unroll") for (int _i = 0; _i < 2; ++_i) \
;         __builtin_amdgcn_global_load_lds((const unsigned*)((const char*)(gbase) + (voff)[_i]), (PG8_LAS unsigned*)(lds + (bufoff) + ldsw + _i * 8192), 16, 0, 0); } while (0)
; #define PG8_LDA(dst, b, h) do { _Pragma("unroll") for (int m = 0; m < 4; ++m) _Pragma("unroll") for (int k = 0; k < 2; ++k) dst[m][k] = *(const PG8_LAS bf16x8*)(lds + PG8_SA(b, h) + aoff + m * 2048 + k * 1024); } while (0)
; #define PG8_LDB(dst, b, h) do { _Pragma("unroll") for (int n = 0; n < 2; ++n) _Pragma("unroll") for (int k = 0; k < 2; ++k) dst[n][k] = *(const PG8_LAS bf16x8*)(lds + PG8_SB(b, h) + boff + n * 2048 + k * 1024); } while (0)
; #define PG8_MMA(ai, bj, At, Bt) do { __builtin_amdgcn_s_setprio(1); _Pragma("unroll") for (int m = 0; m < 4; ++m) _Pragma("unroll") for (int n = 0; n < 2; ++n) _Pragma("unroll") for (int k = 0; k < 2; ++k) \
;         acc[ai][bj][m][n] = __builtin_amdgcn_mfma_f32_16x16x32_bf16(Bt[n][k], At[m][k], acc[ai][bj][m][n], 0, 0, 0); __builtin_amdgcn_s_setprio(0); } while (0)
; #define PG8_WAIT_L(n) asm volatile("s_waitcnt lgkmcnt(" #n ")" ::: "memory")
; #define PG8_BAR __builtin_amdgcn_s_barrier()
; #define PG8_SCHED __builtin_amdgcn_sched_barrier(0)
;     __device__ __forceinline__ bool next(int i, pg8::Unit& u) const { if (i != 0) return false; u.pm = pm; u.pn = pn; return true; }
; template <class Epi, class Sched>
; __device__ __forceinline__ void gemm_phase(PG8_LAS unsigned char* lds, const Gemm g, const Sched& S, const Epi& E) {
;     ...
;         const bool has_next = S.next(ui + 1, nxt);
;         const char* nA = has_next ? (const char*)g.A + (size_t)nxt.pm * tstep : cA; const char* nB = has_next ? (const char*)g.Bt + (size_t)nxt.pn * tstep : cB;
;         for (int t = 0; t < nt; t += 2) {
;             const bool last = (t == nt - 2);
;             const char* a1 = cA + (size_t)(t + 1) * kstep;
;             const char* a2 = last ? nA : cA + (size_t)(t + 2) * kstep; const char* b2 = last ? nB : cB + (size_t)(t + 2) * kstep;
;             const char* a3 = a2 + kstep; const char* b3 = b2 + kstep;
;             if (last && has_next) S.a_ready(nxt);
;             PG8_LDB(B0, 0, 0); PG8_SCHED; PG8_LDA(At, 0, 0); PG8_STAGE(PG8_SA(1, 1), a1 + hstep, voffA);
;             PG8_WAIT_L(8); PG8_BAR; PG8_WAIT_L(0); PG8_MMA(0, 0, At, B0); PG8_BAR; PG8_SCHED;
.LBB0_665:
	s_ashr_i32 s19, s18, 31
	s_lshl_b64 s[10:11], s[18:19], 20
	v_cmp_lt_i64_e32 vcc, s[20:21], v[156:157]
	s_add_u32 s20, s41, s10
	s_addc_u32 s21, s42, s11
	s_and_b64 s[10:11], vcc, exec
	s_cselect_b32 s19, s21, s31
	s_cselect_b32 s70, s20, s30
	s_ashr_i32 s17, s16, 31
	s_lshl_b64 s[10:11], s[16:17], 20
	s_add_u32 s26, s43, s10
	s_addc_u32 s27, s44, s11
	s_and_b64 s[10:11], vcc, exec
	s_cselect_b32 s17, s27, s35
	s_cselect_b32 s71, s26, s34
	s_add_u32 s30, s30, 0x80080
	s_addc_u32 s31, s31, 0
	s_add_u32 s72, s34, 0x100
	s_addc_u32 s73, s35, 0
	s_mov_b32 s74, -2
	s_setprio 0
	ds_read_b128 v[128:131], v169
	ds_read_b128 v[132:135], v169 offset:1024
	ds_read_b128 v[136:139], v169 offset:2048
	ds_read_b128 v[140:143], v169 offset:3072
	ds_read_b128 v[160:163], v170
	ds_read_b128 v[172:175], v170 offset:1024
	ds_read_b128 v[176:179], v170 offset:2048
	ds_read_b128 v[180:183], v170 offset:3072
	ds_read_b128 v[184:187], v170 offset:4096
	ds_read_b128 v[188:191], v170 offset:5120
	ds_read_b128 v[192:195], v170 offset:6144
	ds_read_b128 v[196:199], v170 offset:7168
	s_waitcnt lgkmcnt(11)
	ds_read_b128 v[200:203], v171
	ds_read_b128 v[204:207], v171 offset:1024
	ds_read_b128 v[208:211], v171 offset:2048
	ds_read_b128 v[212:215], v171 offset:3072
	s_add_u32 s10, s30, 0xfff80080
	s_addc_u32 s11, s31, -1
	s_cmp_eq_u32 s74, 28
	s_cselect_b32 s39, s19, s11
	s_cselect_b32 s38, s70, s10
	s_cselect_b32 s35, s17, s73
	s_cselect_b32 s34, s71, s72
	v_lshl_add_u64 v[164:165], s[30:31], 0, v[152:153]
	s_add_i32 m0, s29, 0xc000
	s_nop 0
	global_load_lds_dwordx4 v[164:165], off
	v_lshl_add_u64 v[164:165], s[30:31], 0, v[154:155]
	s_add_i32 m0, s29, 0xe000
	s_nop 0
	global_load_lds_dwordx4 v[164:165], off
	s_waitcnt vmcnt(8)
	s_waitcnt lgkmcnt(0)
	s_setprio 1
	s_barrier
	v_mfma_f32_16x16x32_bf16 v[120:123], v[128:131], v[160:163], 0
	v_mfma_f32_16x16x32_bf16 v[124:127], v[136:139], v[160:163], 0
	v_mfma_f32_16x16x32_bf16 v[112:115], v[128:131], v[176:179], 0
	v_mfma_f32_16x16x32_bf16 v[116:119], v[136:139], v[176:179], 0
	v_mfma_f32_16x16x32_bf16 v[96:99], v[128:131], v[184:187], 0
	v_mfma_f32_16x16x32_bf16 v[88:91], v[136:139], v[184:187], 0
	v_mfma_f32_16x16x32_bf16 v[80:83], v[128:131], v[192:195], 0
	v_mfma_f32_16x16x32_bf16 v[72:75], v[136:139], v[192:195], 0
	v_mfma_f32_16x16x32_bf16 v[120:123], v[132:135], v[172:175], v[120:123]
	v_mfma_f32_16x16x32_bf16 v[124:127], v[140:143], v[172:175], v[124:127]
	v_mfma_f32_16x16x32_bf16 v[112:115], v[132:135], v[180:183], v[112:115]
	v_mfma_f32_16x16x32_bf16 v[116:119], v[140:143], v[180:183], v[116:119]
	v_mfma_f32_16x16x32_bf16 v[96:99], v[132:135], v[188:191], v[96:99]
	v_mfma_f32_16x16x32_bf16 v[88:91], v[140:143], v[188:191], v[88:91]
	v_mfma_f32_16x16x32_bf16 v[80:83], v[132:135], v[196:199], v[80:83]
	v_mfma_f32_16x16x32_bf16 v[72:75], v[140:143], v[196:199], v[72:75]
	v_mfma_f32_16x16x32_bf16 v[108:111], v[200:203], v[160:163], 0
	v_mfma_f32_16x16x32_bf16 v[104:107], v[208:211], v[160:163], 0
	v_mfma_f32_16x16x32_bf16 v[100:103], v[200:203], v[176:179], 0
	v_mfma_f32_16x16x32_bf16 v[92:95], v[208:211], v[176:179], 0
	v_mfma_f32_16x16x32_bf16 v[84:87], v[200:203], v[184:187], 0
	v_mfma_f32_16x16x32_bf16 v[76:79], v[208:211], v[184:187], 0
	v_mfma_f32_16x16x32_bf16 v[68:71], v[200:203], v[192:195], 0
	v_mfma_f32_16x16x32_bf16 v[64:67], v[208:211], v[192:195], 0
	v_mfma_f32_16x16x32_bf16 v[108:111], v[204:207], v[172:175], v[108:111]
	v_mfma_f32_16x16x32_bf16 v[104:107], v[212:215], v[172:175], v[104:107]
	v_mfma_f32_16x16x32_bf16 v[100:103], v[204:207], v[180:183], v[100:103]
	v_mfma_f32_16x16x32_bf16 v[92:95], v[212:215], v[180:183], v[92:95]
	v_mfma_f32_16x16x32_bf16 v[84:87], v[204:207], v[188:191], v[84:87]
	v_mfma_f32_16x16x32_bf16 v[76:79], v[212:215], v[188:191], v[76:79]
	v_mfma_f32_16x16x32_bf16 v[68:71], v[204:207], v[196:199], v[68:71]
	v_mfma_f32_16x16x32_bf16 v[64:67], v[212:215], v[196:199], v[64:67]
	s_barrier
	s_setprio 0
	ds_read_b128 v[160:163], v170 offset:16384
	ds_read_b128 v[172:175], v170 offset:17408
	ds_read_b128 v[176:179], v170 offset:18432
	ds_read_b128 v[180:183], v170 offset:19456
	ds_read_b128 v[184:187], v170 offset:20480
	ds_read_b128 v[188:191], v170 offset:21504
	ds_read_b128 v[192:195], v170 offset:22528
	ds_read_b128 v[196:199], v170 offset:23552
	s_add_i32 s10, s66, s45
	v_lshl_add_u64 v[164:165], s[34:35], 0, v[146:147]
	s_mov_b32 m0, s10
	s_nop 0
	global_load_lds_dwordx4 v[164:165], off
	v_lshl_add_u64 v[216:217], s[34:35], 0, v[150:151]
	s_add_i32 m0, s10, 0x2000
	s_nop 0
	global_load_lds_dwordx4 v[216:217], off
	s_mov_b32 m0, s29
	v_lshl_add_u64 v[218:219], s[38:39], 0, v[144:145]
	global_load_lds_dwordx4 v[218:219], off
	v_lshl_add_u64 v[220:221], s[38:39], 0, v[148:149]
	s_mov_b32 m0, s46
	s_nop 0
	global_load_lds_dwordx4 v[220:221], off
	s_add_u32 s10, s34, 0x80000
	s_addc_u32 s11, s35, 0
	s_add_i32 s33, s67, s45
	v_lshl_add_u64 v[246:247], s[10:11], 0, v[146:147]
	s_mov_b32 m0, s33
	s_nop 0
	global_load_lds_dwordx4 v[246:247], off
	v_lshl_add_u64 v[246:247], s[10:11], 0, v[150:151]
	s_add_i32 m0, s33, 0x2000
	s_nop 0
	global_load_lds_dwordx4 v[246:247], off
	s_waitcnt vmcnt(8)
	s_waitcnt lgkmcnt(0)
	s_setprio 1
	s_barrier
; #define PG8_STAGE(bufoff, gbase, voff) do { _Pragma("unroll") for (int _i = 0; _i < 2; ++_i) \
;         __builtin_amdgcn_global_load_lds((const unsigned*)((const char*)(gbase) + (voff)[_i]), (PG8_LAS unsigned*)(lds + (bufoff) + ldsw + _i * 8192), 16, 0, 0); } while (0)
; #define PG8_LDA(dst, b, h) do { _Pragma("unroll") for (int m = 0; m < 4; ++m) _Pragma("unroll") for (int k = 0; k < 2; ++k) dst[m][k] = *(const PG8_LAS bf16x8*)(lds + PG8_SA(b, h) + aoff + m * 2048 + k * 1024); } while (0)
; #define PG8_LDB(dst, b, h) do { _Pragma("unroll") for (int n = 0; n < 2; ++n) _Pragma("unroll") for (int k = 0; k < 2; ++k) dst[n][k] = *(const PG8_LAS bf16x8*)(lds + PG8_SB(b, h) + boff + n * 2048 + k * 1024); } while (0)
; #define PG8_MMA(ai, bj, At, Bt) do { __builtin_amdgcn_s_setprio(1); _Pragma("unroll") for (int m = 0; m < 4; ++m) _Pragma("unroll") for (int n = 0; n < 2; ++n) _Pragma("unroll") for (int k = 0; k < 2; ++k) \
;         acc[ai][bj][m][n] = __builtin_amdgcn_mfma_f32_16x16x32_bf16(Bt[n][k], At[m][k], acc[ai][bj][m][n], 0, 0, 0); __builtin_amdgcn_s_setprio(0); } while (0)
; #define PG8_WAIT_V(n) asm volatile("s_waitcnt vmcnt(" #n ")" ::: "memory")
; #define PG8_WAIT_L(n) asm volatile("s_waitcnt lgkmcnt(" #n ")" ::: "memory")
; template <class Epi, class Sched>
; __device__ __forceinline__ void gemm_phase(PG8_LAS unsigned char* lds, const Gemm g, const Sched& S, const Epi& E) {
;     ...
;             PG8_LDB(B0, 0, 0); PG8_SCHED; PG8_LDA(At, 0, 0); PG8_STAGE(PG8_SA(1, 1), a1 + hstep, voffA);
;             PG8_WAIT_L(8); PG8_BAR; PG8_WAIT_L(0); PG8_MMA(0, 0, At, B0); PG8_BAR; PG8_SCHED;
;             PG8_LDB(B1, 0, 1); PG8_STAGE(PG8_SB(0, 0), b2, voffB);
;             PG8_BAR; PG8_WAIT_L(0); PG8_MMA(0, 1, At, B1); PG8_BAR;
;             PG8_LDA(At, 0, 1); PG8_STAGE(PG8_SA(0, 0), a2, voffA);
;             PG8_BAR; PG8_WAIT_L(0); PG8_MMA(1, 0, At, B0); PG8_BAR; PG8_SCHED;
;             PG8_STAGE(PG8_SB(0, 1), b2 + hstep, voffB);
;             PG8_WAIT_V(6); PG8_BAR; PG8_MMA(1, 1, At, B1); PG8_BAR;
;             PG8_LDB(B0, 1, 0); PG8_SCHED; PG8_LDA(At, 1, 0); PG8_STAGE(PG8_SA(0, 1), a2 + hstep, voffA);
;             PG8_WAIT_L(8); PG8_BAR; PG8_WAIT_L(0); PG8_MMA(0, 0, At, B0); PG8_BAR; PG8_SCHED;
;             PG8_LDB(B1, 1, 1); PG8_STAGE(PG8_SB(1, 0), b3, voffB);
;             PG8_BAR; PG8_WAIT_L(0); PG8_MMA(0, 1, At, B1); PG8_BAR;
	v_mfma_f32_16x16x32_bf16 v[60:63], v[128:131], v[160:163], 0
	v_mfma_f32_16x16x32_bf16 v[56:59], v[136:139], v[160:163], 0
	v_mfma_f32_16x16x32_bf16 v[48:51], v[128:131], v[176:179], 0
	v_mfma_f32_16x16x32_bf16 v[40:43], v[136:139], v[176:179], 0
	v_mfma_f32_16x16x32_bf16 v[32:35], v[128:131], v[184:187], 0
	v_mfma_f32_16x16x32_bf16 v[24:27], v[136:139], v[184:187], 0
	v_mfma_f32_16x16x32_bf16 v[16:19], v[128:131], v[192:195], 0
	v_mfma_f32_16x16x32_bf16 v[8:11], v[136:139], v[192:195], 0
	s_add_i32 s33, 0, 0x18000
	v_mfma_f32_16x16x32_bf16 v[60:63], v[132:135], v[172:175], v[60:63]
	v_mfma_f32_16x16x32_bf16 v[56:59], v[140:143], v[172:175], v[56:59]
	v_mfma_f32_16x16x32_bf16 v[48:51], v[132:135], v[180:183], v[48:51]
	v_mfma_f32_16x16x32_bf16 v[40:43], v[140:143], v[180:183], v[40:43]
	v_mfma_f32_16x16x32_bf16 v[32:35], v[132:135], v[188:191], v[32:35]
	v_mfma_f32_16x16x32_bf16 v[24:27], v[140:143], v[188:191], v[24:27]
	v_mfma_f32_16x16x32_bf16 v[16:19], v[132:135], v[196:199], v[16:19]
	v_mfma_f32_16x16x32_bf16 v[8:11], v[140:143], v[196:199], v[8:11]
	v_mfma_f32_16x16x32_bf16 v[52:55], v[200:203], v[160:163], 0
	v_mfma_f32_16x16x32_bf16 v[44:47], v[208:211], v[160:163], 0
	v_mfma_f32_16x16x32_bf16 v[36:39], v[200:203], v[176:179], 0
	v_mfma_f32_16x16x32_bf16 v[28:31], v[208:211], v[176:179], 0
	v_mfma_f32_16x16x32_bf16 v[20:23], v[200:203], v[184:187], 0
	v_mfma_f32_16x16x32_bf16 v[12:15], v[208:211], v[184:187], 0
	v_mfma_f32_16x16x32_bf16 v[4:7], v[200:203], v[192:195], 0
	v_mfma_f32_16x16x32_bf16 v[0:3], v[208:211], v[192:195], 0
	v_mfma_f32_16x16x32_bf16 v[52:55], v[204:207], v[172:175], v[52:55]
	v_mfma_f32_16x16x32_bf16 v[44:47], v[212:215], v[172:175], v[44:47]
	v_mfma_f32_16x16x32_bf16 v[36:39], v[204:207], v[180:183], v[36:39]
	v_mfma_f32_16x16x32_bf16 v[28:31], v[212:215], v[180:183], v[28:31]
	v_mfma_f32_16x16x32_bf16 v[20:23], v[204:207], v[188:191], v[20:23]
	v_mfma_f32_16x16x32_bf16 v[12:15], v[212:215], v[188:191], v[12:15]
	v_mfma_f32_16x16x32_bf16 v[4:7], v[204:207], v[196:199], v[4:7]
	v_mfma_f32_16x16x32_bf16 v[0:3], v[212:215], v[196:199], v[0:3]
	s_barrier
	s_setprio 0
	ds_read_b128 v[128:131], v169 offset:32768
	ds_read_b128 v[132:135], v169 offset:33792
	ds_read_b128 v[136:139], v169 offset:34816
	ds_read_b128 v[140:143], v169 offset:35840
	ds_read_b128 v[160:163], v170 offset:32768
	ds_read_b128 v[172:175], v170 offset:33792
	ds_read_b128 v[176:179], v170 offset:34816
	ds_read_b128 v[180:183], v170 offset:35840
	ds_read_b128 v[184:187], v170 offset:36864
	ds_read_b128 v[188:191], v170 offset:37888
	ds_read_b128 v[192:195], v170 offset:38912
	ds_read_b128 v[196:199], v170 offset:39936
	s_waitcnt lgkmcnt(11)
	ds_read_b128 v[200:203], v171 offset:32768
	ds_read_b128 v[204:207], v171 offset:33792
	ds_read_b128 v[208:211], v171 offset:34816
	ds_read_b128 v[212:215], v171 offset:35840
	s_add_u32 s10, s38, 0x80000
	s_addc_u32 s11, s39, 0
	s_mov_b32 m0, s47
	v_lshl_add_u64 v[246:247], s[10:11], 0, v[144:145]
	global_load_lds_dwordx4 v[246:247], off
	v_lshl_add_u64 v[246:247], s[10:11], 0, v[148:149]
	s_mov_b32 m0, s48
	s_nop 0
	global_load_lds_dwordx4 v[246:247], off
	s_waitcnt vmcnt(8)
	s_waitcnt lgkmcnt(0)
	s_setprio 1
	s_barrier
	v_mfma_f32_16x16x32_bf16 v[120:123], v[128:131], v[160:163], v[120:123]
	v_mfma_f32_16x16x32_bf16 v[124:127], v[136:139], v[160:163], v[124:127]
	v_mfma_f32_16x16x32_bf16 v[112:115], v[128:131], v[176:179], v[112:115]
	v_mfma_f32_16x16x32_bf16 v[116:119], v[136:139], v[176:179], v[116:119]
	v_mfma_f32_16x16x32_bf16 v[96:99], v[128:131], v[184:187], v[96:99]
	v_mfma_f32_16x16x32_bf16 v[88:91], v[136:139], v[184:187], v[88:91]
	v_mfma_f32_16x16x32_bf16 v[80:83], v[128:131], v[192:195], v[80:83]
	v_mfma_f32_16x16x32_bf16 v[72:75], v[136:139], v[192:195], v[72:75]
	v_mfma_f32_16x16x32_bf16 v[120:123], v[132:135], v[172:175], v[120:123]
	v_mfma_f32_16x16x32_bf16 v[124:127], v[140:143], v[172:175], v[124:127]
	v_mfma_f32_16x16x32_bf16 v[112:115], v[132:135], v[180:183], v[112:115]
	v_mfma_f32_16x16x32_bf16 v[116:119], v[140:143], v[180:183], v[116:119]
	v_mfma_f32_16x16x32_bf16 v[96:99], v[132:135], v[188:191], v[96:99]
	v_mfma_f32_16x16x32_bf16 v[88:91], v[140:143], v[188:191], v[88:91]
	v_mfma_f32_16x16x32_bf16 v[80:83], v[132:135], v[196:199], v[80:83]
	v_mfma_f32_16x16x32_bf16 v[72:75], v[140:143], v[196:199], v[72:75]
	v_mfma_f32_16x16x32_bf16 v[108:111], v[200:203], v[160:163], v[108:111]
	v_mfma_f32_16x16x32_bf16 v[104:107], v[208:211], v[160:163], v[104:107]
	v_mfma_f32_16x16x32_bf16 v[100:103], v[200:203], v[176:179], v[100:103]
	v_mfma_f32_16x16x32_bf16 v[92:95], v[208:211], v[176:179], v[92:95]
	v_mfma_f32_16x16x32_bf16 v[84:87], v[200:203], v[184:187], v[84:87]
	v_mfma_f32_16x16x32_bf16 v[76:79], v[208:211], v[184:187], v[76:79]
	v_mfma_f32_16x16x32_bf16 v[68:71], v[200:203], v[192:195], v[68:71]
	v_mfma_f32_16x16x32_bf16 v[64:67], v[208:211], v[192:195], v[64:67]
	v_mfma_f32_16x16x32_bf16 v[108:111], v[204:207], v[172:175], v[108:111]
	v_mfma_f32_16x16x32_bf16 v[104:107], v[212:215], v[172:175], v[104:107]
	v_mfma_f32_16x16x32_bf16 v[100:103], v[204:207], v[180:183], v[100:103]
	v_mfma_f32_16x16x32_bf16 v[92:95], v[212:215], v[180:183], v[92:95]
	v_mfma_f32_16x16x32_bf16 v[84:87], v[204:207], v[188:191], v[84:87]
	v_mfma_f32_16x16x32_bf16 v[76:79], v[212:215], v[188:191], v[76:79]
	v_mfma_f32_16x16x32_bf16 v[68:71], v[204:207], v[196:199], v[68:71]
	v_mfma_f32_16x16x32_bf16 v[64:67], v[212:215], v[196:199], v[64:67]
	s_barrier
; #define PG8_STAGE(bufoff, gbase, voff) do { _Pragma("unroll") for (int _i = 0; _i < 2; ++_i) \
;         __builtin_amdgcn_global_load_lds((const unsigned*)((const char*)(gbase) + (voff)[_i]), (PG8_LAS unsigned*)(lds + (bufoff) + ldsw + _i * 8192), 16, 0, 0); } while (0)
; #define PG8_LDA(dst, b, h) do { _Pragma("unroll") for (int m = 0; m < 4; ++m) _Pragma("unroll") for (int k = 0; k < 2; ++k) dst[m][k] = *(const PG8_LAS bf16x8*)(lds + PG8_SA(b, h) + aoff + m * 2048 + k * 1024); } while (0)
; #define PG8_WAIT_V(n) asm volatile("s_waitcnt vmcnt(" #n ")" ::: "memory")
; template <class Epi, class Sched>
; __device__ __forceinline__ void gemm_phase(PG8_LAS unsigned char* lds, const Gemm g, const Sched& S, const Epi& E) {
;     ...
;         for (int t = 0; t < nt; t += 2) {
;             const bool last = (t == nt - 2);
;             const char* a1 = cA + (size_t)(t + 1) * kstep;
;             const char* a2 = last ? nA : cA + (size_t)(t + 2) * kstep; const char* b2 = last ? nB : cB + (size_t)(t + 2) * kstep;
;             const char* a3 = a2 + kstep; const char* b3 = b2 + kstep;
;             if (last && has_next) S.a_ready(nxt);
;             PG8_LDB(B0, 0, 0); PG8_SCHED; PG8_LDA(At, 0, 0); PG8_STAGE(PG8_SA(1, 1), a1 + hstep, voffA);
;             PG8_WAIT_L(8); PG8_BAR; PG8_WAIT_L(0); PG8_MMA(0, 0, At, B0); PG8_BAR; PG8_SCHED;
;             PG8_LDB(B1, 0, 1); PG8_STAGE(PG8_SB(0, 0), b2, voffB);
;             PG8_BAR; PG8_WAIT_L(0); PG8_MMA(0, 1, At, B1); PG8_BAR;
;             PG8_LDA(At, 0, 1); PG8_STAGE(PG8_SA(0, 0), a2, voffA);
;             PG8_BAR; PG8_WAIT_L(0); PG8_MMA(1, 0, At, B0); PG8_BAR; PG8_SCHED;
;             PG8_STAGE(PG8_SB(0, 1), b2 + hstep, voffB);
;             PG8_WAIT_V(6); PG8_BAR; PG8_MMA(1, 1, At, B1); PG8_BAR;
;             PG8_LDB(B0, 1, 0); PG8_SCHED; PG8_LDA(At, 1, 0); PG8_STAGE(PG8_SA(0, 1), a2 + hstep, voffA);
;             PG8_WAIT_L(8); PG8_BAR; PG8_WAIT_L(0); PG8_MMA(0, 0, At, B0); PG8_BAR; PG8_SCHED;
;             PG8_LDB(B1, 1, 1); PG8_STAGE(PG8_SB(1, 0), b3, voffB);
;             PG8_BAR; PG8_WAIT_L(0); PG8_MMA(0, 1, At, B1); PG8_BAR;
;             PG8_LDA(At, 1, 1); PG8_STAGE(PG8_SA(1, 0), a3, voffA);
;             PG8_BAR; PG8_WAIT_L(0); PG8_MMA(1, 0, At, B0); PG8_BAR; PG8_SCHED;
;             PG8_STAGE(PG8_SB(1, 1), b3 + hstep, voffB);
;             PG8_WAIT_V(6); PG8_BAR; PG8_MMA(1, 1, At, B1); PG8_BAR;
	s_setprio 0
	ds_read_b128 v[160:163], v170 offset:49152
	ds_read_b128 v[172:175], v170 offset:50176
	ds_read_b128 v[176:179], v170 offset:51200
	ds_read_b128 v[180:183], v170 offset:52224
	ds_read_b128 v[184:187], v170 offset:53248
	ds_read_b128 v[188:191], v170 offset:54272
	ds_read_b128 v[192:195], v170 offset:55296
	ds_read_b128 v[196:199], v170 offset:56320
	s_add_i32 s38, 0, 0x1c000
	s_add_i32 s10, s33, s45
	v_lshl_add_u64 v[164:165], v[164:165], 0, s[4:5]
	s_mov_b32 m0, s10
	s_nop 0
	global_load_lds_dwordx4 v[164:165], off
	v_lshl_add_u64 v[164:165], v[216:217], 0, s[4:5]
	s_add_i32 m0, s10, 0x2000
	s_nop 0
	global_load_lds_dwordx4 v[164:165], off
	s_mov_b32 m0, s50
	v_lshl_add_u64 v[164:165], v[218:219], 0, s[4:5]
	global_load_lds_dwordx4 v[164:165], off
	v_lshl_add_u64 v[164:165], v[220:221], 0, s[4:5]
	s_mov_b32 m0, s51
	s_nop 0
	global_load_lds_dwordx4 v[164:165], off
	s_add_u32 s10, s34, 0x80080
	s_addc_u32 s11, s35, 0
	s_add_i32 s33, s38, s45
	v_lshl_add_u64 v[246:247], s[10:11], 0, v[146:147]
	s_mov_b32 m0, s33
	s_nop 0
	global_load_lds_dwordx4 v[246:247], off
	v_lshl_add_u64 v[246:247], s[10:11], 0, v[150:151]
	s_add_i32 m0, s33, 0x2000
	s_nop 0
	global_load_lds_dwordx4 v[246:247], off
	s_waitcnt vmcnt(8)
	s_waitcnt lgkmcnt(0)
	s_setprio 1
	s_barrier
	v_mfma_f32_16x16x32_bf16 v[60:63], v[128:131], v[160:163], v[60:63]
	v_mfma_f32_16x16x32_bf16 v[56:59], v[136:139], v[160:163], v[56:59]
	v_mfma_f32_16x16x32_bf16 v[48:51], v[128:131], v[176:179], v[48:51]
	v_mfma_f32_16x16x32_bf16 v[40:43], v[136:139], v[176:179], v[40:43]
	v_mfma_f32_16x16x32_bf16 v[32:35], v[128:131], v[184:187], v[32:35]
	v_mfma_f32_16x16x32_bf16 v[24:27], v[136:139], v[184:187], v[24:27]
	v_mfma_f32_16x16x32_bf16 v[16:19], v[128:131], v[192:195], v[16:19]
	v_mfma_f32_16x16x32_bf16 v[8:11], v[136:139], v[192:195], v[8:11]
	s_add_i32 s74, s74, 2
	s_add_u32 s30, s30, 0x100
	s_addc_u32 s31, s31, 0
	s_add_u32 s72, s72, 0x100
	s_addc_u32 s73, s73, 0
	s_cmp_gt_u32 s74, 29
	v_mfma_f32_16x16x32_bf16 v[60:63], v[132:135], v[172:175], v[60:63]
	v_mfma_f32_16x16x32_bf16 v[56:59], v[140:143], v[172:175], v[56:59]
	v_mfma_f32_16x16x32_bf16 v[48:51], v[132:135], v[180:183], v[48:51]
	v_mfma_f32_16x16x32_bf16 v[40:43], v[140:143], v[180:183], v[40:43]
	v_mfma_f32_16x16x32_bf16 v[32:35], v[132:135], v[188:191], v[32:35]
	v_mfma_f32_16x16x32_bf16 v[24:27], v[140:143], v[188:191], v[24:27]
	v_mfma_f32_16x16x32_bf16 v[16:19], v[132:135], v[196:199], v[16:19]
	v_mfma_f32_16x16x32_bf16 v[8:11], v[140:143], v[196:199], v[8:11]
	v_mfma_f32_16x16x32_bf16 v[52:55], v[200:203], v[160:163], v[52:55]
	v_mfma_f32_16x16x32_bf16 v[44:47], v[208:211], v[160:163], v[44:47]
	v_mfma_f32_16x16x32_bf16 v[36:39], v[200:203], v[176:179], v[36:39]
	v_mfma_f32_16x16x32_bf16 v[28:31], v[208:211], v[176:179], v[28:31]
	v_mfma_f32_16x16x32_bf16 v[20:23], v[200:203], v[184:187], v[20:23]
	v_mfma_f32_16x16x32_bf16 v[12:15], v[208:211], v[184:187], v[12:15]
	v_mfma_f32_16x16x32_bf16 v[4:7], v[200:203], v[192:195], v[4:7]
	v_mfma_f32_16x16x32_bf16 v[0:3], v[208:211], v[192:195], v[0:3]
	v_mfma_f32_16x16x32_bf16 v[52:55], v[204:207], v[172:175], v[52:55]
	v_mfma_f32_16x16x32_bf16 v[44:47], v[212:215], v[172:175], v[44:47]
	v_mfma_f32_16x16x32_bf16 v[36:39], v[204:207], v[180:183], v[36:39]
	v_mfma_f32_16x16x32_bf16 v[28:31], v[212:215], v[180:183], v[28:31]
	v_mfma_f32_16x16x32_bf16 v[20:23], v[204:207], v[188:191], v[20:23]
	v_mfma_f32_16x16x32_bf16 v[12:15], v[212:215], v[188:191], v[12:15]
	v_mfma_f32_16x16x32_bf16 v[4:7], v[204:207], v[196:199], v[4:7]
	v_mfma_f32_16x16x32_bf16 v[0:3], v[212:215], v[196:199], v[0:3]
	s_barrier
.LBB0_666:
	s_setprio 0
	ds_read_b128 v[128:131], v169
	ds_read_b128 v[132:135], v169 offset:1024
	ds_read_b128 v[136:139], v169 offset:2048
	ds_read_b128 v[140:143], v169 offset:3072
	ds_read_b128 v[160:163], v170
	ds_read_b128 v[172:175], v170 offset:1024
	ds_read_b128 v[176:179], v170 offset:2048
	ds_read_b128 v[180:183], v170 offset:3072
	ds_read_b128 v[184:187], v170 offset:4096
	ds_read_b128 v[188:191], v170 offset:5120
	ds_read_b128 v[192:195], v170 offset:6144
	ds_read_b128 v[196:199], v170 offset:7168
	s_waitcnt lgkmcnt(11)
	ds_read_b128 v[200:203], v171
	ds_read_b128 v[204:207], v171 offset:1024
	ds_read_b128 v[208:211], v171 offset:2048
	ds_read_b128 v[212:215], v171 offset:3072
	s_add_u32 s10, s30, 0xfff80080
	s_addc_u32 s11, s31, -1
	s_cmp_eq_u32 s74, 28
	s_cselect_b32 s39, s19, s11
	s_cselect_b32 s38, s70, s10
	s_cselect_b32 s35, s17, s73
	s_cselect_b32 s34, s71, s72
	v_lshl_add_u64 v[164:165], s[30:31], 0, v[152:153]
	s_add_i32 m0, s29, 0xc000
	s_nop 0
	global_load_lds_dwordx4 v[164:165], off
	v_lshl_add_u64 v[164:165], s[30:31], 0, v[154:155]
	s_add_i32 m0, s29, 0xe000
	s_nop 0
	global_load_lds_dwordx4 v[164:165], off
	s_waitcnt vmcnt(8)
	s_waitcnt lgkmcnt(0)
	s_setprio 1
	s_barrier
; #define PG8_STAGE(bufoff, gbase, voff) do { _Pragma("unroll") for (int _i = 0; _i < 2; ++_i) \
;         __builtin_amdgcn_global_load_lds((const unsigned*)((const char*)(gbase) + (voff)[_i]), (PG8_LAS unsigned*)(lds + (bufoff) + ldsw + _i * 8192), 16, 0, 0); } while (0)
; #define PG8_LDA(dst, b, h) do { _Pragma("unroll") for (int m = 0; m < 4; ++m) _Pragma("unroll") for (int k = 0; k < 2; ++k) dst[m][k] = *(const PG8_LAS bf16x8*)(lds + PG8_SA(b, h) + aoff + m * 2048 + k * 1024); } while (0)
; #define PG8_LDB(dst, b, h) do { _Pragma("unroll") for (int n = 0; n < 2; ++n) _Pragma("unroll") for (int k = 0; k < 2; ++k) dst[n][k] = *(const PG8_LAS bf16x8*)(lds + PG8_SB(b, h) + boff + n * 2048 + k * 1024); } while (0)
; #define PG8_WAIT_V(n) asm volatile("s_waitcnt vmcnt(" #n ")" ::: "memory")
; #define PG8_WAIT_L(n) asm volatile("s_waitcnt lgkmcnt(" #n ")" ::: "memory")
; #define PG8_BAR __builtin_amdgcn_s_barrier()
; #define PG8_SCHED __builtin_amdgcn_sched_barrier(0)
; template <class Epi, class Sched>
; __device__ __forceinline__ void gemm_phase(PG8_LAS unsigned char* lds, const Gemm g, const Sched& S, const Epi& E) {
;     ...
;             PG8_LDB(B0, 0, 0); PG8_SCHED; PG8_LDA(At, 0, 0); PG8_STAGE(PG8_SA(1, 1), a1 + hstep, voffA);
;             PG8_WAIT_L(8); PG8_BAR; PG8_WAIT_L(0); PG8_MMA(0, 0, At, B0); PG8_BAR; PG8_SCHED;
;             PG8_LDB(B1, 0, 1); PG8_STAGE(PG8_SB(0, 0), b2, voffB);
;             PG8_BAR; PG8_WAIT_L(0); PG8_MMA(0, 1, At, B1); PG8_BAR;
;             PG8_LDA(At, 0, 1); PG8_STAGE(PG8_SA(0, 0), a2, voffA);
;             PG8_BAR; PG8_WAIT_L(0); PG8_MMA(1, 0, At, B0); PG8_BAR; PG8_SCHED;
;             PG8_STAGE(PG8_SB(0, 1), b2 + hstep, voffB);
;             PG8_WAIT_V(6); PG8_BAR; PG8_MMA(1, 1, At, B1); PG8_BAR;
;             PG8_LDB(B0, 1, 0); PG8_SCHED; PG8_LDA(At, 1, 0); PG8_STAGE(PG8_SA(0, 1), a2 + hstep, voffA);
;             PG8_WAIT_L(8); PG8_BAR; PG8_WAIT_L(0); PG8_MMA(0, 0, At, B0); PG8_BAR; PG8_SCHED;
;             PG8_LDB(B1, 1, 1); PG8_STAGE(PG8_SB(1, 0), b3, voffB);
;             PG8_BAR; PG8_WAIT_L(0); PG8_MMA(0, 1, At, B1); PG8_BAR;
;             PG8_LDA(At, 1, 1); PG8_STAGE(PG8_SA(1, 0), a3, voffA);
;             PG8_BAR; PG8_WAIT_L(0); PG8_MMA(1, 0, At, B0); PG8_BAR; PG8_SCHED;
;             PG8_STAGE(PG8_SB(1, 1), b3 + hstep, voffB);
;             PG8_WAIT_V(6); PG8_BAR; PG8_MMA(1, 1, At, B1); PG8_BAR;
	v_mfma_f32_16x16x32_bf16 v[120:123], v[128:131], v[160:163], v[120:123]
	v_mfma_f32_16x16x32_bf16 v[124:127], v[136:139], v[160:163], v[124:127]
	v_mfma_f32_16x16x32_bf16 v[112:115], v[128:131], v[176:179], v[112:115]
	v_mfma_f32_16x16x32_bf16 v[116:119], v[136:139], v[176:179], v[116:119]
	v_mfma_f32_16x16x32_bf16 v[96:99], v[128:131], v[184:187], v[96:99]
	v_mfma_f32_16x16x32_bf16 v[88:91], v[136:139], v[184:187], v[88:91]
	v_mfma_f32_16x16x32_bf16 v[80:83], v[128:131], v[192:195], v[80:83]
	v_mfma_f32_16x16x32_bf16 v[72:75], v[136:139], v[192:195], v[72:75]
	v_mfma_f32_16x16x32_bf16 v[120:123], v[132:135], v[172:175], v[120:123]
	v_mfma_f32_16x16x32_bf16 v[124:127], v[140:143], v[172:175], v[124:127]
	v_mfma_f32_16x16x32_bf16 v[112:115], v[132:135], v[180:183], v[112:115]
	v_mfma_f32_16x16x32_bf16 v[116:119], v[140:143], v[180:183], v[116:119]
	v_mfma_f32_16x16x32_bf16 v[96:99], v[132:135], v[188:191], v[96:99]
	v_mfma_f32_16x16x32_bf16 v[88:91], v[140:143], v[188:191], v[88:91]
	v_mfma_f32_16x16x32_bf16 v[80:83], v[132:135], v[196:199], v[80:83]
	v_mfma_f32_16x16x32_bf16 v[72:75], v[140:143], v[196:199], v[72:75]
	v_mfma_f32_16x16x32_bf16 v[108:111], v[200:203], v[160:163], v[108:111]
	v_mfma_f32_16x16x32_bf16 v[104:107], v[208:211], v[160:163], v[104:107]
	v_mfma_f32_16x16x32_bf16 v[100:103], v[200:203], v[176:179], v[100:103]
	v_mfma_f32_16x16x32_bf16 v[92:95], v[208:211], v[176:179], v[92:95]
	v_mfma_f32_16x16x32_bf16 v[84:87], v[200:203], v[184:187], v[84:87]
	v_mfma_f32_16x16x32_bf16 v[76:79], v[208:211], v[184:187], v[76:79]
	v_mfma_f32_16x16x32_bf16 v[68:71], v[200:203], v[192:195], v[68:71]
	v_mfma_f32_16x16x32_bf16 v[64:67], v[208:211], v[192:195], v[64:67]
	v_mfma_f32_16x16x32_bf16 v[108:111], v[204:207], v[172:175], v[108:111]
	v_mfma_f32_16x16x32_bf16 v[104:107], v[212:215], v[172:175], v[104:107]
	v_mfma_f32_16x16x32_bf16 v[100:103], v[204:207], v[180:183], v[100:103]
	v_mfma_f32_16x16x32_bf16 v[92:95], v[212:215], v[180:183], v[92:95]
	v_mfma_f32_16x16x32_bf16 v[84:87], v[204:207], v[188:191], v[84:87]
	v_mfma_f32_16x16x32_bf16 v[76:79], v[212:215], v[188:191], v[76:79]
	v_mfma_f32_16x16x32_bf16 v[68:71], v[204:207], v[196:199], v[68:71]
	v_mfma_f32_16x16x32_bf16 v[64:67], v[212:215], v[196:199], v[64:67]
	s_barrier
	s_setprio 0
	ds_read_b128 v[160:163], v170 offset:16384
	ds_read_b128 v[172:175], v170 offset:17408
	ds_read_b128 v[176:179], v170 offset:18432
	ds_read_b128 v[180:183], v170 offset:19456
	ds_read_b128 v[184:187], v170 offset:20480
	ds_read_b128 v[188:191], v170 offset:21504
	ds_read_b128 v[192:195], v170 offset:22528
	ds_read_b128 v[196:199], v170 offset:23552
	s_add_i32 s10, s66, s45
	v_lshl_add_u64 v[164:165], s[34:35], 0, v[146:147]
	s_mov_b32 m0, s10
	s_nop 0
	global_load_lds_dwordx4 v[164:165], off
	v_lshl_add_u64 v[216:217], s[34:35], 0, v[150:151]
	s_add_i32 m0, s10, 0x2000
	s_nop 0
	global_load_lds_dwordx4 v[216:217], off
	s_mov_b32 m0, s29
	v_lshl_add_u64 v[218:219], s[38:39], 0, v[144:145]
	global_load_lds_dwordx4 v[218:219], off
	v_lshl_add_u64 v[220:221], s[38:39], 0, v[148:149]
	s_mov_b32 m0, s46
	s_nop 0
	global_load_lds_dwordx4 v[220:221], off
	s_add_u32 s10, s34, 0x80000
	s_addc_u32 s11, s35, 0
	s_add_i32 s33, s67, s45
	v_lshl_add_u64 v[246:247], s[10:11], 0, v[146:147]
	s_mov_b32 m0, s33
	s_nop 0
	global_load_lds_dwordx4 v[246:247], off
	v_lshl_add_u64 v[246:247], s[10:11], 0, v[150:151]
	s_add_i32 m0, s33, 0x2000
	s_nop 0
	global_load_lds_dwordx4 v[246:247], off
	s_waitcnt vmcnt(8)
	s_waitcnt lgkmcnt(0)
	s_setprio 1
	s_barrier
	v_mfma_f32_16x16x32_bf16 v[60:63], v[128:131], v[160:163], v[60:63]
	v_mfma_f32_16x16x32_bf16 v[56:59], v[136:139], v[160:163], v[56:59]
	v_mfma_f32_16x16x32_bf16 v[48:51], v[128:131], v[176:179], v[48:51]
	v_mfma_f32_16x16x32_bf16 v[40:43], v[136:139], v[176:179], v[40:43]
	v_mfma_f32_16x16x32_bf16 v[32:35], v[128:131], v[184:187], v[32:35]
	v_mfma_f32_16x16x32_bf16 v[24:27], v[136:139], v[184:187], v[24:27]
	v_mfma_f32_16x16x32_bf16 v[16:19], v[128:131], v[192:195], v[16:19]
	v_mfma_f32_16x16x32_bf16 v[8:11], v[136:139], v[192:195], v[8:11]
	s_add_i32 s33, 0, 0x18000
	v_mfma_f32_16x16x32_bf16 v[60:63], v[132:135], v[172:175], v[60:63]
	v_mfma_f32_16x16x32_bf16 v[56:59], v[140:143], v[172:175], v[56:59]
	v_mfma_f32_16x16x32_bf16 v[48:51], v[132:135], v[180:183], v[48:51]
	v_mfma_f32_16x16x32_bf16 v[40:43], v[140:143], v[180:183], v[40:43]
	v_mfma_f32_16x16x32_bf16 v[32:35], v[132:135], v[188:191], v[32:35]
	v_mfma_f32_16x16x32_bf16 v[24:27], v[140:143], v[188:191], v[24:27]
	v_mfma_f32_16x16x32_bf16 v[16:19], v[132:135], v[196:199], v[16:19]
	v_mfma_f32_16x16x32_bf16 v[8:11], v[140:143], v[196:199], v[8:11]
	v_mfma_f32_16x16x32_bf16 v[52:55], v[200:203], v[160:163], v[52:55]
	v_mfma_f32_16x16x32_bf16 v[44:47], v[208:211], v[160:163], v[44:47]
	v_mfma_f32_16x16x32_bf16 v[36:39], v[200:203], v[176:179], v[36:39]
	v_mfma_f32_16x16x32_bf16 v[28:31], v[208:211], v[176:179], v[28:31]
	v_mfma_f32_16x16x32_bf16 v[20:23], v[200:203], v[184:187], v[20:23]
	v_mfma_f32_16x16x32_bf16 v[12:15], v[208:211], v[184:187], v[12:15]
	v_mfma_f32_16x16x32_bf16 v[4:7], v[200:203], v[192:195], v[4:7]
	v_mfma_f32_16x16x32_bf16 v[0:3], v[208:211], v[192:195], v[0:3]
	v_mfma_f32_16x16x32_bf16 v[52:55], v[204:207], v[172:175], v[52:55]
	v_mfma_f32_16x16x32_bf16 v[44:47], v[212:215], v[172:175], v[44:47]
	v_mfma_f32_16x16x32_bf16 v[36:39], v[204:207], v[180:183], v[36:39]
	v_mfma_f32_16x16x32_bf16 v[28:31], v[212:215], v[180:183], v[28:31]
	v_mfma_f32_16x16x32_bf16 v[20:23], v[204:207], v[188:191], v[20:23]
	v_mfma_f32_16x16x32_bf16 v[12:15], v[212:215], v[188:191], v[12:15]
	v_mfma_f32_16x16x32_bf16 v[4:7], v[204:207], v[196:199], v[4:7]
	v_mfma_f32_16x16x32_bf16 v[0:3], v[212:215], v[196:199], v[0:3]
	s_barrier
; #define PG8_STAGE(bufoff, gbase, voff) do { _Pragma("unroll") for (int _i = 0; _i < 2; ++_i) \
;         __builtin_amdgcn_global_load_lds((const unsigned*)((const char*)(gbase) + (voff)[_i]), (PG8_LAS unsigned*)(lds + (bufoff) + ldsw + _i * 8192), 16, 0, 0); } while (0)
; #define PG8_LDA(dst, b, h) do { _Pragma("unroll") for (int m = 0; m < 4; ++m) _Pragma("unroll") for (int k = 0; k < 2; ++k) dst[m][k] = *(const PG8_LAS bf16x8*)(lds + PG8_SA(b, h) + aoff + m * 2048 + k * 1024); } while (0)
; #define PG8_LDB(dst, b, h) do { _Pragma("unroll") for (int n = 0; n < 2; ++n) _Pragma("unroll") for (int k = 0; k < 2; ++k) dst[n][k] = *(const PG8_LAS bf16x8*)(lds + PG8_SB(b, h) + boff + n * 2048 + k * 1024); } while (0)
; #define PG8_MMA(ai, bj, At, Bt) do { __builtin_amdgcn_s_setprio(1); _Pragma("unroll") for (int m = 0; m < 4; ++m) _Pragma("unroll") for (int n = 0; n < 2; ++n) _Pragma("unroll") for (int k = 0; k < 2; ++k) \
;         acc[ai][bj][m][n] = __builtin_amdgcn_mfma_f32_16x16x32_bf16(Bt[n][k], At[m][k], acc[ai][bj][m][n], 0, 0, 0); __builtin_amdgcn_s_setprio(0); } while (0)
; #define PG8_WAIT_V(n) asm volatile("s_waitcnt vmcnt(" #n ")" ::: "memory")
; #define PG8_WAIT_L(n) asm volatile("s_waitcnt lgkmcnt(" #n ")" ::: "memory")
; #define PG8_BAR __builtin_amdgcn_s_barrier()
; #define PG8_SCHED __builtin_amdgcn_sched_barrier(0)
; template <class Epi, class Sched>
; __device__ __forceinline__ void gemm_phase(PG8_LAS unsigned char* lds, const Gemm g, const Sched& S, const Epi& E) {
;     ...
;             PG8_LDB(B0, 1, 0); PG8_SCHED; PG8_LDA(At, 1, 0); PG8_STAGE(PG8_SA(0, 1), a2 + hstep, voffA);
;             PG8_WAIT_L(8); PG8_BAR; PG8_WAIT_L(0); PG8_MMA(0, 0, At, B0); PG8_BAR; PG8_SCHED;
;             PG8_LDB(B1, 1, 1); PG8_STAGE(PG8_SB(1, 0), b3, voffB);
;             PG8_BAR; PG8_WAIT_L(0); PG8_MMA(0, 1, At, B1); PG8_BAR;
;             PG8_LDA(At, 1, 1); PG8_STAGE(PG8_SA(1, 0), a3, voffA);
;             PG8_BAR; PG8_WAIT_L(0); PG8_MMA(1, 0, At, B0); PG8_BAR; PG8_SCHED;
;             PG8_STAGE(PG8_SB(1, 1), b3 + hstep, voffB);
;             PG8_WAIT_V(6); PG8_BAR; PG8_MMA(1, 1, At, B1); PG8_BAR;
	s_setprio 0
	ds_read_b128 v[128:131], v169 offset:32768
	ds_read_b128 v[132:135], v169 offset:33792
	ds_read_b128 v[136:139], v169 offset:34816
	ds_read_b128 v[140:143], v169 offset:35840
	ds_read_b128 v[160:163], v170 offset:32768
	ds_read_b128 v[172:175], v170 offset:33792
	ds_read_b128 v[176:179], v170 offset:34816
	ds_read_b128 v[180:183], v170 offset:35840
	ds_read_b128 v[184:187], v170 offset:36864
	ds_read_b128 v[188:191], v170 offset:37888
	ds_read_b128 v[192:195], v170 offset:38912
	ds_read_b128 v[196:199], v170 offset:39936
	s_waitcnt lgkmcnt(11)
	ds_read_b128 v[200:203], v171 offset:32768
	ds_read_b128 v[204:207], v171 offset:33792
	ds_read_b128 v[208:211], v171 offset:34816
	ds_read_b128 v[212:215], v171 offset:35840
	s_add_u32 s10, s38, 0x80000
	s_addc_u32 s11, s39, 0
	s_mov_b32 m0, s47
	v_lshl_add_u64 v[246:247], s[10:11], 0, v[144:145]
	global_load_lds_dwordx4 v[246:247], off
	v_lshl_add_u64 v[246:247], s[10:11], 0, v[148:149]
	s_mov_b32 m0, s48
	s_nop 0
	global_load_lds_dwordx4 v[246:247], off
	s_waitcnt vmcnt(8)
	s_waitcnt lgkmcnt(0)
	s_setprio 1
	s_barrier
	v_mfma_f32_16x16x32_bf16 v[120:123], v[128:131], v[160:163], v[120:123]
	v_mfma_f32_16x16x32_bf16 v[124:127], v[136:139], v[160:163], v[124:127]
	v_mfma_f32_16x16x32_bf16 v[112:115], v[128:131], v[176:179], v[112:115]
	v_mfma_f32_16x16x32_bf16 v[116:119], v[136:139], v[176:179], v[116:119]
	v_mfma_f32_16x16x32_bf16 v[96:99], v[128:131], v[184:187], v[96:99]
	v_mfma_f32_16x16x32_bf16 v[88:91], v[136:139], v[184:187], v[88:91]
	v_mfma_f32_16x16x32_bf16 v[80:83], v[128:131], v[192:195], v[80:83]
	v_mfma_f32_16x16x32_bf16 v[72:75], v[136:139], v[192:195], v[72:75]
	v_mfma_f32_16x16x32_bf16 v[120:123], v[132:135], v[172:175], v[120:123]
	v_mfma_f32_16x16x32_bf16 v[124:127], v[140:143], v[172:175], v[124:127]
	v_mfma_f32_16x16x32_bf16 v[112:115], v[132:135], v[180:183], v[112:115]
	v_mfma_f32_16x16x32_bf16 v[116:119], v[140:143], v[180:183], v[116:119]
	v_mfma_f32_16x16x32_bf16 v[96:99], v[132:135], v[188:191], v[96:99]
	v_mfma_f32_16x16x32_bf16 v[88:91], v[140:143], v[188:191], v[88:91]
	v_mfma_f32_16x16x32_bf16 v[80:83], v[132:135], v[196:199], v[80:83]
	v_mfma_f32_16x16x32_bf16 v[72:75], v[140:143], v[196:199], v[72:75]
	v_mfma_f32_16x16x32_bf16 v[108:111], v[200:203], v[160:163], v[108:111]
	v_mfma_f32_16x16x32_bf16 v[104:107], v[208:211], v[160:163], v[104:107]
	v_mfma_f32_16x16x32_bf16 v[100:103], v[200:203], v[176:179], v[100:103]
	v_mfma_f32_16x16x32_bf16 v[92:95], v[208:211], v[176:179], v[92:95]
	v_mfma_f32_16x16x32_bf16 v[84:87], v[200:203], v[184:187], v[84:87]
	v_mfma_f32_16x16x32_bf16 v[76:79], v[208:211], v[184:187], v[76:79]
	v_mfma_f32_16x16x32_bf16 v[68:71], v[200:203], v[192:195], v[68:71]
	v_mfma_f32_16x16x32_bf16 v[64:67], v[208:211], v[192:195], v[64:67]
	v_mfma_f32_16x16x32_bf16 v[108:111], v[204:207], v[172:175], v[108:111]
	v_mfma_f32_16x16x32_bf16 v[104:107], v[212:215], v[172:175], v[104:107]
	v_mfma_f32_16x16x32_bf16 v[100:103], v[204:207], v[180:183], v[100:103]
	v_mfma_f32_16x16x32_bf16 v[92:95], v[212:215], v[180:183], v[92:95]
	v_mfma_f32_16x16x32_bf16 v[84:87], v[204:207], v[188:191], v[84:87]
	v_mfma_f32_16x16x32_bf16 v[76:79], v[212:215], v[188:191], v[76:79]
	v_mfma_f32_16x16x32_bf16 v[68:71], v[204:207], v[196:199], v[68:71]
	v_mfma_f32_16x16x32_bf16 v[64:67], v[212:215], v[196:199], v[64:67]
	s_barrier
	s_setprio 0
	ds_read_b128 v[160:163], v170 offset:49152
	ds_read_b128 v[172:175], v170 offset:50176
	ds_read_b128 v[176:179], v170 offset:51200
	ds_read_b128 v[180:183], v170 offset:52224
	ds_read_b128 v[184:187], v170 offset:53248
	ds_read_b128 v[188:191], v170 offset:54272
	ds_read_b128 v[192:195], v170 offset:55296
	ds_read_b128 v[196:199], v170 offset:56320
	s_add_i32 s38, 0, 0x1c000
	s_add_i32 s10, s33, s45
	v_lshl_add_u64 v[164:165], v[164:165], 0, s[4:5]
	s_mov_b32 m0, s10
	s_nop 0
	global_load_lds_dwordx4 v[164:165], off
	v_lshl_add_u64 v[164:165], v[216:217], 0, s[4:5]
	s_add_i32 m0, s10, 0x2000
	s_nop 0
	global_load_lds_dwordx4 v[164:165], off
	s_mov_b32 m0, s50
	v_lshl_add_u64 v[164:165], v[218:219], 0, s[4:5]
	global_load_lds_dwordx4 v[164:165], off
	v_lshl_add_u64 v[164:165], v[220:221], 0, s[4:5]
	s_mov_b32 m0, s51
	s_nop 0
	global_load_lds_dwordx4 v[164:165], off
	s_add_u32 s10, s34, 0x80080
	s_addc_u32 s11, s35, 0
	s_add_i32 s33, s38, s45
	v_lshl_add_u64 v[246:247], s[10:11], 0, v[146:147]
	s_mov_b32 m0, s33
	s_nop 0
	global_load_lds_dwordx4 v[246:247], off
	v_lshl_add_u64 v[246:247], s[10:11], 0, v[150:151]
	s_add_i32 m0, s33, 0x2000
	s_nop 0
	global_load_lds_dwordx4 v[246:247], off
	s_waitcnt vmcnt(8)
	s_waitcnt lgkmcnt(0)
	s_setprio 1
	s_barrier
; #define PG8_MMA(ai, bj, At, Bt) do { __builtin_amdgcn_s_setprio(1); _Pragma("unroll") for (int m = 0; m < 4; ++m) _Pragma("unroll") for (int n = 0; n < 2; ++n) _Pragma("unroll") for (int k = 0; k < 2; ++k) \
;         acc[ai][bj][m][n] = __builtin_amdgcn_mfma_f32_16x16x32_bf16(Bt[n][k], At[m][k], acc[ai][bj][m][n], 0, 0, 0); __builtin_amdgcn_s_setprio(0); } while (0)
; #define PG8_WAIT_V(n) asm volatile("s_waitcnt vmcnt(" #n ")" ::: "memory")
; #define PG8_BAR __builtin_amdgcn_s_barrier()
; template <class Epi, class Sched>
; __device__ __forceinline__ void gemm_phase(PG8_LAS unsigned char* lds, const Gemm g, const Sched& S, const Epi& E) {
;     ...
;             PG8_WAIT_V(6); PG8_BAR; PG8_MMA(1, 1, At, B1); PG8_BAR;
;         }
;         E(acc, cur, wr, wc, fr, fq); S.done(cur);
;         if (!has_next) break;
;     __device__ __forceinline__ void operator()(const AccT& acc, const pg8::Unit& u, int wr, int wc, int fr, int fq) const {
;         const int row0 = u.pm * 256 + wr * 64 + fr, col0 = u.pn * 256 + wc * 32 + 8 * fq;
;         const float* ga = mod + (u.pm >= 64 ? 12288 : 0) + 2 * 2048;
;         f32x4 gv[2][2];
; #pragma unroll
;         for (int bj = 0; bj < 2; ++bj)
; #pragma unroll
;             for (int n = 0; n < 2; ++n) gv[bj][n] = *(const f32x4*)(ga + col0 + bj * 128 + n * 4);
; #pragma unroll
;         for (int ai = 0; ai < 2; ++ai) {
;             f32x4 xa[4][2], xb[4][2];
; #pragma unroll
;             for (int m = 0; m < 4; ++m) { const size_t off = (size_t)(row0 + ai * 128 + m * 16) * D + col0;
; #pragma unroll
;                 for (int bj = 0; bj < 2; ++bj) { xa[m][bj] = *(const f32x4*)(x + off + bj * 128); xb[m][bj] = *(const f32x4*)(x + off + bj * 128 + 4); } }
	v_mfma_f32_16x16x32_bf16 v[60:63], v[128:131], v[160:163], v[60:63]
	v_mfma_f32_16x16x32_bf16 v[56:59], v[136:139], v[160:163], v[56:59]
	v_mfma_f32_16x16x32_bf16 v[48:51], v[128:131], v[176:179], v[48:51]
	v_mfma_f32_16x16x32_bf16 v[40:43], v[136:139], v[176:179], v[40:43]
	v_mfma_f32_16x16x32_bf16 v[32:35], v[128:131], v[184:187], v[32:35]
	v_mfma_f32_16x16x32_bf16 v[24:27], v[136:139], v[184:187], v[24:27]
	v_mfma_f32_16x16x32_bf16 v[16:19], v[128:131], v[192:195], v[16:19]
	v_mfma_f32_16x16x32_bf16 v[8:11], v[136:139], v[192:195], v[8:11]
	s_add_i32 s74, s74, 2
	s_add_u32 s30, s30, 0x100
	s_addc_u32 s31, s31, 0
	s_add_u32 s72, s72, 0x100
	s_addc_u32 s73, s73, 0
	s_cmp_gt_u32 s74, 29
	v_mfma_f32_16x16x32_bf16 v[60:63], v[132:135], v[172:175], v[60:63]
	v_mfma_f32_16x16x32_bf16 v[56:59], v[140:143], v[172:175], v[56:59]
	v_mfma_f32_16x16x32_bf16 v[48:51], v[132:135], v[180:183], v[48:51]
	v_mfma_f32_16x16x32_bf16 v[40:43], v[140:143], v[180:183], v[40:43]
	v_mfma_f32_16x16x32_bf16 v[32:35], v[132:135], v[188:191], v[32:35]
	v_mfma_f32_16x16x32_bf16 v[24:27], v[140:143], v[188:191], v[24:27]
	v_mfma_f32_16x16x32_bf16 v[16:19], v[132:135], v[196:199], v[16:19]
	v_mfma_f32_16x16x32_bf16 v[8:11], v[140:143], v[196:199], v[8:11]
	v_mfma_f32_16x16x32_bf16 v[52:55], v[200:203], v[160:163], v[52:55]
	v_mfma_f32_16x16x32_bf16 v[44:47], v[208:211], v[160:163], v[44:47]
	v_mfma_f32_16x16x32_bf16 v[36:39], v[200:203], v[176:179], v[36:39]
	v_mfma_f32_16x16x32_bf16 v[28:31], v[208:211], v[176:179], v[28:31]
	v_mfma_f32_16x16x32_bf16 v[20:23], v[200:203], v[184:187], v[20:23]
	v_mfma_f32_16x16x32_bf16 v[12:15], v[208:211], v[184:187], v[12:15]
	v_mfma_f32_16x16x32_bf16 v[4:7], v[200:203], v[192:195], v[4:7]
	v_mfma_f32_16x16x32_bf16 v[0:3], v[208:211], v[192:195], v[0:3]
	v_mfma_f32_16x16x32_bf16 v[52:55], v[204:207], v[172:175], v[52:55]
	v_mfma_f32_16x16x32_bf16 v[44:47], v[212:215], v[172:175], v[44:47]
	v_mfma_f32_16x16x32_bf16 v[36:39], v[204:207], v[180:183], v[36:39]
	v_mfma_f32_16x16x32_bf16 v[28:31], v[212:215], v[180:183], v[28:31]
	v_mfma_f32_16x16x32_bf16 v[20:23], v[204:207], v[188:191], v[20:23]
	v_mfma_f32_16x16x32_bf16 v[12:15], v[212:215], v[188:191], v[12:15]
	v_mfma_f32_16x16x32_bf16 v[4:7], v[204:207], v[196:199], v[4:7]
	v_mfma_f32_16x16x32_bf16 v[0:3], v[212:215], v[196:199], v[0:3]
	s_barrier
	s_cbranch_scc0 .LBB0_666
	s_setprio 0
	v_lshl_or_b32 v160, s69, 8, v168
	s_cmp_gt_i32 s28, 63
	v_ashrrev_i32_e32 v161, 31, v160
	v_lshl_add_u32 v164, s28, 8, v166
	s_cselect_b32 s10, 0xc000, 0
	v_lshlrev_b64 v[128:129], 2, v[160:161]
	v_ashrrev_i32_e32 v165, 31, v164
	s_add_u32 s10, s58, s10
	v_lshl_add_u64 v[162:163], s[36:37], 0, v[128:129]
	v_lshlrev_b64 v[130:131], 13, v[164:165]
	v_or_b32_e32 v220, 16, v164
	s_addc_u32 s11, s59, 0
	v_lshl_add_u64 v[130:131], v[162:163], 0, v[130:131]
	v_ashrrev_i32_e32 v221, 31, v220
	global_load_dwordx4 v[172:175], v[130:131], off offset:16
	global_load_dwordx4 v[176:179], v[130:131], off
	global_load_dwordx4 v[180:183], v[130:131], off offset:528
	global_load_dwordx4 v[184:187], v[130:131], off offset:512
	v_lshlrev_b64 v[130:131], 13, v[220:221]
	v_lshl_add_u64 v[128:129], s[10:11], 0, v[128:129]
	v_lshl_add_u64 v[200:201], v[162:163], 0, v[130:131]
	v_lshl_add_u64 v[130:131], v[128:129], 0, s[6:7]
	global_load_dwordx4 v[188:191], v[200:201], off offset:16
	global_load_dwordx4 v[192:195], v[200:201], off
	global_load_dwordx4 v[136:139], v[130:131], off offset:16
	global_load_dwordx4 v[132:135], v[130:131], off offset:512
	v_add_co_u32_e32 v128, vcc, s68, v128
	v_or_b32_e32 v236, 32, v164
	s_nop 0
	v_addc_co_u32_e32 v129, vcc, 0, v129, vcc
	global_load_dwordx4 v[140:143], v[128:129], off
	s_nop 0
	global_load_dwordx4 v[128:131], v[130:131], off offset:528
	s_nop 0
	global_load_dwordx4 v[196:199], v[200:201], off offset:512
	s_nop 0
	global_load_dwordx4 v[200:203], v[200:201], off offset:528
	v_ashrrev_i32_e32 v237, 31, v236
	v_lshlrev_b64 v[204:205], 13, v[236:237]
	v_lshl_add_u64 v[216:217], v[162:163], 0, v[204:205]
	global_load_dwordx4 v[204:207], v[216:217], off
	global_load_dwordx4 v[208:211], v[216:217], off offset:16
	global_load_dwordx4 v[212:215], v[216:217], off offset:528
	s_nop 0
	global_load_dwordx4 v[216:219], v[216:217], off offset:512
	v_or_b32_e32 v238, 48, v164
	v_ashrrev_i32_e32 v239, 31, v238
	v_lshlrev_b64 v[222:223], 12, v[164:165]
	v_lshlrev_b64 v[224:225], 13, v[238:239]
	v_lshlrev_b64 v[160:161], 1, v[160:161]
	v_lshl_add_u64 v[222:223], s[0:1], 0, v[222:223]
	v_lshl_add_u64 v[232:233], v[162:163], 0, v[224:225]
	v_lshlrev_b64 v[240:241], 12, v[220:221]
	v_lshl_add_u64 v[244:245], v[222:223], 0, v[160:161]
	global_load_dwordx4 v[220:223], v[232:233], off offset:16
	global_load_dwordx4 v[224:227], v[232:233], off
	global_load_dwordx4 v[228:231], v[232:233], off offset:528
	s_nop 0
	global_load_dwordx4 v[232:235], v[232:233], off offset:512
	s_and_b64 vcc, exec, s[2:3]
	s_mov_b32 s69, s16
	s_mov_b32 s28, s18
	s_mov_b64 s[34:35], s[26:27]
	s_mov_b64 s[30:31], s[20:21]
	s_waitcnt vmcnt(0)
;     __device__ __forceinline__ void operator()(const AccT& acc, const pg8::Unit& u, int wr, int wc, int fr, int fq) const {
;     ...
;         for (int ai = 0; ai < 2; ++ai) {
;             f32x4 xa[4][2], xb[4][2];
; #pragma unroll
;             for (int m = 0; m < 4; ++m) { const size_t off = (size_t)(row0 + ai * 128 + m * 16) * D + col0;
; #pragma unroll
;                 for (int bj = 0; bj < 2; ++bj) { xa[m][bj] = *(const f32x4*)(x + off + bj * 128); xb[m][bj] = *(const f32x4*)(x + off + bj * 128 + 4); } }
; #pragma unroll
;             for (int m = 0; m < 4; ++m) { const size_t off = (size_t)(row0 + ai * 128 + m * 16) * D + col0;
; #pragma unroll
;                 for (int bj = 0; bj < 2; ++bj) {
;                     const f32x4 a = ALPHA * xa[m][bj] + gv[bj][0] * acc[ai][bj][m][0], b = ALPHA * xb[m][bj] + gv[bj][1] * acc[ai][bj][m][1];
;                     u32x4 w; w.x = pk_h2(a[0], a[1]); w.y = pk_h2(a[2], a[3]); w.z = pk_h2(b[0], b[1]); w.w = pk_h2(b[2], b[3]);
;                     *(u32x4*)(U1 + off + bj * 128) = w; } }
	v_pk_mul_f32 v[174:175], v[174:175], s[8:9] op_sel_hi:[1,0]
	v_pk_mul_f32 v[178:179], v[178:179], s[8:9] op_sel_hi:[1,0]
	v_pk_mul_f32 v[176:177], v[176:177], s[8:9] op_sel_hi:[1,0]
	v_pk_mul_f32 v[172:173], v[172:173], s[8:9] op_sel_hi:[1,0]
	v_pk_mul_f32 v[186:187], v[186:187], s[8:9] op_sel_hi:[1,0]
	v_pk_mul_f32 v[184:185], v[184:185], s[8:9] op_sel_hi:[1,0]
	v_pk_mul_f32 v[182:183], v[182:183], s[8:9] op_sel_hi:[1,0]
	v_pk_mul_f32 v[180:181], v[180:181], s[8:9] op_sel_hi:[1,0]
	v_pk_mul_f32 v[194:195], v[194:195], s[8:9] op_sel_hi:[1,0]
	v_pk_fma_f32 v[126:127], v[126:127], v[138:139], v[174:175]
	v_pk_fma_f32 v[124:125], v[124:125], v[136:137], v[172:173]
	v_pk_mul_f32 v[192:193], v[192:193], s[8:9] op_sel_hi:[1,0]
	v_pk_mul_f32 v[190:191], v[190:191], s[8:9] op_sel_hi:[1,0]
	v_pk_fma_f32 v[122:123], v[122:123], v[142:143], v[178:179]
	v_pk_fma_f32 v[120:121], v[120:121], v[140:141], v[176:177]
	v_pk_mul_f32 v[188:189], v[188:189], s[8:9] op_sel_hi:[1,0]
	v_pk_fma_f32 v[172:173], v[110:111], v[134:135], v[186:187]
	v_pk_fma_f32 v[110:111], v[108:109], v[132:133], v[184:185]
	v_cvt_pk_f16_f32 v108, v124, v125
	v_cvt_pk_f16_f32 v109, v126, v127
	v_pk_fma_f32 v[124:125], v[106:107], v[130:131], v[182:183]
	v_pk_fma_f32 v[104:105], v[104:105], v[128:129], v[180:181]
	v_cvt_pk_f16_f32 v106, v120, v121
	v_cvt_pk_f16_f32 v107, v122, v123
	v_pk_fma_f32 v[118:119], v[118:119], v[138:139], v[190:191]
	v_pk_fma_f32 v[116:117], v[116:117], v[136:137], v[188:189]
	v_cvt_pk_f16_f32 v110, v110, v111
	v_cvt_pk_f16_f32 v111, v172, v173
	v_pk_fma_f32 v[114:115], v[114:115], v[142:143], v[194:195]
	v_pk_fma_f32 v[126:127], v[112:113], v[140:141], v[192:193]
	v_cvt_pk_f16_f32 v112, v104, v105
	v_cvt_pk_f16_f32 v113, v124, v125
	global_store_dwordx4 v[244:245], v[106:109], off
	global_store_dwordx4 v[244:245], v[110:113], off offset:256
	v_cvt_pk_f16_f32 v104, v126, v127
	v_lshl_add_u64 v[108:109], s[0:1], 0, v[240:241]
	v_cvt_pk_f16_f32 v105, v114, v115
	v_cvt_pk_f16_f32 v106, v116, v117
	v_cvt_pk_f16_f32 v107, v118, v119
	v_lshl_add_u64 v[108:109], v[108:109], 0, v[160:161]
	global_store_dwordx4 v[108:109], v[104:107], off
	v_add_u32_e32 v172, 0x80, v164
	v_ashrrev_i32_e32 v173, 31, v172
	v_pk_mul_f32 v[104:105], v[198:199], s[8:9] op_sel_hi:[1,0]
	v_pk_mul_f32 v[106:107], v[196:197], s[8:9] op_sel_hi:[1,0]
	v_pk_fma_f32 v[102:103], v[102:103], v[134:135], v[104:105]
	v_pk_fma_f32 v[100:101], v[100:101], v[132:133], v[106:107]
	v_pk_mul_f32 v[104:105], v[202:203], s[8:9] op_sel_hi:[1,0]
	v_pk_mul_f32 v[106:107], v[200:201], s[8:9] op_sel_hi:[1,0]
	v_pk_fma_f32 v[104:105], v[94:95], v[130:131], v[104:105]
	v_pk_fma_f32 v[94:95], v[92:93], v[128:129], v[106:107]
	v_cvt_pk_f16_f32 v92, v100, v101
	v_cvt_pk_f16_f32 v93, v102, v103
	v_cvt_pk_f16_f32 v94, v94, v95
	v_cvt_pk_f16_f32 v95, v104, v105
	global_store_dwordx4 v[108:109], v[92:95], off offset:256
	v_pk_mul_f32 v[100:101], v[204:205], s[8:9] op_sel_hi:[1,0]
	v_add_u32_e32 v174, 0x90, v164
	v_pk_mul_f32 v[94:95], v[206:207], s[8:9] op_sel_hi:[1,0]
	v_lshlrev_b64 v[92:93], 12, v[236:237]
	v_pk_fma_f32 v[94:95], v[98:99], v[142:143], v[94:95]
	v_pk_fma_f32 v[96:97], v[96:97], v[140:141], v[100:101]
	v_pk_mul_f32 v[98:99], v[210:211], s[8:9] op_sel_hi:[1,0]
	v_pk_mul_f32 v[100:101], v[208:209], s[8:9] op_sel_hi:[1,0]
	v_pk_fma_f32 v[98:99], v[90:91], v[138:139], v[98:99]
	v_pk_fma_f32 v[90:91], v[88:89], v[136:137], v[100:101]
	v_lshl_add_u64 v[92:93], s[0:1], 0, v[92:93]
	v_cvt_pk_f16_f32 v88, v96, v97
	v_cvt_pk_f16_f32 v89, v94, v95
	v_cvt_pk_f16_f32 v90, v90, v91
	v_cvt_pk_f16_f32 v91, v98, v99
	v_lshl_add_u64 v[92:93], v[92:93], 0, v[160:161]
	global_store_dwordx4 v[92:93], v[88:91], off
	v_ashrrev_i32_e32 v175, 31, v174
	v_add_u32_e32 v176, 0xa0, v164
	v_pk_mul_f32 v[88:89], v[218:219], s[8:9] op_sel_hi:[1,0]
	v_pk_mul_f32 v[90:91], v[216:217], s[8:9] op_sel_hi:[1,0]
	v_pk_fma_f32 v[86:87], v[86:87], v[134:135], v[88:89]
	v_pk_fma_f32 v[84:85], v[84:85], v[132:133], v[90:91]
	v_pk_mul_f32 v[88:89], v[214:215], s[8:9] op_sel_hi:[1,0]
	v_pk_mul_f32 v[90:91], v[212:213], s[8:9] op_sel_hi:[1,0]
	v_pk_fma_f32 v[88:89], v[78:79], v[130:131], v[88:89]
	v_pk_fma_f32 v[78:79], v[76:77], v[128:129], v[90:91]
	v_cvt_pk_f16_f32 v76, v84, v85
	v_cvt_pk_f16_f32 v77, v86, v87
	v_cvt_pk_f16_f32 v78, v78, v79
	v_cvt_pk_f16_f32 v79, v88, v89
	global_store_dwordx4 v[92:93], v[76:79], off offset:256
	v_pk_mul_f32 v[84:85], v[224:225], s[8:9] op_sel_hi:[1,0]
	v_ashrrev_i32_e32 v177, 31, v176
	v_pk_mul_f32 v[78:79], v[226:227], s[8:9] op_sel_hi:[1,0]
	v_lshlrev_b64 v[76:77], 12, v[238:239]
	v_pk_fma_f32 v[78:79], v[82:83], v[142:143], v[78:79]
	v_pk_fma_f32 v[80:81], v[80:81], v[140:141], v[84:85]
	v_pk_mul_f32 v[82:83], v[222:223], s[8:9] op_sel_hi:[1,0]
	v_pk_mul_f32 v[84:85], v[220:221], s[8:9] op_sel_hi:[1,0]
	v_pk_fma_f32 v[82:83], v[74:75], v[138:139], v[82:83]
	v_pk_fma_f32 v[74:75], v[72:73], v[136:137], v[84:85]
	v_lshl_add_u64 v[76:77], s[0:1], 0, v[76:77]
	v_cvt_pk_f16_f32 v72, v80, v81
	v_cvt_pk_f16_f32 v73, v78, v79
	v_cvt_pk_f16_f32 v74, v74, v75
	v_cvt_pk_f16_f32 v75, v82, v83
	v_lshl_add_u64 v[76:77], v[76:77], 0, v[160:161]
	global_store_dwordx4 v[76:77], v[72:75], off
	v_lshlrev_b64 v[80:81], 13, v[174:175]
	v_lshl_add_u64 v[92:93], v[162:163], 0, v[80:81]
	v_pk_mul_f32 v[72:73], v[234:235], s[8:9] op_sel_hi:[1,0]
	v_pk_mul_f32 v[74:75], v[232:233], s[8:9] op_sel_hi:[1,0]
	v_pk_fma_f32 v[70:71], v[70:71], v[134:135], v[72:73]
	v_pk_fma_f32 v[68:69], v[68:69], v[132:133], v[74:75]
	v_pk_mul_f32 v[72:73], v[230:231], s[8:9] op_sel_hi:[1,0]
	v_pk_mul_f32 v[74:75], v[228:229], s[8:9] op_sel_hi:[1,0]
;     __device__ __forceinline__ void operator()(const AccT& acc, const pg8::Unit& u, int wr, int wc, int fr, int fq) const {
;     ...
;         for (int ai = 0; ai < 2; ++ai) {
;             f32x4 xa[4][2], xb[4][2];
; #pragma unroll
;             for (int m = 0; m < 4; ++m) { const size_t off = (size_t)(row0 + ai * 128 + m * 16) * D + col0;
; #pragma unroll
;                 for (int bj = 0; bj < 2; ++bj) { xa[m][bj] = *(const f32x4*)(x + off + bj * 128); xb[m][bj] = *(const f32x4*)(x + off + bj * 128 + 4); } }
; #pragma unroll
;             for (int m = 0; m < 4; ++m) { const size_t off = (size_t)(row0 + ai * 128 + m * 16) * D + col0;
; #pragma unroll
;                 for (int bj = 0; bj < 2; ++bj) {
;                     const f32x4 a = ALPHA * xa[m][bj] + gv[bj][0] * acc[ai][bj][m][0], b = ALPHA * xb[m][bj] + gv[bj][1] * acc[ai][bj][m][1];
;                     u32x4 w; w.x = pk_h2(a[0], a[1]); w.y = pk_h2(a[2], a[3]); w.z = pk_h2(b[0], b[1]); w.w = pk_h2(b[2], b[3]);
;                     *(u32x4*)(U1 + off + bj * 128) = w; } }
	v_pk_fma_f32 v[72:73], v[66:67], v[130:131], v[72:73]
	v_pk_fma_f32 v[66:67], v[64:65], v[128:129], v[74:75]
	v_cvt_pk_f16_f32 v64, v68, v69
	v_cvt_pk_f16_f32 v65, v70, v71
	v_cvt_pk_f16_f32 v66, v66, v67
	v_cvt_pk_f16_f32 v67, v72, v73
	global_store_dwordx4 v[76:77], v[64:67], off offset:256
	v_lshlrev_b64 v[96:97], 13, v[176:177]
	v_lshl_add_u64 v[108:109], v[162:163], 0, v[96:97]
	v_lshlrev_b64 v[64:65], 13, v[172:173]
	v_lshl_add_u64 v[76:77], v[162:163], 0, v[64:65]
	global_load_dwordx4 v[64:67], v[76:77], off
	global_load_dwordx4 v[68:71], v[76:77], off offset:16
	global_load_dwordx4 v[72:75], v[76:77], off offset:512
	s_nop 0
	global_load_dwordx4 v[76:79], v[76:77], off offset:528
	s_nop 0
	global_load_dwordx4 v[80:83], v[92:93], off
	global_load_dwordx4 v[84:87], v[92:93], off offset:16
	global_load_dwordx4 v[88:91], v[92:93], off offset:512
	s_nop 0
	global_load_dwordx4 v[92:95], v[92:93], off offset:528
	s_nop 0
	global_load_dwordx4 v[96:99], v[108:109], off
	global_load_dwordx4 v[100:103], v[108:109], off offset:16
	global_load_dwordx4 v[104:107], v[108:109], off offset:528
	s_nop 0
	global_load_dwordx4 v[108:111], v[108:109], off offset:512
	v_add_u32_e32 v164, 0xb0, v164
	v_ashrrev_i32_e32 v165, 31, v164
	v_lshlrev_b64 v[112:113], 13, v[164:165]
	v_lshl_add_u64 v[124:125], v[162:163], 0, v[112:113]
	global_load_dwordx4 v[112:115], v[124:125], off offset:16
	global_load_dwordx4 v[116:119], v[124:125], off
	global_load_dwordx4 v[120:123], v[124:125], off offset:528
	s_nop 0
	global_load_dwordx4 v[124:127], v[124:125], off offset:512
	v_lshlrev_b64 v[162:163], 12, v[172:173]
	s_waitcnt vmcnt(0)
; #define PG8_WAIT_V(n) asm volatile("s_waitcnt vmcnt(" #n ")" ::: "memory")
; #define PG8_BAR __builtin_amdgcn_s_barrier()
; template <class Epi, class Sched>
; __device__ __forceinline__ void gemm_phase(PG8_LAS unsigned char* lds, const Gemm g, const Sched& S, const Epi& E) {
;     ...
;         E(acc, cur, wr, wc, fr, fq); S.done(cur);
;         if (!has_next) break;
; #pragma unroll
;         for (int a = 0; a < 2; ++a)
; #pragma unroll
;             for (int b = 0; b < 2; ++b)
; #pragma unroll
;                 for (int m = 0; m < 4; ++m)
; #pragma unroll
;                     for (int n = 0; n < 2; ++n) acc[a][b][m][n] = (f32x4){0.f, 0.f, 0.f, 0.f};
;         cur = nxt; cA = nA; cB = nB; ++ui;
;     }
;     PG8_WAIT_V(0);
;     if (wr == 0) PG8_BAR;
;     PG8_BAR;
;     __device__ __forceinline__ void operator()(const AccT& acc, const pg8::Unit& u, int wr, int wc, int fr, int fq) const {
;     ...
;         for (int ai = 0; ai < 2; ++ai) {
;             f32x4 xa[4][2], xb[4][2];
; #pragma unroll
;             for (int m = 0; m < 4; ++m) { const size_t off = (size_t)(row0 + ai * 128 + m * 16) * D + col0;
; #pragma unroll
;                 for (int bj = 0; bj < 2; ++bj) { xa[m][bj] = *(const f32x4*)(x + off + bj * 128); xb[m][bj] = *(const f32x4*)(x + off + bj * 128 + 4); } }
; #pragma unroll
;             for (int m = 0; m < 4; ++m) { const size_t off = (size_t)(row0 + ai * 128 + m * 16) * D + col0;
; #pragma unroll
;                 for (int bj = 0; bj < 2; ++bj) {
;                     const f32x4 a = ALPHA * xa[m][bj] + gv[bj][0] * acc[ai][bj][m][0], b = ALPHA * xb[m][bj] + gv[bj][1] * acc[ai][bj][m][1];
;                     u32x4 w; w.x = pk_h2(a[0], a[1]); w.y = pk_h2(a[2], a[3]); w.z = pk_h2(b[0], b[1]); w.w = pk_h2(b[2], b[3]);
;                     *(u32x4*)(U1 + off + bj * 128) = w; } }
	v_pk_mul_f32 v[66:67], v[66:67], s[8:9] op_sel_hi:[1,0]
	v_pk_mul_f32 v[64:65], v[64:65], s[8:9] op_sel_hi:[1,0]
	v_pk_fma_f32 v[62:63], v[62:63], v[142:143], v[66:67]
	v_pk_fma_f32 v[60:61], v[60:61], v[140:141], v[64:65]
	v_pk_mul_f32 v[64:65], v[70:71], s[8:9] op_sel_hi:[1,0]
	v_pk_mul_f32 v[66:67], v[68:69], s[8:9] op_sel_hi:[1,0]
	v_pk_fma_f32 v[64:65], v[58:59], v[138:139], v[64:65]
	v_pk_fma_f32 v[58:59], v[56:57], v[136:137], v[66:67]
	v_cvt_pk_f16_f32 v56, v60, v61
	v_lshl_add_u64 v[60:61], s[0:1], 0, v[162:163]
	v_cvt_pk_f16_f32 v57, v62, v63
	v_cvt_pk_f16_f32 v58, v58, v59
	v_cvt_pk_f16_f32 v59, v64, v65
	v_lshl_add_u64 v[60:61], v[60:61], 0, v[160:161]
	global_store_dwordx4 v[60:61], v[56:59], off
	s_nop 1
	v_pk_mul_f32 v[56:57], v[74:75], s[8:9] op_sel_hi:[1,0]
	v_pk_mul_f32 v[58:59], v[72:73], s[8:9] op_sel_hi:[1,0]
	v_pk_fma_f32 v[54:55], v[54:55], v[134:135], v[56:57]
	v_pk_fma_f32 v[52:53], v[52:53], v[132:133], v[58:59]
	v_pk_mul_f32 v[56:57], v[78:79], s[8:9] op_sel_hi:[1,0]
	v_pk_mul_f32 v[58:59], v[76:77], s[8:9] op_sel_hi:[1,0]
	v_pk_fma_f32 v[56:57], v[46:47], v[130:131], v[56:57]
	v_pk_fma_f32 v[46:47], v[44:45], v[128:129], v[58:59]
	v_cvt_pk_f16_f32 v44, v52, v53
	v_cvt_pk_f16_f32 v45, v54, v55
	v_cvt_pk_f16_f32 v46, v46, v47
	v_cvt_pk_f16_f32 v47, v56, v57
	global_store_dwordx4 v[60:61], v[44:47], off offset:256
	v_pk_mul_f32 v[52:53], v[80:81], s[8:9] op_sel_hi:[1,0]
	s_nop 0
	v_pk_mul_f32 v[46:47], v[82:83], s[8:9] op_sel_hi:[1,0]
	v_lshlrev_b64 v[44:45], 12, v[174:175]
	v_pk_fma_f32 v[46:47], v[50:51], v[142:143], v[46:47]
	v_pk_fma_f32 v[48:49], v[48:49], v[140:141], v[52:53]
	v_pk_mul_f32 v[50:51], v[86:87], s[8:9] op_sel_hi:[1,0]
	v_pk_mul_f32 v[52:53], v[84:85], s[8:9] op_sel_hi:[1,0]
	v_pk_fma_f32 v[50:51], v[42:43], v[138:139], v[50:51]
	v_pk_fma_f32 v[42:43], v[40:41], v[136:137], v[52:53]
	v_lshl_add_u64 v[44:45], s[0:1], 0, v[44:45]
	v_cvt_pk_f16_f32 v40, v48, v49
	v_cvt_pk_f16_f32 v41, v46, v47
	v_cvt_pk_f16_f32 v42, v42, v43
	v_cvt_pk_f16_f32 v43, v50, v51
	v_lshl_add_u64 v[44:45], v[44:45], 0, v[160:161]
	global_store_dwordx4 v[44:45], v[40:43], off
	s_nop 1
	v_pk_mul_f32 v[40:41], v[90:91], s[8:9] op_sel_hi:[1,0]
	v_pk_mul_f32 v[42:43], v[88:89], s[8:9] op_sel_hi:[1,0]
	v_pk_fma_f32 v[38:39], v[38:39], v[134:135], v[40:41]
	v_pk_fma_f32 v[36:37], v[36:37], v[132:133], v[42:43]
	v_pk_mul_f32 v[40:41], v[94:95], s[8:9] op_sel_hi:[1,0]
	v_pk_mul_f32 v[42:43], v[92:93], s[8:9] op_sel_hi:[1,0]
	v_pk_fma_f32 v[40:41], v[30:31], v[130:131], v[40:41]
	v_pk_fma_f32 v[30:31], v[28:29], v[128:129], v[42:43]
	v_cvt_pk_f16_f32 v28, v36, v37
	v_cvt_pk_f16_f32 v29, v38, v39
	v_cvt_pk_f16_f32 v30, v30, v31
	v_cvt_pk_f16_f32 v31, v40, v41
	global_store_dwordx4 v[44:45], v[28:31], off offset:256
	v_pk_mul_f32 v[36:37], v[96:97], s[8:9] op_sel_hi:[1,0]
	s_nop 0
	v_pk_mul_f32 v[30:31], v[98:99], s[8:9] op_sel_hi:[1,0]
	v_lshlrev_b64 v[28:29], 12, v[176:177]
	v_pk_fma_f32 v[30:31], v[34:35], v[142:143], v[30:31]
	v_pk_fma_f32 v[32:33], v[32:33], v[140:141], v[36:37]
	v_pk_mul_f32 v[34:35], v[102:103], s[8:9] op_sel_hi:[1,0]
	v_pk_mul_f32 v[36:37], v[100:101], s[8:9] op_sel_hi:[1,0]
	v_pk_fma_f32 v[34:35], v[26:27], v[138:139], v[34:35]
	v_pk_fma_f32 v[26:27], v[24:25], v[136:137], v[36:37]
	v_lshl_add_u64 v[28:29], s[0:1], 0, v[28:29]
	v_cvt_pk_f16_f32 v24, v32, v33
	v_cvt_pk_f16_f32 v25, v30, v31
	v_cvt_pk_f16_f32 v26, v26, v27
	v_cvt_pk_f16_f32 v27, v34, v35
	v_lshl_add_u64 v[28:29], v[28:29], 0, v[160:161]
	global_store_dwordx4 v[28:29], v[24:27], off
	s_nop 1
	v_pk_mul_f32 v[24:25], v[110:111], s[8:9] op_sel_hi:[1,0]
	v_pk_mul_f32 v[26:27], v[108:109], s[8:9] op_sel_hi:[1,0]
	v_pk_fma_f32 v[22:23], v[22:23], v[134:135], v[24:25]
	v_pk_fma_f32 v[20:21], v[20:21], v[132:133], v[26:27]
	v_pk_mul_f32 v[24:25], v[106:107], s[8:9] op_sel_hi:[1,0]
	v_pk_mul_f32 v[26:27], v[104:105], s[8:9] op_sel_hi:[1,0]
	v_pk_fma_f32 v[24:25], v[14:15], v[130:131], v[24:25]
	v_pk_fma_f32 v[14:15], v[12:13], v[128:129], v[26:27]
	v_cvt_pk_f16_f32 v12, v20, v21
	v_cvt_pk_f16_f32 v13, v22, v23
	v_cvt_pk_f16_f32 v14, v14, v15
	v_cvt_pk_f16_f32 v15, v24, v25
	global_store_dwordx4 v[28:29], v[12:15], off offset:256
	v_pk_mul_f32 v[20:21], v[116:117], s[8:9] op_sel_hi:[1,0]
	s_nop 0
	v_pk_mul_f32 v[14:15], v[118:119], s[8:9] op_sel_hi:[1,0]
	v_lshlrev_b64 v[12:13], 12, v[164:165]
	v_pk_fma_f32 v[14:15], v[18:19], v[142:143], v[14:15]
	v_pk_fma_f32 v[16:17], v[16:17], v[140:141], v[20:21]
	v_pk_mul_f32 v[18:19], v[114:115], s[8:9] op_sel_hi:[1,0]
	v_pk_mul_f32 v[20:21], v[112:113], s[8:9] op_sel_hi:[1,0]
	v_pk_fma_f32 v[18:19], v[10:11], v[138:139], v[18:19]
	v_pk_fma_f32 v[10:11], v[8:9], v[136:137], v[20:21]
	v_lshl_add_u64 v[12:13], s[0:1], 0, v[12:13]
	v_cvt_pk_f16_f32 v8, v16, v17
	v_cvt_pk_f16_f32 v9, v14, v15
	v_cvt_pk_f16_f32 v10, v10, v11
	v_cvt_pk_f16_f32 v11, v18, v19
	v_lshl_add_u64 v[12:13], v[12:13], 0, v[160:161]
	global_store_dwordx4 v[12:13], v[8:11], off
	s_nop 1
	v_pk_mul_f32 v[8:9], v[126:127], s[8:9] op_sel_hi:[1,0]
	v_pk_mul_f32 v[10:11], v[124:125], s[8:9] op_sel_hi:[1,0]
	v_pk_fma_f32 v[6:7], v[6:7], v[134:135], v[8:9]
	v_pk_fma_f32 v[4:5], v[4:5], v[132:133], v[10:11]
	v_pk_mul_f32 v[8:9], v[122:123], s[8:9] op_sel_hi:[1,0]
	v_pk_mul_f32 v[10:11], v[120:121], s[8:9] op_sel_hi:[1,0]
	v_pk_fma_f32 v[8:9], v[2:3], v[130:131], v[8:9]
	v_pk_fma_f32 v[2:3], v[0:1], v[128:129], v[10:11]
	v_cvt_pk_f16_f32 v0, v4, v5
	v_cvt_pk_f16_f32 v1, v6, v7
	v_cvt_pk_f16_f32 v2, v2, v3
	v_cvt_pk_f16_f32 v3, v8, v9
	global_store_dwordx4 v[12:13], v[0:3], off offset:256
	s_cbranch_vccz .LBB0_659
	s_waitcnt vmcnt(0)
	s_cmpk_gt_u32 s9, 0xff
	s_cbranch_scc1 .LBB0_670
	s_barrier

; #define PG8_STAGE(bufoff, gbase, voff) do { _Pragma("unroll") for (int _i = 0; _i < 2; ++_i) \
;         __builtin_amdgcn_global_load_lds((const unsigned*)((const char*)(gbase) + (voff)[_i]), (PG8_LAS unsigned*)(lds + (bufoff) + ldsw + _i * 8192), 16, 0, 0); } while (0)
; #define PG8_LDA(dst, b, h) do { _Pragma("unroll") for (int m = 0; m < 4; ++m) _Pragma("unroll") for (int k = 0; k < 2; ++k) dst[m][k] = *(const PG8_LAS bf16x8*)(lds + PG8_SA(b, h) + aoff + m * 2048 + k * 1024); } while (0)
; #define PG8_LDB(dst, b, h) do { _Pragma("unroll") for (int n = 0; n < 2; ++n) _Pragma("unroll") for (int k = 0; k < 2; ++k) dst[n][k] = *(const PG8_LAS bf16x8*)(lds + PG8_SB(b, h) + boff + n * 2048 + k * 1024); } while (0)
; #define PG8_MMA(ai, bj, At, Bt) do { __builtin_amdgcn_s_setprio(1); _Pragma("unroll") for (int m = 0; m < 4; ++m) _Pragma("unroll") for (int n = 0; n < 2; ++n) _Pragma("unroll") for (int k = 0; k < 2; ++k) \
;         acc[ai][bj][m][n] = __builtin_amdgcn_mfma_f32_16x16x32_bf16(Bt[n][k], At[m][k], acc[ai][bj][m][n], 0, 0, 0); __builtin_amdgcn_s_setprio(0); } while (0)
; #define PG8_WAIT_L(n) asm volatile("s_waitcnt lgkmcnt(" #n ")" ::: "memory")
; #define PG8_BAR __builtin_amdgcn_s_barrier()
; #define PG8_SCHED __builtin_amdgcn_sched_barrier(0)
;     __device__ __forceinline__ bool next(int i, pg8::Unit& u) const { if (i != 0) return false; u.pm = pm; u.pn = pn; return true; }
; template <class Epi, class Sched>
; __device__ __forceinline__ void gemm_phase(PG8_LAS unsigned char* lds, const Gemm g, const Sched& S, const Epi& E) {
;     ...
;         const bool has_next = S.next(ui + 1, nxt);
;         const char* nA = has_next ? (const char*)g.A + (size_t)nxt.pm * tstep : cA; const char* nB = has_next ? (const char*)g.Bt + (size_t)nxt.pn * tstep : cB;
;         for (int t = 0; t < nt; t += 2) {
;             const bool last = (t == nt - 2);
;             const char* a1 = cA + (size_t)(t + 1) * kstep;
;             const char* a2 = last ? nA : cA + (size_t)(t + 2) * kstep; const char* b2 = last ? nB : cB + (size_t)(t + 2) * kstep;
;             const char* a3 = a2 + kstep; const char* b3 = b2 + kstep;
;             if (last && has_next) S.a_ready(nxt);
;             PG8_LDB(B0, 0, 0); PG8_SCHED; PG8_LDA(At, 0, 0); PG8_STAGE(PG8_SA(1, 1), a1 + hstep, voffA);
;             PG8_WAIT_L(8); PG8_BAR; PG8_WAIT_L(0); PG8_MMA(0, 0, At, B0); PG8_BAR; PG8_SCHED;
.LBB0_802:
	s_ashr_i32 s9, s8, 31
	s_lshl_b64 s[10:11], s[8:9], 20
	v_cmp_lt_i64_e32 vcc, s[16:17], v[140:141]
	s_add_u32 s16, s35, s10
	s_addc_u32 s17, s36, s11
	s_and_b64 s[10:11], vcc, exec
	s_cselect_b32 s9, s17, s27
	s_cselect_b32 s66, s16, s26
	s_ashr_i32 s7, s6, 31
	s_lshl_b64 s[10:11], s[6:7], 20
	s_add_u32 s18, s37, s10
	s_addc_u32 s19, s38, s11
	s_and_b64 s[10:11], vcc, exec
	s_cselect_b32 s7, s19, s29
	s_cselect_b32 s67, s18, s28
	s_add_u32 s26, s26, 0x80080
	s_addc_u32 s27, s27, 0
	s_add_u32 s68, s28, 0x100
	s_addc_u32 s69, s29, 0
	s_mov_b32 s70, -2
	s_setprio 0
	ds_read_b128 v[150:153], v147
	ds_read_b128 v[154:157], v147 offset:1024
	ds_read_b128 v[158:161], v147 offset:2048
	ds_read_b128 v[162:165], v147 offset:3072
	ds_read_b128 v[166:169], v148
	ds_read_b128 v[170:173], v148 offset:1024
	ds_read_b128 v[174:177], v148 offset:2048
	ds_read_b128 v[178:181], v148 offset:3072
	ds_read_b128 v[182:185], v148 offset:4096
	ds_read_b128 v[186:189], v148 offset:5120
	ds_read_b128 v[190:193], v148 offset:6144
	ds_read_b128 v[194:197], v148 offset:7168
	s_waitcnt lgkmcnt(11)
	ds_read_b128 v[198:201], v149
	ds_read_b128 v[202:205], v149 offset:1024
	ds_read_b128 v[206:209], v149 offset:2048
	ds_read_b128 v[210:213], v149 offset:3072
	s_add_u32 s10, s26, 0xfff80080
	s_addc_u32 s11, s27, -1
	s_cmp_eq_u32 s70, 28
	s_cselect_b32 s31, s9, s11
	s_cselect_b32 s30, s66, s10
	s_cselect_b32 s29, s7, s69
	s_cselect_b32 s28, s67, s68
	v_lshl_add_u64 v[222:223], s[26:27], 0, v[136:137]
	s_add_i32 m0, s21, 0xc000
	s_nop 0
	global_load_lds_dwordx4 v[222:223], off
	v_lshl_add_u64 v[222:223], s[26:27], 0, v[138:139]
	s_add_i32 m0, s21, 0xe000
	s_nop 0
	global_load_lds_dwordx4 v[222:223], off
	s_waitcnt vmcnt(8)
	s_waitcnt lgkmcnt(0)
	s_setprio 1
	s_barrier
	v_mfma_f32_16x16x32_bf16 v[124:127], v[150:153], v[166:169], 0
	v_mfma_f32_16x16x32_bf16 v[120:123], v[158:161], v[166:169], 0
	v_mfma_f32_16x16x32_bf16 v[108:111], v[150:153], v[174:177], 0
	v_mfma_f32_16x16x32_bf16 v[104:107], v[158:161], v[174:177], 0
	v_mfma_f32_16x16x32_bf16 v[92:95], v[150:153], v[182:185], 0
	v_mfma_f32_16x16x32_bf16 v[88:91], v[158:161], v[182:185], 0
	v_mfma_f32_16x16x32_bf16 v[76:79], v[150:153], v[190:193], 0
	v_mfma_f32_16x16x32_bf16 v[72:75], v[158:161], v[190:193], 0
	v_mfma_f32_16x16x32_bf16 v[124:127], v[154:157], v[170:173], v[124:127]
	v_mfma_f32_16x16x32_bf16 v[120:123], v[162:165], v[170:173], v[120:123]
	v_mfma_f32_16x16x32_bf16 v[108:111], v[154:157], v[178:181], v[108:111]
	v_mfma_f32_16x16x32_bf16 v[104:107], v[162:165], v[178:181], v[104:107]
	v_mfma_f32_16x16x32_bf16 v[92:95], v[154:157], v[186:189], v[92:95]
	v_mfma_f32_16x16x32_bf16 v[88:91], v[162:165], v[186:189], v[88:91]
	v_mfma_f32_16x16x32_bf16 v[76:79], v[154:157], v[194:197], v[76:79]
	v_mfma_f32_16x16x32_bf16 v[72:75], v[162:165], v[194:197], v[72:75]
	v_mfma_f32_16x16x32_bf16 v[116:119], v[198:201], v[166:169], 0
	v_mfma_f32_16x16x32_bf16 v[112:115], v[206:209], v[166:169], 0
	v_mfma_f32_16x16x32_bf16 v[100:103], v[198:201], v[174:177], 0
	v_mfma_f32_16x16x32_bf16 v[96:99], v[206:209], v[174:177], 0
	v_mfma_f32_16x16x32_bf16 v[84:87], v[198:201], v[182:185], 0
	v_mfma_f32_16x16x32_bf16 v[80:83], v[206:209], v[182:185], 0
	v_mfma_f32_16x16x32_bf16 v[68:71], v[198:201], v[190:193], 0
	v_mfma_f32_16x16x32_bf16 v[64:67], v[206:209], v[190:193], 0
	v_mfma_f32_16x16x32_bf16 v[116:119], v[202:205], v[170:173], v[116:119]
	v_mfma_f32_16x16x32_bf16 v[112:115], v[210:213], v[170:173], v[112:115]
	v_mfma_f32_16x16x32_bf16 v[100:103], v[202:205], v[178:181], v[100:103]
	v_mfma_f32_16x16x32_bf16 v[96:99], v[210:213], v[178:181], v[96:99]
	v_mfma_f32_16x16x32_bf16 v[84:87], v[202:205], v[186:189], v[84:87]
	v_mfma_f32_16x16x32_bf16 v[80:83], v[210:213], v[186:189], v[80:83]
	v_mfma_f32_16x16x32_bf16 v[68:71], v[202:205], v[194:197], v[68:71]
	v_mfma_f32_16x16x32_bf16 v[64:67], v[210:213], v[194:197], v[64:67]
	s_barrier
	s_setprio 0
	ds_read_b128 v[166:169], v148 offset:16384
	ds_read_b128 v[170:173], v148 offset:17408
	ds_read_b128 v[174:177], v148 offset:18432
	ds_read_b128 v[178:181], v148 offset:19456
	ds_read_b128 v[182:185], v148 offset:20480
	ds_read_b128 v[186:189], v148 offset:21504
	ds_read_b128 v[190:193], v148 offset:22528
	ds_read_b128 v[194:197], v148 offset:23552
	s_add_i32 s10, s50, s39
	v_lshl_add_u64 v[214:215], s[28:29], 0, v[132:133]
	s_mov_b32 m0, s10
	s_nop 0
	global_load_lds_dwordx4 v[214:215], off
	v_lshl_add_u64 v[216:217], s[28:29], 0, v[128:129]
	s_add_i32 m0, s10, 0x2000
	s_nop 0
	global_load_lds_dwordx4 v[216:217], off
	s_mov_b32 m0, s21
	v_lshl_add_u64 v[218:219], s[30:31], 0, v[134:135]
	global_load_lds_dwordx4 v[218:219], off
	v_lshl_add_u64 v[220:221], s[30:31], 0, v[130:131]
	s_mov_b32 m0, s42
	s_nop 0
	global_load_lds_dwordx4 v[220:221], off
	s_add_u32 s10, s28, 0x80000
	s_addc_u32 s11, s29, 0
	s_add_i32 s33, s51, s39
	v_lshl_add_u64 v[222:223], s[10:11], 0, v[132:133]
	s_mov_b32 m0, s33
	s_nop 0
	global_load_lds_dwordx4 v[222:223], off
	v_lshl_add_u64 v[222:223], s[10:11], 0, v[128:129]
	s_add_i32 m0, s33, 0x2000
	s_nop 0
	global_load_lds_dwordx4 v[222:223], off
	s_waitcnt vmcnt(8)
	s_waitcnt lgkmcnt(0)
	s_setprio 1
	s_barrier
; #define PG8_STAGE(bufoff, gbase, voff) do { _Pragma("unroll") for (int _i = 0; _i < 2; ++_i) \
;         __builtin_amdgcn_global_load_lds((const unsigned*)((const char*)(gbase) + (voff)[_i]), (PG8_LAS unsigned*)(lds + (bufoff) + ldsw + _i * 8192), 16, 0, 0); } while (0)
; #define PG8_LDA(dst, b, h) do { _Pragma("unroll") for (int m = 0; m < 4; ++m) _Pragma("unroll") for (int k = 0; k < 2; ++k) dst[m][k] = *(const PG8_LAS bf16x8*)(lds + PG8_SA(b, h) + aoff + m * 2048 + k * 1024); } while (0)
; #define PG8_LDB(dst, b, h) do { _Pragma("unroll") for (int n = 0; n < 2; ++n) _Pragma("unroll") for (int k = 0; k < 2; ++k) dst[n][k] = *(const PG8_LAS bf16x8*)(lds + PG8_SB(b, h) + boff + n * 2048 + k * 1024); } while (0)
; #define PG8_MMA(ai, bj, At, Bt) do { __builtin_amdgcn_s_setprio(1); _Pragma("unroll") for (int m = 0; m < 4; ++m) _Pragma("unroll") for (int n = 0; n < 2; ++n) _Pragma("unroll") for (int k = 0; k < 2; ++k) \
;         acc[ai][bj][m][n] = __builtin_amdgcn_mfma_f32_16x16x32_bf16(Bt[n][k], At[m][k], acc[ai][bj][m][n], 0, 0, 0); __builtin_amdgcn_s_setprio(0); } while (0)
; #define PG8_WAIT_V(n) asm volatile("s_waitcnt vmcnt(" #n ")" ::: "memory")
; #define PG8_WAIT_L(n) asm volatile("s_waitcnt lgkmcnt(" #n ")" ::: "memory")
; template <class Epi, class Sched>
; __device__ __forceinline__ void gemm_phase(PG8_LAS unsigned char* lds, const Gemm g, const Sched& S, const Epi& E) {
;     ...
;             PG8_LDB(B0, 0, 0); PG8_SCHED; PG8_LDA(At, 0, 0); PG8_STAGE(PG8_SA(1, 1), a1 + hstep, voffA);
;             PG8_WAIT_L(8); PG8_BAR; PG8_WAIT_L(0); PG8_MMA(0, 0, At, B0); PG8_BAR; PG8_SCHED;
;             PG8_LDB(B1, 0, 1); PG8_STAGE(PG8_SB(0, 0), b2, voffB);
;             PG8_BAR; PG8_WAIT_L(0); PG8_MMA(0, 1, At, B1); PG8_BAR;
;             PG8_LDA(At, 0, 1); PG8_STAGE(PG8_SA(0, 0), a2, voffA);
;             PG8_BAR; PG8_WAIT_L(0); PG8_MMA(1, 0, At, B0); PG8_BAR; PG8_SCHED;
;             PG8_STAGE(PG8_SB(0, 1), b2 + hstep, voffB);
;             PG8_WAIT_V(6); PG8_BAR; PG8_MMA(1, 1, At, B1); PG8_BAR;
;             PG8_LDB(B0, 1, 0); PG8_SCHED; PG8_LDA(At, 1, 0); PG8_STAGE(PG8_SA(0, 1), a2 + hstep, voffA);
;             PG8_WAIT_L(8); PG8_BAR; PG8_WAIT_L(0); PG8_MMA(0, 0, At, B0); PG8_BAR; PG8_SCHED;
;             PG8_LDB(B1, 1, 1); PG8_STAGE(PG8_SB(1, 0), b3, voffB);
;             PG8_BAR; PG8_WAIT_L(0); PG8_MMA(0, 1, At, B1); PG8_BAR;
	v_mfma_f32_16x16x32_bf16 v[60:63], v[150:153], v[166:169], 0
	v_mfma_f32_16x16x32_bf16 v[56:59], v[158:161], v[166:169], 0
	v_mfma_f32_16x16x32_bf16 v[44:47], v[150:153], v[174:177], 0
	v_mfma_f32_16x16x32_bf16 v[40:43], v[158:161], v[174:177], 0
	v_mfma_f32_16x16x32_bf16 v[28:31], v[150:153], v[182:185], 0
	v_mfma_f32_16x16x32_bf16 v[24:27], v[158:161], v[182:185], 0
	v_mfma_f32_16x16x32_bf16 v[12:15], v[150:153], v[190:193], 0
	v_mfma_f32_16x16x32_bf16 v[8:11], v[158:161], v[190:193], 0
	s_add_i32 s33, 0, 0x18000
	v_mfma_f32_16x16x32_bf16 v[60:63], v[154:157], v[170:173], v[60:63]
	v_mfma_f32_16x16x32_bf16 v[56:59], v[162:165], v[170:173], v[56:59]
	v_mfma_f32_16x16x32_bf16 v[44:47], v[154:157], v[178:181], v[44:47]
	v_mfma_f32_16x16x32_bf16 v[40:43], v[162:165], v[178:181], v[40:43]
	v_mfma_f32_16x16x32_bf16 v[28:31], v[154:157], v[186:189], v[28:31]
	v_mfma_f32_16x16x32_bf16 v[24:27], v[162:165], v[186:189], v[24:27]
	v_mfma_f32_16x16x32_bf16 v[12:15], v[154:157], v[194:197], v[12:15]
	v_mfma_f32_16x16x32_bf16 v[8:11], v[162:165], v[194:197], v[8:11]
	v_mfma_f32_16x16x32_bf16 v[52:55], v[198:201], v[166:169], 0
	v_mfma_f32_16x16x32_bf16 v[48:51], v[206:209], v[166:169], 0
	v_mfma_f32_16x16x32_bf16 v[36:39], v[198:201], v[174:177], 0
	v_mfma_f32_16x16x32_bf16 v[32:35], v[206:209], v[174:177], 0
	v_mfma_f32_16x16x32_bf16 v[20:23], v[198:201], v[182:185], 0
	v_mfma_f32_16x16x32_bf16 v[16:19], v[206:209], v[182:185], 0
	v_mfma_f32_16x16x32_bf16 v[4:7], v[198:201], v[190:193], 0
	v_mfma_f32_16x16x32_bf16 v[0:3], v[206:209], v[190:193], 0
	v_mfma_f32_16x16x32_bf16 v[52:55], v[202:205], v[170:173], v[52:55]
	v_mfma_f32_16x16x32_bf16 v[48:51], v[210:213], v[170:173], v[48:51]
	v_mfma_f32_16x16x32_bf16 v[36:39], v[202:205], v[178:181], v[36:39]
	v_mfma_f32_16x16x32_bf16 v[32:35], v[210:213], v[178:181], v[32:35]
	v_mfma_f32_16x16x32_bf16 v[20:23], v[202:205], v[186:189], v[20:23]
	v_mfma_f32_16x16x32_bf16 v[16:19], v[210:213], v[186:189], v[16:19]
	v_mfma_f32_16x16x32_bf16 v[4:7], v[202:205], v[194:197], v[4:7]
	v_mfma_f32_16x16x32_bf16 v[0:3], v[210:213], v[194:197], v[0:3]
	s_barrier
	s_setprio 0
	ds_read_b128 v[150:153], v147 offset:32768
	ds_read_b128 v[154:157], v147 offset:33792
	ds_read_b128 v[158:161], v147 offset:34816
	ds_read_b128 v[162:165], v147 offset:35840
	ds_read_b128 v[166:169], v148 offset:32768
	ds_read_b128 v[170:173], v148 offset:33792
	ds_read_b128 v[174:177], v148 offset:34816
	ds_read_b128 v[178:181], v148 offset:35840
	ds_read_b128 v[182:185], v148 offset:36864
	ds_read_b128 v[186:189], v148 offset:37888
	ds_read_b128 v[190:193], v148 offset:38912
	ds_read_b128 v[194:197], v148 offset:39936
	s_waitcnt lgkmcnt(11)
	ds_read_b128 v[198:201], v149 offset:32768
	ds_read_b128 v[202:205], v149 offset:33792
	ds_read_b128 v[206:209], v149 offset:34816
	ds_read_b128 v[210:213], v149 offset:35840
	s_add_u32 s10, s30, 0x80000
	s_addc_u32 s11, s31, 0
	s_mov_b32 m0, s43
	v_lshl_add_u64 v[222:223], s[10:11], 0, v[134:135]
	global_load_lds_dwordx4 v[222:223], off
	v_lshl_add_u64 v[222:223], s[10:11], 0, v[130:131]
	s_mov_b32 m0, s44
	s_nop 0
	global_load_lds_dwordx4 v[222:223], off
	s_waitcnt vmcnt(8)
	s_waitcnt lgkmcnt(0)
	s_setprio 1
	s_barrier
	v_mfma_f32_16x16x32_bf16 v[124:127], v[150:153], v[166:169], v[124:127]
	v_mfma_f32_16x16x32_bf16 v[120:123], v[158:161], v[166:169], v[120:123]
	v_mfma_f32_16x16x32_bf16 v[108:111], v[150:153], v[174:177], v[108:111]
	v_mfma_f32_16x16x32_bf16 v[104:107], v[158:161], v[174:177], v[104:107]
	v_mfma_f32_16x16x32_bf16 v[92:95], v[150:153], v[182:185], v[92:95]
	v_mfma_f32_16x16x32_bf16 v[88:91], v[158:161], v[182:185], v[88:91]
	v_mfma_f32_16x16x32_bf16 v[76:79], v[150:153], v[190:193], v[76:79]
	v_mfma_f32_16x16x32_bf16 v[72:75], v[158:161], v[190:193], v[72:75]
	v_mfma_f32_16x16x32_bf16 v[124:127], v[154:157], v[170:173], v[124:127]
	v_mfma_f32_16x16x32_bf16 v[120:123], v[162:165], v[170:173], v[120:123]
	v_mfma_f32_16x16x32_bf16 v[108:111], v[154:157], v[178:181], v[108:111]
	v_mfma_f32_16x16x32_bf16 v[104:107], v[162:165], v[178:181], v[104:107]
	v_mfma_f32_16x16x32_bf16 v[92:95], v[154:157], v[186:189], v[92:95]
	v_mfma_f32_16x16x32_bf16 v[88:91], v[162:165], v[186:189], v[88:91]
	v_mfma_f32_16x16x32_bf16 v[76:79], v[154:157], v[194:197], v[76:79]
	v_mfma_f32_16x16x32_bf16 v[72:75], v[162:165], v[194:197], v[72:75]
	v_mfma_f32_16x16x32_bf16 v[116:119], v[198:201], v[166:169], v[116:119]
	v_mfma_f32_16x16x32_bf16 v[112:115], v[206:209], v[166:169], v[112:115]
	v_mfma_f32_16x16x32_bf16 v[100:103], v[198:201], v[174:177], v[100:103]
	v_mfma_f32_16x16x32_bf16 v[96:99], v[206:209], v[174:177], v[96:99]
	v_mfma_f32_16x16x32_bf16 v[84:87], v[198:201], v[182:185], v[84:87]
	v_mfma_f32_16x16x32_bf16 v[80:83], v[206:209], v[182:185], v[80:83]
	v_mfma_f32_16x16x32_bf16 v[68:71], v[198:201], v[190:193], v[68:71]
	v_mfma_f32_16x16x32_bf16 v[64:67], v[206:209], v[190:193], v[64:67]
	v_mfma_f32_16x16x32_bf16 v[116:119], v[202:205], v[170:173], v[116:119]
	v_mfma_f32_16x16x32_bf16 v[112:115], v[210:213], v[170:173], v[112:115]
	v_mfma_f32_16x16x32_bf16 v[100:103], v[202:205], v[178:181], v[100:103]
	v_mfma_f32_16x16x32_bf16 v[96:99], v[210:213], v[178:181], v[96:99]
	v_mfma_f32_16x16x32_bf16 v[84:87], v[202:205], v[186:189], v[84:87]
	v_mfma_f32_16x16x32_bf16 v[80:83], v[210:213], v[186:189], v[80:83]
	v_mfma_f32_16x16x32_bf16 v[68:71], v[202:205], v[194:197], v[68:71]
	v_mfma_f32_16x16x32_bf16 v[64:67], v[210:213], v[194:197], v[64:67]
	s_barrier
; #define PG8_STAGE(bufoff, gbase, voff) do { _Pragma("unroll") for (int _i = 0; _i < 2; ++_i) \
;         __builtin_amdgcn_global_load_lds((const unsigned*)((const char*)(gbase) + (voff)[_i]), (PG8_LAS unsigned*)(lds + (bufoff) + ldsw + _i * 8192), 16, 0, 0); } while (0)
; #define PG8_LDA(dst, b, h) do { _Pragma("unroll") for (int m = 0; m < 4; ++m) _Pragma("unroll") for (int k = 0; k < 2; ++k) dst[m][k] = *(const PG8_LAS bf16x8*)(lds + PG8_SA(b, h) + aoff + m * 2048 + k * 1024); } while (0)
; #define PG8_WAIT_V(n) asm volatile("s_waitcnt vmcnt(" #n ")" ::: "memory")
; template <class Epi, class Sched>
; __device__ __forceinline__ void gemm_phase(PG8_LAS unsigned char* lds, const Gemm g, const Sched& S, const Epi& E) {
;     ...
;         for (int t = 0; t < nt; t += 2) {
;             const bool last = (t == nt - 2);
;             const char* a1 = cA + (size_t)(t + 1) * kstep;
;             const char* a2 = last ? nA : cA + (size_t)(t + 2) * kstep; const char* b2 = last ? nB : cB + (size_t)(t + 2) * kstep;
;             const char* a3 = a2 + kstep; const char* b3 = b2 + kstep;
;             if (last && has_next) S.a_ready(nxt);
;             PG8_LDB(B0, 0, 0); PG8_SCHED; PG8_LDA(At, 0, 0); PG8_STAGE(PG8_SA(1, 1), a1 + hstep, voffA);
;             PG8_WAIT_L(8); PG8_BAR; PG8_WAIT_L(0); PG8_MMA(0, 0, At, B0); PG8_BAR; PG8_SCHED;
;             PG8_LDB(B1, 0, 1); PG8_STAGE(PG8_SB(0, 0), b2, voffB);
;             PG8_BAR; PG8_WAIT_L(0); PG8_MMA(0, 1, At, B1); PG8_BAR;
;             PG8_LDA(At, 0, 1); PG8_STAGE(PG8_SA(0, 0), a2, voffA);
;             PG8_BAR; PG8_WAIT_L(0); PG8_MMA(1, 0, At, B0); PG8_BAR; PG8_SCHED;
;             PG8_STAGE(PG8_SB(0, 1), b2 + hstep, voffB);
;             PG8_WAIT_V(6); PG8_BAR; PG8_MMA(1, 1, At, B1); PG8_BAR;
;             PG8_LDB(B0, 1, 0); PG8_SCHED; PG8_LDA(At, 1, 0); PG8_STAGE(PG8_SA(0, 1), a2 + hstep, voffA);
;             PG8_WAIT_L(8); PG8_BAR; PG8_WAIT_L(0); PG8_MMA(0, 0, At, B0); PG8_BAR; PG8_SCHED;
;             PG8_LDB(B1, 1, 1); PG8_STAGE(PG8_SB(1, 0), b3, voffB);
;             PG8_BAR; PG8_WAIT_L(0); PG8_MMA(0, 1, At, B1); PG8_BAR;
;             PG8_LDA(At, 1, 1); PG8_STAGE(PG8_SA(1, 0), a3, voffA);
;             PG8_BAR; PG8_WAIT_L(0); PG8_MMA(1, 0, At, B0); PG8_BAR; PG8_SCHED;
;             PG8_STAGE(PG8_SB(1, 1), b3 + hstep, voffB);
;             PG8_WAIT_V(6); PG8_BAR; PG8_MMA(1, 1, At, B1); PG8_BAR;
	s_setprio 0
	ds_read_b128 v[166:169], v148 offset:49152
	ds_read_b128 v[170:173], v148 offset:50176
	ds_read_b128 v[174:177], v148 offset:51200
	ds_read_b128 v[178:181], v148 offset:52224
	ds_read_b128 v[182:185], v148 offset:53248
	ds_read_b128 v[186:189], v148 offset:54272
	ds_read_b128 v[190:193], v148 offset:55296
	ds_read_b128 v[194:197], v148 offset:56320
	s_add_i32 s30, 0, 0x1c000
	s_add_i32 s10, s33, s39
	v_lshl_add_u64 v[214:215], v[214:215], 0, s[4:5]
	s_mov_b32 m0, s10
	s_nop 0
	global_load_lds_dwordx4 v[214:215], off
	v_lshl_add_u64 v[214:215], v[216:217], 0, s[4:5]
	s_add_i32 m0, s10, 0x2000
	s_nop 0
	global_load_lds_dwordx4 v[214:215], off
	s_mov_b32 m0, s46
	v_lshl_add_u64 v[214:215], v[218:219], 0, s[4:5]
	global_load_lds_dwordx4 v[214:215], off
	v_lshl_add_u64 v[214:215], v[220:221], 0, s[4:5]
	s_mov_b32 m0, s47
	s_nop 0
	global_load_lds_dwordx4 v[214:215], off
	s_add_u32 s10, s28, 0x80080
	s_addc_u32 s11, s29, 0
	s_add_i32 s28, s30, s39
	v_lshl_add_u64 v[222:223], s[10:11], 0, v[132:133]
	s_mov_b32 m0, s28
	s_nop 0
	global_load_lds_dwordx4 v[222:223], off
	v_lshl_add_u64 v[222:223], s[10:11], 0, v[128:129]
	s_add_i32 m0, s28, 0x2000
	s_nop 0
	global_load_lds_dwordx4 v[222:223], off
	s_waitcnt vmcnt(8)
	s_waitcnt lgkmcnt(0)
	s_setprio 1
	s_barrier
	v_mfma_f32_16x16x32_bf16 v[60:63], v[150:153], v[166:169], v[60:63]
	v_mfma_f32_16x16x32_bf16 v[56:59], v[158:161], v[166:169], v[56:59]
	v_mfma_f32_16x16x32_bf16 v[44:47], v[150:153], v[174:177], v[44:47]
	v_mfma_f32_16x16x32_bf16 v[40:43], v[158:161], v[174:177], v[40:43]
	v_mfma_f32_16x16x32_bf16 v[28:31], v[150:153], v[182:185], v[28:31]
	v_mfma_f32_16x16x32_bf16 v[24:27], v[158:161], v[182:185], v[24:27]
	v_mfma_f32_16x16x32_bf16 v[12:15], v[150:153], v[190:193], v[12:15]
	v_mfma_f32_16x16x32_bf16 v[8:11], v[158:161], v[190:193], v[8:11]
	s_add_i32 s70, s70, 2
	s_add_u32 s26, s26, 0x100
	s_addc_u32 s27, s27, 0
	s_add_u32 s68, s68, 0x100
	s_addc_u32 s69, s69, 0
	s_cmp_gt_u32 s70, 29
	v_mfma_f32_16x16x32_bf16 v[60:63], v[154:157], v[170:173], v[60:63]
	v_mfma_f32_16x16x32_bf16 v[56:59], v[162:165], v[170:173], v[56:59]
	v_mfma_f32_16x16x32_bf16 v[44:47], v[154:157], v[178:181], v[44:47]
	v_mfma_f32_16x16x32_bf16 v[40:43], v[162:165], v[178:181], v[40:43]
	v_mfma_f32_16x16x32_bf16 v[28:31], v[154:157], v[186:189], v[28:31]
	v_mfma_f32_16x16x32_bf16 v[24:27], v[162:165], v[186:189], v[24:27]
	v_mfma_f32_16x16x32_bf16 v[12:15], v[154:157], v[194:197], v[12:15]
	v_mfma_f32_16x16x32_bf16 v[8:11], v[162:165], v[194:197], v[8:11]
	v_mfma_f32_16x16x32_bf16 v[52:55], v[198:201], v[166:169], v[52:55]
	v_mfma_f32_16x16x32_bf16 v[48:51], v[206:209], v[166:169], v[48:51]
	v_mfma_f32_16x16x32_bf16 v[36:39], v[198:201], v[174:177], v[36:39]
	v_mfma_f32_16x16x32_bf16 v[32:35], v[206:209], v[174:177], v[32:35]
	v_mfma_f32_16x16x32_bf16 v[20:23], v[198:201], v[182:185], v[20:23]
	v_mfma_f32_16x16x32_bf16 v[16:19], v[206:209], v[182:185], v[16:19]
	v_mfma_f32_16x16x32_bf16 v[4:7], v[198:201], v[190:193], v[4:7]
	v_mfma_f32_16x16x32_bf16 v[0:3], v[206:209], v[190:193], v[0:3]
	v_mfma_f32_16x16x32_bf16 v[52:55], v[202:205], v[170:173], v[52:55]
	v_mfma_f32_16x16x32_bf16 v[48:51], v[210:213], v[170:173], v[48:51]
	v_mfma_f32_16x16x32_bf16 v[36:39], v[202:205], v[178:181], v[36:39]
	v_mfma_f32_16x16x32_bf16 v[32:35], v[210:213], v[178:181], v[32:35]
	v_mfma_f32_16x16x32_bf16 v[20:23], v[202:205], v[186:189], v[20:23]
	v_mfma_f32_16x16x32_bf16 v[16:19], v[210:213], v[186:189], v[16:19]
	v_mfma_f32_16x16x32_bf16 v[4:7], v[202:205], v[194:197], v[4:7]
	v_mfma_f32_16x16x32_bf16 v[0:3], v[210:213], v[194:197], v[0:3]
	s_barrier
.LBB0_803:
	s_setprio 0
	ds_read_b128 v[150:153], v147
	ds_read_b128 v[154:157], v147 offset:1024
	ds_read_b128 v[158:161], v147 offset:2048
	ds_read_b128 v[162:165], v147 offset:3072
	ds_read_b128 v[166:169], v148
	ds_read_b128 v[170:173], v148 offset:1024
	ds_read_b128 v[174:177], v148 offset:2048
	ds_read_b128 v[178:181], v148 offset:3072
	ds_read_b128 v[182:185], v148 offset:4096
	ds_read_b128 v[186:189], v148 offset:5120
	ds_read_b128 v[190:193], v148 offset:6144
	ds_read_b128 v[194:197], v148 offset:7168
	s_waitcnt lgkmcnt(11)
	ds_read_b128 v[198:201], v149
	ds_read_b128 v[202:205], v149 offset:1024
	ds_read_b128 v[206:209], v149 offset:2048
	ds_read_b128 v[210:213], v149 offset:3072
	s_add_u32 s10, s26, 0xfff80080
	s_addc_u32 s11, s27, -1
	s_cmp_eq_u32 s70, 28
	s_cselect_b32 s31, s9, s11
	s_cselect_b32 s30, s66, s10
	s_cselect_b32 s29, s7, s69
	s_cselect_b32 s28, s67, s68
	v_lshl_add_u64 v[222:223], s[26:27], 0, v[136:137]
	s_add_i32 m0, s21, 0xc000
	s_nop 0
	global_load_lds_dwordx4 v[222:223], off
	v_lshl_add_u64 v[222:223], s[26:27], 0, v[138:139]
	s_add_i32 m0, s21, 0xe000
	s_nop 0
	global_load_lds_dwordx4 v[222:223], off
	s_waitcnt vmcnt(8)
	s_waitcnt lgkmcnt(0)
	s_setprio 1
	s_barrier
; #define PG8_STAGE(bufoff, gbase, voff) do { _Pragma("unroll") for (int _i = 0; _i < 2; ++_i) \
;         __builtin_amdgcn_global_load_lds((const unsigned*)((const char*)(gbase) + (voff)[_i]), (PG8_LAS unsigned*)(lds + (bufoff) + ldsw + _i * 8192), 16, 0, 0); } while (0)
; #define PG8_LDA(dst, b, h) do { _Pragma("unroll") for (int m = 0; m < 4; ++m) _Pragma("unroll") for (int k = 0; k < 2; ++k) dst[m][k] = *(const PG8_LAS bf16x8*)(lds + PG8_SA(b, h) + aoff + m * 2048 + k * 1024); } while (0)
; #define PG8_LDB(dst, b, h) do { _Pragma("unroll") for (int n = 0; n < 2; ++n) _Pragma("unroll") for (int k = 0; k < 2; ++k) dst[n][k] = *(const PG8_LAS bf16x8*)(lds + PG8_SB(b, h) + boff + n * 2048 + k * 1024); } while (0)
; #define PG8_WAIT_V(n) asm volatile("s_waitcnt vmcnt(" #n ")" ::: "memory")
; #define PG8_WAIT_L(n) asm volatile("s_waitcnt lgkmcnt(" #n ")" ::: "memory")
; #define PG8_BAR __builtin_amdgcn_s_barrier()
; #define PG8_SCHED __builtin_amdgcn_sched_barrier(0)
; template <class Epi, class Sched>
; __device__ __forceinline__ void gemm_phase(PG8_LAS unsigned char* lds, const Gemm g, const Sched& S, const Epi& E) {
;     ...
;             PG8_LDB(B0, 0, 0); PG8_SCHED; PG8_LDA(At, 0, 0); PG8_STAGE(PG8_SA(1, 1), a1 + hstep, voffA);
;             PG8_WAIT_L(8); PG8_BAR; PG8_WAIT_L(0); PG8_MMA(0, 0, At, B0); PG8_BAR; PG8_SCHED;
;             PG8_LDB(B1, 0, 1); PG8_STAGE(PG8_SB(0, 0), b2, voffB);
;             PG8_BAR; PG8_WAIT_L(0); PG8_MMA(0, 1, At, B1); PG8_BAR;
;             PG8_LDA(At, 0, 1); PG8_STAGE(PG8_SA(0, 0), a2, voffA);
;             PG8_BAR; PG8_WAIT_L(0); PG8_MMA(1, 0, At, B0); PG8_BAR; PG8_SCHED;
;             PG8_STAGE(PG8_SB(0, 1), b2 + hstep, voffB);
;             PG8_WAIT_V(6); PG8_BAR; PG8_MMA(1, 1, At, B1); PG8_BAR;
;             PG8_LDB(B0, 1, 0); PG8_SCHED; PG8_LDA(At, 1, 0); PG8_STAGE(PG8_SA(0, 1), a2 + hstep, voffA);
;             PG8_WAIT_L(8); PG8_BAR; PG8_WAIT_L(0); PG8_MMA(0, 0, At, B0); PG8_BAR; PG8_SCHED;
;             PG8_LDB(B1, 1, 1); PG8_STAGE(PG8_SB(1, 0), b3, voffB);
;             PG8_BAR; PG8_WAIT_L(0); PG8_MMA(0, 1, At, B1); PG8_BAR;
;             PG8_LDA(At, 1, 1); PG8_STAGE(PG8_SA(1, 0), a3, voffA);
;             PG8_BAR; PG8_WAIT_L(0); PG8_MMA(1, 0, At, B0); PG8_BAR; PG8_SCHED;
;             PG8_STAGE(PG8_SB(1, 1), b3 + hstep, voffB);
;             PG8_WAIT_V(6); PG8_BAR; PG8_MMA(1, 1, At, B1); PG8_BAR;
	v_mfma_f32_16x16x32_bf16 v[124:127], v[150:153], v[166:169], v[124:127]
	v_mfma_f32_16x16x32_bf16 v[120:123], v[158:161], v[166:169], v[120:123]
	v_mfma_f32_16x16x32_bf16 v[108:111], v[150:153], v[174:177], v[108:111]
	v_mfma_f32_16x16x32_bf16 v[104:107], v[158:161], v[174:177], v[104:107]
	v_mfma_f32_16x16x32_bf16 v[92:95], v[150:153], v[182:185], v[92:95]
	v_mfma_f32_16x16x32_bf16 v[88:91], v[158:161], v[182:185], v[88:91]
	v_mfma_f32_16x16x32_bf16 v[76:79], v[150:153], v[190:193], v[76:79]
	v_mfma_f32_16x16x32_bf16 v[72:75], v[158:161], v[190:193], v[72:75]
	v_mfma_f32_16x16x32_bf16 v[124:127], v[154:157], v[170:173], v[124:127]
	v_mfma_f32_16x16x32_bf16 v[120:123], v[162:165], v[170:173], v[120:123]
	v_mfma_f32_16x16x32_bf16 v[108:111], v[154:157], v[178:181], v[108:111]
	v_mfma_f32_16x16x32_bf16 v[104:107], v[162:165], v[178:181], v[104:107]
	v_mfma_f32_16x16x32_bf16 v[92:95], v[154:157], v[186:189], v[92:95]
	v_mfma_f32_16x16x32_bf16 v[88:91], v[162:165], v[186:189], v[88:91]
	v_mfma_f32_16x16x32_bf16 v[76:79], v[154:157], v[194:197], v[76:79]
	v_mfma_f32_16x16x32_bf16 v[72:75], v[162:165], v[194:197], v[72:75]
	v_mfma_f32_16x16x32_bf16 v[116:119], v[198:201], v[166:169], v[116:119]
	v_mfma_f32_16x16x32_bf16 v[112:115], v[206:209], v[166:169], v[112:115]
	v_mfma_f32_16x16x32_bf16 v[100:103], v[198:201], v[174:177], v[100:103]
	v_mfma_f32_16x16x32_bf16 v[96:99], v[206:209], v[174:177], v[96:99]
	v_mfma_f32_16x16x32_bf16 v[84:87], v[198:201], v[182:185], v[84:87]
	v_mfma_f32_16x16x32_bf16 v[80:83], v[206:209], v[182:185], v[80:83]
	v_mfma_f32_16x16x32_bf16 v[68:71], v[198:201], v[190:193], v[68:71]
	v_mfma_f32_16x16x32_bf16 v[64:67], v[206:209], v[190:193], v[64:67]
	v_mfma_f32_16x16x32_bf16 v[116:119], v[202:205], v[170:173], v[116:119]
	v_mfma_f32_16x16x32_bf16 v[112:115], v[210:213], v[170:173], v[112:115]
	v_mfma_f32_16x16x32_bf16 v[100:103], v[202:205], v[178:181], v[100:103]
	v_mfma_f32_16x16x32_bf16 v[96:99], v[210:213], v[178:181], v[96:99]
	v_mfma_f32_16x16x32_bf16 v[84:87], v[202:205], v[186:189], v[84:87]
	v_mfma_f32_16x16x32_bf16 v[80:83], v[210:213], v[186:189], v[80:83]
	v_mfma_f32_16x16x32_bf16 v[68:71], v[202:205], v[194:197], v[68:71]
	v_mfma_f32_16x16x32_bf16 v[64:67], v[210:213], v[194:197], v[64:67]
	s_barrier
	s_setprio 0
	ds_read_b128 v[166:169], v148 offset:16384
	ds_read_b128 v[170:173], v148 offset:17408
	ds_read_b128 v[174:177], v148 offset:18432
	ds_read_b128 v[178:181], v148 offset:19456
	ds_read_b128 v[182:185], v148 offset:20480
	ds_read_b128 v[186:189], v148 offset:21504
	ds_read_b128 v[190:193], v148 offset:22528
	ds_read_b128 v[194:197], v148 offset:23552
	s_add_i32 s10, s50, s39
	v_lshl_add_u64 v[214:215], s[28:29], 0, v[132:133]
	s_mov_b32 m0, s10
	s_nop 0
	global_load_lds_dwordx4 v[214:215], off
	v_lshl_add_u64 v[216:217], s[28:29], 0, v[128:129]
	s_add_i32 m0, s10, 0x2000
	s_nop 0
	global_load_lds_dwordx4 v[216:217], off
	s_mov_b32 m0, s21
	v_lshl_add_u64 v[218:219], s[30:31], 0, v[134:135]
	global_load_lds_dwordx4 v[218:219], off
	v_lshl_add_u64 v[220:221], s[30:31], 0, v[130:131]
	s_mov_b32 m0, s42
	s_nop 0
	global_load_lds_dwordx4 v[220:221], off
	s_add_u32 s10, s28, 0x80000
	s_addc_u32 s11, s29, 0
	s_add_i32 s33, s51, s39
	v_lshl_add_u64 v[222:223], s[10:11], 0, v[132:133]
	s_mov_b32 m0, s33
	s_nop 0
	global_load_lds_dwordx4 v[222:223], off
	v_lshl_add_u64 v[222:223], s[10:11], 0, v[128:129]
	s_add_i32 m0, s33, 0x2000
	s_nop 0
	global_load_lds_dwordx4 v[222:223], off
	s_waitcnt vmcnt(8)
	s_waitcnt lgkmcnt(0)
	s_setprio 1
	s_barrier
	v_mfma_f32_16x16x32_bf16 v[60:63], v[150:153], v[166:169], v[60:63]
	v_mfma_f32_16x16x32_bf16 v[56:59], v[158:161], v[166:169], v[56:59]
	v_mfma_f32_16x16x32_bf16 v[44:47], v[150:153], v[174:177], v[44:47]
	v_mfma_f32_16x16x32_bf16 v[40:43], v[158:161], v[174:177], v[40:43]
	v_mfma_f32_16x16x32_bf16 v[28:31], v[150:153], v[182:185], v[28:31]
	v_mfma_f32_16x16x32_bf16 v[24:27], v[158:161], v[182:185], v[24:27]
	v_mfma_f32_16x16x32_bf16 v[12:15], v[150:153], v[190:193], v[12:15]
	v_mfma_f32_16x16x32_bf16 v[8:11], v[158:161], v[190:193], v[8:11]
	s_add_i32 s33, 0, 0x18000
	v_mfma_f32_16x16x32_bf16 v[60:63], v[154:157], v[170:173], v[60:63]
	v_mfma_f32_16x16x32_bf16 v[56:59], v[162:165], v[170:173], v[56:59]
	v_mfma_f32_16x16x32_bf16 v[44:47], v[154:157], v[178:181], v[44:47]
	v_mfma_f32_16x16x32_bf16 v[40:43], v[162:165], v[178:181], v[40:43]
	v_mfma_f32_16x16x32_bf16 v[28:31], v[154:157], v[186:189], v[28:31]
	v_mfma_f32_16x16x32_bf16 v[24:27], v[162:165], v[186:189], v[24:27]
	v_mfma_f32_16x16x32_bf16 v[12:15], v[154:157], v[194:197], v[12:15]
	v_mfma_f32_16x16x32_bf16 v[8:11], v[162:165], v[194:197], v[8:11]
	v_mfma_f32_16x16x32_bf16 v[52:55], v[198:201], v[166:169], v[52:55]
	v_mfma_f32_16x16x32_bf16 v[48:51], v[206:209], v[166:169], v[48:51]
	v_mfma_f32_16x16x32_bf16 v[36:39], v[198:201], v[174:177], v[36:39]
	v_mfma_f32_16x16x32_bf16 v[32:35], v[206:209], v[174:177], v[32:35]
	v_mfma_f32_16x16x32_bf16 v[20:23], v[198:201], v[182:185], v[20:23]
	v_mfma_f32_16x16x32_bf16 v[16:19], v[206:209], v[182:185], v[16:19]
	v_mfma_f32_16x16x32_bf16 v[4:7], v[198:201], v[190:193], v[4:7]
	v_mfma_f32_16x16x32_bf16 v[0:3], v[206:209], v[190:193], v[0:3]
	v_mfma_f32_16x16x32_bf16 v[52:55], v[202:205], v[170:173], v[52:55]
	v_mfma_f32_16x16x32_bf16 v[48:51], v[210:213], v[170:173], v[48:51]
	v_mfma_f32_16x16x32_bf16 v[36:39], v[202:205], v[178:181], v[36:39]
	v_mfma_f32_16x16x32_bf16 v[32:35], v[210:213], v[178:181], v[32:35]
	v_mfma_f32_16x16x32_bf16 v[20:23], v[202:205], v[186:189], v[20:23]
	v_mfma_f32_16x16x32_bf16 v[16:19], v[210:213], v[186:189], v[16:19]
	v_mfma_f32_16x16x32_bf16 v[4:7], v[202:205], v[194:197], v[4:7]
	v_mfma_f32_16x16x32_bf16 v[0:3], v[210:213], v[194:197], v[0:3]
	s_barrier
; #define PG8_STAGE(bufoff, gbase, voff) do { _Pragma("unroll") for (int _i = 0; _i < 2; ++_i) \
;         __builtin_amdgcn_global_load_lds((const unsigned*)((const char*)(gbase) + (voff)[_i]), (PG8_LAS unsigned*)(lds + (bufoff) + ldsw + _i * 8192), 16, 0, 0); } while (0)
; #define PG8_LDA(dst, b, h) do { _Pragma("unroll") for (int m = 0; m < 4; ++m) _Pragma("unroll") for (int k = 0; k < 2; ++k) dst[m][k] = *(const PG8_LAS bf16x8*)(lds + PG8_SA(b, h) + aoff + m * 2048 + k * 1024); } while (0)
; #define PG8_LDB(dst, b, h) do { _Pragma("unroll") for (int n = 0; n < 2; ++n) _Pragma("unroll") for (int k = 0; k < 2; ++k) dst[n][k] = *(const PG8_LAS bf16x8*)(lds + PG8_SB(b, h) + boff + n * 2048 + k * 1024); } while (0)
; #define PG8_MMA(ai, bj, At, Bt) do { __builtin_amdgcn_s_setprio(1); _Pragma("unroll") for (int m = 0; m < 4; ++m) _Pragma("unroll") for (int n = 0; n < 2; ++n) _Pragma("unroll") for (int k = 0; k < 2; ++k) \
;         acc[ai][bj][m][n] = __builtin_amdgcn_mfma_f32_16x16x32_bf16(Bt[n][k], At[m][k], acc[ai][bj][m][n], 0, 0, 0); __builtin_amdgcn_s_setprio(0); } while (0)
; #define PG8_WAIT_V(n) asm volatile("s_waitcnt vmcnt(" #n ")" ::: "memory")
; #define PG8_WAIT_L(n) asm volatile("s_waitcnt lgkmcnt(" #n ")" ::: "memory")
; #define PG8_BAR __builtin_amdgcn_s_barrier()
; #define PG8_SCHED __builtin_amdgcn_sched_barrier(0)
; template <class Epi, class Sched>
; __device__ __forceinline__ void gemm_phase(PG8_LAS unsigned char* lds, const Gemm g, const Sched& S, const Epi& E) {
;     ...
;             PG8_LDB(B0, 1, 0); PG8_SCHED; PG8_LDA(At, 1, 0); PG8_STAGE(PG8_SA(0, 1), a2 + hstep, voffA);
;             PG8_WAIT_L(8); PG8_BAR; PG8_WAIT_L(0); PG8_MMA(0, 0, At, B0); PG8_BAR; PG8_SCHED;
;             PG8_LDB(B1, 1, 1); PG8_STAGE(PG8_SB(1, 0), b3, voffB);
;             PG8_BAR; PG8_WAIT_L(0); PG8_MMA(0, 1, At, B1); PG8_BAR;
;             PG8_LDA(At, 1, 1); PG8_STAGE(PG8_SA(1, 0), a3, voffA);
;             PG8_BAR; PG8_WAIT_L(0); PG8_MMA(1, 0, At, B0); PG8_BAR; PG8_SCHED;
;             PG8_STAGE(PG8_SB(1, 1), b3 + hstep, voffB);
;             PG8_WAIT_V(6); PG8_BAR; PG8_MMA(1, 1, At, B1); PG8_BAR;
	s_setprio 0
	ds_read_b128 v[150:153], v147 offset:32768
	ds_read_b128 v[154:157], v147 offset:33792
	ds_read_b128 v[158:161], v147 offset:34816
	ds_read_b128 v[162:165], v147 offset:35840
	ds_read_b128 v[166:169], v148 offset:32768
	ds_read_b128 v[170:173], v148 offset:33792
	ds_read_b128 v[174:177], v148 offset:34816
	ds_read_b128 v[178:181], v148 offset:35840
	ds_read_b128 v[182:185], v148 offset:36864
	ds_read_b128 v[186:189], v148 offset:37888
	ds_read_b128 v[190:193], v148 offset:38912
	ds_read_b128 v[194:197], v148 offset:39936
	s_waitcnt lgkmcnt(11)
	ds_read_b128 v[198:201], v149 offset:32768
	ds_read_b128 v[202:205], v149 offset:33792
	ds_read_b128 v[206:209], v149 offset:34816
	ds_read_b128 v[210:213], v149 offset:35840
	s_add_u32 s10, s30, 0x80000
	s_addc_u32 s11, s31, 0
	s_mov_b32 m0, s43
	v_lshl_add_u64 v[222:223], s[10:11], 0, v[134:135]
	global_load_lds_dwordx4 v[222:223], off
	v_lshl_add_u64 v[222:223], s[10:11], 0, v[130:131]
	s_mov_b32 m0, s44
	s_nop 0
	global_load_lds_dwordx4 v[222:223], off
	s_waitcnt vmcnt(8)
	s_waitcnt lgkmcnt(0)
	s_setprio 1
	s_barrier
	v_mfma_f32_16x16x32_bf16 v[124:127], v[150:153], v[166:169], v[124:127]
	v_mfma_f32_16x16x32_bf16 v[120:123], v[158:161], v[166:169], v[120:123]
	v_mfma_f32_16x16x32_bf16 v[108:111], v[150:153], v[174:177], v[108:111]
	v_mfma_f32_16x16x32_bf16 v[104:107], v[158:161], v[174:177], v[104:107]
	v_mfma_f32_16x16x32_bf16 v[92:95], v[150:153], v[182:185], v[92:95]
	v_mfma_f32_16x16x32_bf16 v[88:91], v[158:161], v[182:185], v[88:91]
	v_mfma_f32_16x16x32_bf16 v[76:79], v[150:153], v[190:193], v[76:79]
	v_mfma_f32_16x16x32_bf16 v[72:75], v[158:161], v[190:193], v[72:75]
	v_mfma_f32_16x16x32_bf16 v[124:127], v[154:157], v[170:173], v[124:127]
	v_mfma_f32_16x16x32_bf16 v[120:123], v[162:165], v[170:173], v[120:123]
	v_mfma_f32_16x16x32_bf16 v[108:111], v[154:157], v[178:181], v[108:111]
	v_mfma_f32_16x16x32_bf16 v[104:107], v[162:165], v[178:181], v[104:107]
	v_mfma_f32_16x16x32_bf16 v[92:95], v[154:157], v[186:189], v[92:95]
	v_mfma_f32_16x16x32_bf16 v[88:91], v[162:165], v[186:189], v[88:91]
	v_mfma_f32_16x16x32_bf16 v[76:79], v[154:157], v[194:197], v[76:79]
	v_mfma_f32_16x16x32_bf16 v[72:75], v[162:165], v[194:197], v[72:75]
	v_mfma_f32_16x16x32_bf16 v[116:119], v[198:201], v[166:169], v[116:119]
	v_mfma_f32_16x16x32_bf16 v[112:115], v[206:209], v[166:169], v[112:115]
	v_mfma_f32_16x16x32_bf16 v[100:103], v[198:201], v[174:177], v[100:103]
	v_mfma_f32_16x16x32_bf16 v[96:99], v[206:209], v[174:177], v[96:99]
	v_mfma_f32_16x16x32_bf16 v[84:87], v[198:201], v[182:185], v[84:87]
	v_mfma_f32_16x16x32_bf16 v[80:83], v[206:209], v[182:185], v[80:83]
	v_mfma_f32_16x16x32_bf16 v[68:71], v[198:201], v[190:193], v[68:71]
	v_mfma_f32_16x16x32_bf16 v[64:67], v[206:209], v[190:193], v[64:67]
	v_mfma_f32_16x16x32_bf16 v[116:119], v[202:205], v[170:173], v[116:119]
	v_mfma_f32_16x16x32_bf16 v[112:115], v[210:213], v[170:173], v[112:115]
	v_mfma_f32_16x16x32_bf16 v[100:103], v[202:205], v[178:181], v[100:103]
	v_mfma_f32_16x16x32_bf16 v[96:99], v[210:213], v[178:181], v[96:99]
	v_mfma_f32_16x16x32_bf16 v[84:87], v[202:205], v[186:189], v[84:87]
	v_mfma_f32_16x16x32_bf16 v[80:83], v[210:213], v[186:189], v[80:83]
	v_mfma_f32_16x16x32_bf16 v[68:71], v[202:205], v[194:197], v[68:71]
	v_mfma_f32_16x16x32_bf16 v[64:67], v[210:213], v[194:197], v[64:67]
	s_barrier
	s_setprio 0
	ds_read_b128 v[166:169], v148 offset:49152
	ds_read_b128 v[170:173], v148 offset:50176
	ds_read_b128 v[174:177], v148 offset:51200
	ds_read_b128 v[178:181], v148 offset:52224
	ds_read_b128 v[182:185], v148 offset:53248
	ds_read_b128 v[186:189], v148 offset:54272
	ds_read_b128 v[190:193], v148 offset:55296
	ds_read_b128 v[194:197], v148 offset:56320
	s_add_i32 s30, 0, 0x1c000
	s_add_i32 s10, s33, s39
	v_lshl_add_u64 v[214:215], v[214:215], 0, s[4:5]
	s_mov_b32 m0, s10
	s_nop 0
	global_load_lds_dwordx4 v[214:215], off
	v_lshl_add_u64 v[214:215], v[216:217], 0, s[4:5]
	s_add_i32 m0, s10, 0x2000
	s_nop 0
	global_load_lds_dwordx4 v[214:215], off
	s_mov_b32 m0, s46
	v_lshl_add_u64 v[214:215], v[218:219], 0, s[4:5]
	global_load_lds_dwordx4 v[214:215], off
	v_lshl_add_u64 v[214:215], v[220:221], 0, s[4:5]
	s_mov_b32 m0, s47
	s_nop 0
	global_load_lds_dwordx4 v[214:215], off
	s_add_u32 s10, s28, 0x80080
	s_addc_u32 s11, s29, 0
	s_add_i32 s28, s30, s39
	v_lshl_add_u64 v[222:223], s[10:11], 0, v[132:133]
	s_mov_b32 m0, s28
	s_nop 0
	global_load_lds_dwordx4 v[222:223], off
	v_lshl_add_u64 v[222:223], s[10:11], 0, v[128:129]
	s_add_i32 m0, s28, 0x2000
	s_nop 0
	global_load_lds_dwordx4 v[222:223], off
	s_waitcnt vmcnt(8)
	s_waitcnt lgkmcnt(0)
	s_setprio 1
	s_barrier
; __device__ __forceinline__ unsigned cvt_pk_bf16(float lo, float hi) { const bf16v2_t v = __builtin_convertvector((f32x2){lo, hi}, bf16v2_t); return __builtin_bit_cast(unsigned, v); }
; __device__ __forceinline__ float silu_f(float v) { return v * __builtin_amdgcn_rcpf(1.0f + __expf(-v)); }
; #define PG8_MMA(ai, bj, At, Bt) do { __builtin_amdgcn_s_setprio(1); _Pragma("unroll") for (int m = 0; m < 4; ++m) _Pragma("unroll") for (int n = 0; n < 2; ++n) _Pragma("unroll") for (int k = 0; k < 2; ++k) \
;         acc[ai][bj][m][n] = __builtin_amdgcn_mfma_f32_16x16x32_bf16(Bt[n][k], At[m][k], acc[ai][bj][m][n], 0, 0, 0); __builtin_amdgcn_s_setprio(0); } while (0)
; #define PG8_WAIT_V(n) asm volatile("s_waitcnt vmcnt(" #n ")" ::: "memory")
; #define PG8_BAR __builtin_amdgcn_s_barrier()
; template <class Epi, class Sched>
; __device__ __forceinline__ void gemm_phase(PG8_LAS unsigned char* lds, const Gemm g, const Sched& S, const Epi& E) {
;     ...
;             PG8_WAIT_V(6); PG8_BAR; PG8_MMA(1, 1, At, B1); PG8_BAR;
;         }
;         E(acc, cur, wr, wc, fr, fq); S.done(cur);
;         if (!has_next) break;
;     __device__ __forceinline__ void operator()(const AccT& acc, const pg8::Unit& u, int wr, int wc, int fr, int fq) const {
;         const int row0 = u.pm * 256 + wr * 64 + fr, col = u.pn * 128 + wc * 32 + 8 * fq;
; #pragma unroll
;         for (int ai = 0; ai < 2; ++ai)
; #pragma unroll
;             for (int m = 0; m < 4; ++m) {
;                 f32x4 a = acc[ai][0][m][0], b = acc[ai][0][m][1];
; #pragma unroll
;                 for (int j = 0; j < 4; ++j) { a[j] = silu_f(a[j]) * acc[ai][1][m][0][j]; b[j] = silu_f(b[j]) * acc[ai][1][m][1][j]; }
;                 u32x4 w; w.x = cvt_pk_bf16(a[0], a[1]); w.y = cvt_pk_bf16(a[2], a[3]); w.z = cvt_pk_bf16(b[0], b[1]); w.w = cvt_pk_bf16(b[2], b[3]);
;                 *(u32x4*)(HID + (size_t)(row0 + ai * 128 + m * 16) * DFF + col) = w;
	v_mfma_f32_16x16x32_bf16 v[60:63], v[150:153], v[166:169], v[60:63]
	v_mfma_f32_16x16x32_bf16 v[56:59], v[158:161], v[166:169], v[56:59]
	v_mfma_f32_16x16x32_bf16 v[44:47], v[150:153], v[174:177], v[44:47]
	v_mfma_f32_16x16x32_bf16 v[40:43], v[158:161], v[174:177], v[40:43]
	v_mfma_f32_16x16x32_bf16 v[28:31], v[150:153], v[182:185], v[28:31]
	v_mfma_f32_16x16x32_bf16 v[24:27], v[158:161], v[182:185], v[24:27]
	v_mfma_f32_16x16x32_bf16 v[12:15], v[150:153], v[190:193], v[12:15]
	v_mfma_f32_16x16x32_bf16 v[8:11], v[158:161], v[190:193], v[8:11]
	s_add_i32 s70, s70, 2
	s_add_u32 s26, s26, 0x100
	s_addc_u32 s27, s27, 0
	s_add_u32 s68, s68, 0x100
	s_addc_u32 s69, s69, 0
	s_cmp_gt_u32 s70, 29
	v_mfma_f32_16x16x32_bf16 v[60:63], v[154:157], v[170:173], v[60:63]
	v_mfma_f32_16x16x32_bf16 v[56:59], v[162:165], v[170:173], v[56:59]
	v_mfma_f32_16x16x32_bf16 v[44:47], v[154:157], v[178:181], v[44:47]
	v_mfma_f32_16x16x32_bf16 v[40:43], v[162:165], v[178:181], v[40:43]
	v_mfma_f32_16x16x32_bf16 v[28:31], v[154:157], v[186:189], v[28:31]
	v_mfma_f32_16x16x32_bf16 v[24:27], v[162:165], v[186:189], v[24:27]
	v_mfma_f32_16x16x32_bf16 v[12:15], v[154:157], v[194:197], v[12:15]
	v_mfma_f32_16x16x32_bf16 v[8:11], v[162:165], v[194:197], v[8:11]
	v_mfma_f32_16x16x32_bf16 v[52:55], v[198:201], v[166:169], v[52:55]
	v_mfma_f32_16x16x32_bf16 v[48:51], v[206:209], v[166:169], v[48:51]
	v_mfma_f32_16x16x32_bf16 v[36:39], v[198:201], v[174:177], v[36:39]
	v_mfma_f32_16x16x32_bf16 v[32:35], v[206:209], v[174:177], v[32:35]
	v_mfma_f32_16x16x32_bf16 v[20:23], v[198:201], v[182:185], v[20:23]
	v_mfma_f32_16x16x32_bf16 v[16:19], v[206:209], v[182:185], v[16:19]
	v_mfma_f32_16x16x32_bf16 v[4:7], v[198:201], v[190:193], v[4:7]
	v_mfma_f32_16x16x32_bf16 v[0:3], v[206:209], v[190:193], v[0:3]
	v_mfma_f32_16x16x32_bf16 v[52:55], v[202:205], v[170:173], v[52:55]
	v_mfma_f32_16x16x32_bf16 v[48:51], v[210:213], v[170:173], v[48:51]
	v_mfma_f32_16x16x32_bf16 v[36:39], v[202:205], v[178:181], v[36:39]
	v_mfma_f32_16x16x32_bf16 v[32:35], v[210:213], v[178:181], v[32:35]
	v_mfma_f32_16x16x32_bf16 v[20:23], v[202:205], v[186:189], v[20:23]
	v_mfma_f32_16x16x32_bf16 v[16:19], v[210:213], v[186:189], v[16:19]
	v_mfma_f32_16x16x32_bf16 v[4:7], v[202:205], v[194:197], v[4:7]
	v_mfma_f32_16x16x32_bf16 v[0:3], v[210:213], v[194:197], v[0:3]
	s_barrier
	s_cbranch_scc0 .LBB0_803
	s_setprio 0
	v_mul_f32_e32 v151, 0xbfb8aa3b, v124
	v_mul_f32_e32 v154, 0xbfb8aa3b, v120
	v_exp_f32_e32 v151, v151
	v_exp_f32_e32 v155, v154
	v_mul_f32_e32 v154, 0xbfb8aa3b, v125
	v_exp_f32_e32 v156, v154
	v_add_f32_e32 v151, 1.0, v151
	v_rcp_f32_e32 v154, v151
	v_add_f32_e32 v151, 1.0, v155
	v_add_f32_e32 v155, 1.0, v156
	v_rcp_f32_e32 v155, v155
	v_mul_f32_e32 v156, 0xbfb8aa3b, v121
	v_exp_f32_e32 v157, v156
	v_rcp_f32_e32 v156, v151
	v_pk_mul_f32 v[124:125], v[124:125], v[154:155]
	v_mul_f32_e32 v151, 0xbfb8aa3b, v127
	v_pk_mul_f32 v[116:117], v[124:125], v[116:117]
	v_add_f32_e32 v124, 1.0, v157
	v_mul_f32_e32 v125, 0xbfb8aa3b, v122
	v_rcp_f32_e32 v157, v124
	v_mul_f32_e32 v124, 0xbfb8aa3b, v126
	v_exp_f32_e32 v125, v125
	v_exp_f32_e32 v124, v124
	v_exp_f32_e32 v151, v151
	v_mul_f32_e32 v154, 0xbfb8aa3b, v123
	v_exp_f32_e32 v155, v154
	v_add_f32_e32 v125, 1.0, v125
	v_add_f32_e32 v124, 1.0, v124
	v_rcp_f32_e32 v154, v125
	v_add_f32_e32 v125, 1.0, v151
	v_rcp_f32_e32 v124, v124
	v_rcp_f32_e32 v125, v125
	v_add_f32_e32 v151, 1.0, v155
	v_rcp_f32_e32 v155, v151
	v_pk_mul_f32 v[120:121], v[120:121], v[156:157]
	v_lshl_or_b32 v152, s65, 7, v146
	v_pk_mul_f32 v[112:113], v[120:121], v[112:113]
	v_pk_mul_f32 v[120:121], v[126:127], v[124:125]
	v_lshl_add_u32 v150, s20, 8, v144
	v_pk_mul_f32 v[118:119], v[120:121], v[118:119]
	v_pk_mul_f32 v[120:121], v[122:123], v[154:155]
	v_ashrrev_i32_e32 v153, 31, v152
	v_pk_mul_f32 v[114:115], v[120:121], v[114:115]
	v_cvt_pk_bf16_f32 v116, v116, v117
	v_cvt_pk_bf16_f32 v117, v118, v119
	v_cvt_pk_bf16_f32 v118, v112, v113
	v_mov_b64_e32 v[112:113], s[0:1]
	v_cvt_pk_bf16_f32 v119, v114, v115
	v_mad_i64_i32 v[120:121], s[10:11], v150, s64, v[112:113]
	v_lshlrev_b64 v[114:115], 1, v[152:153]
	v_lshl_add_u64 v[120:121], v[120:121], 0, v[114:115]
	global_store_dwordx4 v[120:121], v[116:119], off
	s_and_b64 vcc, exec, s[2:3]
	s_mov_b32 s65, s6
	v_mul_f32_e32 v116, 0xbfb8aa3b, v108
	v_mul_f32_e32 v117, 0xbfb8aa3b, v104
	v_mul_f32_e32 v118, 0xbfb8aa3b, v109
	v_exp_f32_e32 v116, v116
	v_exp_f32_e32 v117, v117
	v_exp_f32_e32 v118, v118
	s_mov_b32 s20, s8
	v_add_f32_e32 v116, 1.0, v116
	v_add_f32_e32 v119, 1.0, v117
	v_add_f32_e32 v117, 1.0, v118
	v_rcp_f32_e32 v116, v116
	v_rcp_f32_e32 v117, v117
	v_mul_f32_e32 v118, 0xbfb8aa3b, v105
	v_exp_f32_e32 v120, v118
	v_rcp_f32_e32 v118, v119
	v_pk_mul_f32 v[108:109], v[108:109], v[116:117]
	v_mul_f32_e32 v116, 0xbfb8aa3b, v111
	v_pk_mul_f32 v[100:101], v[108:109], v[100:101]
	v_add_f32_e32 v108, 1.0, v120
	v_rcp_f32_e32 v119, v108
	v_mul_f32_e32 v109, 0xbfb8aa3b, v106
	v_mul_f32_e32 v108, 0xbfb8aa3b, v110
	v_exp_f32_e32 v109, v109
	v_exp_f32_e32 v108, v108
	v_exp_f32_e32 v117, v116
	v_mul_f32_e32 v116, 0xbfb8aa3b, v107
	v_pk_mul_f32 v[104:105], v[104:105], v[118:119]
	v_exp_f32_e32 v118, v116
	v_add_f32_e32 v109, 1.0, v109
	v_add_f32_e32 v108, 1.0, v108
	v_rcp_f32_e32 v116, v109
	v_add_f32_e32 v109, 1.0, v117
	v_rcp_f32_e32 v108, v108
	v_rcp_f32_e32 v109, v109
	v_add_f32_e32 v117, 1.0, v118
	v_rcp_f32_e32 v117, v117
	v_pk_mul_f32 v[104:105], v[104:105], v[96:97]
	v_pk_mul_f32 v[96:97], v[110:111], v[108:109]
	s_mov_b64 s[28:29], s[18:19]
	v_pk_mul_f32 v[102:103], v[96:97], v[102:103]
	v_pk_mul_f32 v[96:97], v[106:107], v[116:117]
; __device__ __forceinline__ unsigned cvt_pk_bf16(float lo, float hi) { const bf16v2_t v = __builtin_convertvector((f32x2){lo, hi}, bf16v2_t); return __builtin_bit_cast(unsigned, v); }
; __device__ __forceinline__ float silu_f(float v) { return v * __builtin_amdgcn_rcpf(1.0f + __expf(-v)); }
;     __device__ __forceinline__ void operator()(const AccT& acc, const pg8::Unit& u, int wr, int wc, int fr, int fq) const {
;         const int row0 = u.pm * 256 + wr * 64 + fr, col = u.pn * 128 + wc * 32 + 8 * fq;
; #pragma unroll
;         for (int ai = 0; ai < 2; ++ai)
; #pragma unroll
;             for (int m = 0; m < 4; ++m) {
;                 f32x4 a = acc[ai][0][m][0], b = acc[ai][0][m][1];
; #pragma unroll
;                 for (int j = 0; j < 4; ++j) { a[j] = silu_f(a[j]) * acc[ai][1][m][0][j]; b[j] = silu_f(b[j]) * acc[ai][1][m][1][j]; }
;                 u32x4 w; w.x = cvt_pk_bf16(a[0], a[1]); w.y = cvt_pk_bf16(a[2], a[3]); w.z = cvt_pk_bf16(b[0], b[1]); w.w = cvt_pk_bf16(b[2], b[3]);
;                 *(u32x4*)(HID + (size_t)(row0 + ai * 128 + m * 16) * DFF + col) = w;
	s_mov_b64 s[26:27], s[16:17]
	v_pk_mul_f32 v[106:107], v[96:97], v[98:99]
	v_cvt_pk_bf16_f32 v96, v100, v101
	v_or_b32_e32 v100, 16, v150
	v_mad_i64_i32 v[100:101], s[10:11], v100, s64, v[112:113]
	v_cvt_pk_bf16_f32 v97, v102, v103
	v_cvt_pk_bf16_f32 v98, v104, v105
	v_cvt_pk_bf16_f32 v99, v106, v107
	v_lshl_add_u64 v[100:101], v[100:101], 0, v[114:115]
	global_store_dwordx4 v[100:101], v[96:99], off
	s_nop 1
	v_mul_f32_e32 v96, 0xbfb8aa3b, v92
	v_mul_f32_e32 v97, 0xbfb8aa3b, v88
	v_mul_f32_e32 v98, 0xbfb8aa3b, v93
	v_exp_f32_e32 v96, v96
	v_exp_f32_e32 v97, v97
	v_exp_f32_e32 v98, v98
	v_add_f32_e32 v96, 1.0, v96
	v_add_f32_e32 v99, 1.0, v97
	v_add_f32_e32 v97, 1.0, v98
	v_rcp_f32_e32 v96, v96
	v_rcp_f32_e32 v97, v97
	v_mul_f32_e32 v98, 0xbfb8aa3b, v89
	v_exp_f32_e32 v100, v98
	v_rcp_f32_e32 v98, v99
	v_pk_mul_f32 v[92:93], v[92:93], v[96:97]
	v_mul_f32_e32 v96, 0xbfb8aa3b, v95
	v_pk_mul_f32 v[84:85], v[92:93], v[84:85]
	v_add_f32_e32 v92, 1.0, v100
	v_rcp_f32_e32 v99, v92
	v_mul_f32_e32 v93, 0xbfb8aa3b, v90
	v_mul_f32_e32 v92, 0xbfb8aa3b, v94
	v_exp_f32_e32 v93, v93
	v_exp_f32_e32 v92, v92
	v_exp_f32_e32 v97, v96
	v_mul_f32_e32 v96, 0xbfb8aa3b, v91
	v_pk_mul_f32 v[88:89], v[88:89], v[98:99]
	v_exp_f32_e32 v98, v96
	v_add_f32_e32 v93, 1.0, v93
	v_add_f32_e32 v92, 1.0, v92
	v_rcp_f32_e32 v96, v93
	v_add_f32_e32 v93, 1.0, v97
	v_rcp_f32_e32 v92, v92
	v_rcp_f32_e32 v93, v93
	v_add_f32_e32 v97, 1.0, v98
	v_rcp_f32_e32 v97, v97
	v_pk_mul_f32 v[88:89], v[88:89], v[80:81]
	v_pk_mul_f32 v[80:81], v[94:95], v[92:93]
	s_nop 0
	v_pk_mul_f32 v[86:87], v[80:81], v[86:87]
	v_pk_mul_f32 v[80:81], v[90:91], v[96:97]
	s_nop 0
	v_pk_mul_f32 v[90:91], v[80:81], v[82:83]
	v_cvt_pk_bf16_f32 v80, v84, v85
	v_or_b32_e32 v84, 32, v150
	v_mad_i64_i32 v[84:85], s[10:11], v84, s64, v[112:113]
	v_cvt_pk_bf16_f32 v81, v86, v87
	v_cvt_pk_bf16_f32 v82, v88, v89
	v_cvt_pk_bf16_f32 v83, v90, v91
	v_lshl_add_u64 v[84:85], v[84:85], 0, v[114:115]
	global_store_dwordx4 v[84:85], v[80:83], off
	s_nop 1
	v_mul_f32_e32 v80, 0xbfb8aa3b, v76
	v_mul_f32_e32 v81, 0xbfb8aa3b, v72
	v_mul_f32_e32 v82, 0xbfb8aa3b, v77
	v_exp_f32_e32 v80, v80
	v_exp_f32_e32 v81, v81
	v_exp_f32_e32 v82, v82
	v_add_f32_e32 v80, 1.0, v80
	v_add_f32_e32 v83, 1.0, v81
	v_add_f32_e32 v81, 1.0, v82
	v_rcp_f32_e32 v80, v80
	v_rcp_f32_e32 v81, v81
	v_mul_f32_e32 v82, 0xbfb8aa3b, v73
	v_exp_f32_e32 v84, v82
	v_rcp_f32_e32 v82, v83
	v_pk_mul_f32 v[76:77], v[76:77], v[80:81]
	v_mul_f32_e32 v80, 0xbfb8aa3b, v79
	v_pk_mul_f32 v[68:69], v[76:77], v[68:69]
	v_add_f32_e32 v76, 1.0, v84
	v_rcp_f32_e32 v83, v76
	v_mul_f32_e32 v77, 0xbfb8aa3b, v74
	v_mul_f32_e32 v76, 0xbfb8aa3b, v78
	v_exp_f32_e32 v77, v77
	v_exp_f32_e32 v76, v76
	v_exp_f32_e32 v81, v80
	v_mul_f32_e32 v80, 0xbfb8aa3b, v75
	v_pk_mul_f32 v[72:73], v[72:73], v[82:83]
	v_exp_f32_e32 v82, v80
	v_add_f32_e32 v77, 1.0, v77
	v_add_f32_e32 v76, 1.0, v76
	v_rcp_f32_e32 v80, v77
	v_add_f32_e32 v77, 1.0, v81
	v_rcp_f32_e32 v76, v76
	v_rcp_f32_e32 v77, v77
	v_add_f32_e32 v81, 1.0, v82
	v_rcp_f32_e32 v81, v81
	v_pk_mul_f32 v[72:73], v[72:73], v[64:65]
	v_pk_mul_f32 v[64:65], v[78:79], v[76:77]
	s_nop 0
	v_pk_mul_f32 v[70:71], v[64:65], v[70:71]
	v_pk_mul_f32 v[64:65], v[74:75], v[80:81]
	s_nop 0
	v_pk_mul_f32 v[74:75], v[64:65], v[66:67]
	v_cvt_pk_bf16_f32 v64, v68, v69
	v_or_b32_e32 v68, 48, v150
	v_mad_i64_i32 v[68:69], s[10:11], v68, s64, v[112:113]
	v_cvt_pk_bf16_f32 v65, v70, v71
	v_cvt_pk_bf16_f32 v66, v72, v73
	v_cvt_pk_bf16_f32 v67, v74, v75
	v_lshl_add_u64 v[68:69], v[68:69], 0, v[114:115]
	global_store_dwordx4 v[68:69], v[64:67], off
	v_add_u32_e32 v68, 0x80, v150
	s_nop 0
	v_mul_f32_e32 v64, 0xbfb8aa3b, v60
	v_mul_f32_e32 v65, 0xbfb8aa3b, v56
	v_mul_f32_e32 v66, 0xbfb8aa3b, v61
	v_exp_f32_e32 v64, v64
	v_exp_f32_e32 v65, v65
	v_exp_f32_e32 v66, v66
	v_add_f32_e32 v64, 1.0, v64
	v_add_f32_e32 v67, 1.0, v65
	v_add_f32_e32 v65, 1.0, v66
	v_rcp_f32_e32 v64, v64
	v_rcp_f32_e32 v65, v65
	v_mul_f32_e32 v66, 0xbfb8aa3b, v57
	v_exp_f32_e32 v69, v66
	v_rcp_f32_e32 v66, v67
	v_pk_mul_f32 v[60:61], v[60:61], v[64:65]
	v_mul_f32_e32 v64, 0xbfb8aa3b, v63
	v_pk_mul_f32 v[52:53], v[60:61], v[52:53]
	v_add_f32_e32 v60, 1.0, v69
	v_rcp_f32_e32 v67, v60
	v_mul_f32_e32 v61, 0xbfb8aa3b, v58
	v_mul_f32_e32 v60, 0xbfb8aa3b, v62
	v_exp_f32_e32 v61, v61
	v_exp_f32_e32 v60, v60
	v_exp_f32_e32 v65, v64
	v_mul_f32_e32 v64, 0xbfb8aa3b, v59
	v_pk_mul_f32 v[56:57], v[56:57], v[66:67]
	v_exp_f32_e32 v66, v64
	v_add_f32_e32 v61, 1.0, v61
	v_add_f32_e32 v60, 1.0, v60
	v_rcp_f32_e32 v64, v61
	v_add_f32_e32 v61, 1.0, v65
	v_rcp_f32_e32 v60, v60
	v_rcp_f32_e32 v61, v61
	v_add_f32_e32 v65, 1.0, v66
	v_rcp_f32_e32 v65, v65
	v_pk_mul_f32 v[56:57], v[56:57], v[48:49]
	v_pk_mul_f32 v[48:49], v[62:63], v[60:61]
	s_nop 0
	v_pk_mul_f32 v[54:55], v[48:49], v[54:55]
	v_pk_mul_f32 v[48:49], v[58:59], v[64:65]
	s_nop 0
	v_pk_mul_f32 v[58:59], v[48:49], v[50:51]
	v_cvt_pk_bf16_f32 v48, v52, v53
	v_mad_i64_i32 v[52:53], s[10:11], v68, s64, v[112:113]
	v_cvt_pk_bf16_f32 v49, v54, v55
; __device__ __forceinline__ unsigned cvt_pk_bf16(float lo, float hi) { const bf16v2_t v = __builtin_convertvector((f32x2){lo, hi}, bf16v2_t); return __builtin_bit_cast(unsigned, v); }
; __device__ __forceinline__ float silu_f(float v) { return v * __builtin_amdgcn_rcpf(1.0f + __expf(-v)); }
; template <class Epi, class Sched>
; __device__ __forceinline__ void gemm_phase(PG8_LAS unsigned char* lds, const Gemm g, const Sched& S, const Epi& E) {
;     ...
;         E(acc, cur, wr, wc, fr, fq); S.done(cur);
;         if (!has_next) break;
;     __device__ __forceinline__ void operator()(const AccT& acc, const pg8::Unit& u, int wr, int wc, int fr, int fq) const {
;         const int row0 = u.pm * 256 + wr * 64 + fr, col = u.pn * 128 + wc * 32 + 8 * fq;
; #pragma unroll
;         for (int ai = 0; ai < 2; ++ai)
; #pragma unroll
;             for (int m = 0; m < 4; ++m) {
;                 f32x4 a = acc[ai][0][m][0], b = acc[ai][0][m][1];
; #pragma unroll
;                 for (int j = 0; j < 4; ++j) { a[j] = silu_f(a[j]) * acc[ai][1][m][0][j]; b[j] = silu_f(b[j]) * acc[ai][1][m][1][j]; }
;                 u32x4 w; w.x = cvt_pk_bf16(a[0], a[1]); w.y = cvt_pk_bf16(a[2], a[3]); w.z = cvt_pk_bf16(b[0], b[1]); w.w = cvt_pk_bf16(b[2], b[3]);
;                 *(u32x4*)(HID + (size_t)(row0 + ai * 128 + m * 16) * DFF + col) = w;
	v_cvt_pk_bf16_f32 v50, v56, v57
	v_cvt_pk_bf16_f32 v51, v58, v59
	v_lshl_add_u64 v[52:53], v[52:53], 0, v[114:115]
	global_store_dwordx4 v[52:53], v[48:51], off
	s_nop 1
	v_mul_f32_e32 v48, 0xbfb8aa3b, v44
	v_mul_f32_e32 v49, 0xbfb8aa3b, v40
	v_mul_f32_e32 v50, 0xbfb8aa3b, v45
	v_exp_f32_e32 v48, v48
	v_exp_f32_e32 v49, v49
	v_exp_f32_e32 v50, v50
	v_add_f32_e32 v48, 1.0, v48
	v_add_f32_e32 v51, 1.0, v49
	v_add_f32_e32 v49, 1.0, v50
	v_rcp_f32_e32 v48, v48
	v_rcp_f32_e32 v49, v49
	v_mul_f32_e32 v50, 0xbfb8aa3b, v41
	v_exp_f32_e32 v52, v50
	v_rcp_f32_e32 v50, v51
	v_pk_mul_f32 v[44:45], v[44:45], v[48:49]
	v_mul_f32_e32 v48, 0xbfb8aa3b, v47
	v_pk_mul_f32 v[36:37], v[44:45], v[36:37]
	v_add_f32_e32 v44, 1.0, v52
	v_rcp_f32_e32 v51, v44
	v_mul_f32_e32 v45, 0xbfb8aa3b, v42
	v_mul_f32_e32 v44, 0xbfb8aa3b, v46
	v_exp_f32_e32 v45, v45
	v_exp_f32_e32 v44, v44
	v_exp_f32_e32 v49, v48
	v_mul_f32_e32 v48, 0xbfb8aa3b, v43
	v_pk_mul_f32 v[40:41], v[40:41], v[50:51]
	v_exp_f32_e32 v50, v48
	v_add_f32_e32 v45, 1.0, v45
	v_add_f32_e32 v44, 1.0, v44
	v_rcp_f32_e32 v48, v45
	v_add_f32_e32 v45, 1.0, v49
	v_rcp_f32_e32 v44, v44
	v_rcp_f32_e32 v45, v45
	v_add_f32_e32 v49, 1.0, v50
	v_rcp_f32_e32 v49, v49
	v_pk_mul_f32 v[40:41], v[40:41], v[32:33]
	v_pk_mul_f32 v[32:33], v[46:47], v[44:45]
	s_nop 0
	v_pk_mul_f32 v[38:39], v[32:33], v[38:39]
	v_pk_mul_f32 v[32:33], v[42:43], v[48:49]
	s_nop 0
	v_pk_mul_f32 v[42:43], v[32:33], v[34:35]
	v_cvt_pk_bf16_f32 v32, v36, v37
	v_add_u32_e32 v36, 0x90, v150
	v_mad_i64_i32 v[36:37], s[10:11], v36, s64, v[112:113]
	v_cvt_pk_bf16_f32 v33, v38, v39
	v_cvt_pk_bf16_f32 v34, v40, v41
	v_cvt_pk_bf16_f32 v35, v42, v43
	v_lshl_add_u64 v[36:37], v[36:37], 0, v[114:115]
	global_store_dwordx4 v[36:37], v[32:35], off
	s_nop 1
	v_mul_f32_e32 v32, 0xbfb8aa3b, v28
	v_mul_f32_e32 v33, 0xbfb8aa3b, v24
	v_mul_f32_e32 v34, 0xbfb8aa3b, v29
	v_exp_f32_e32 v32, v32
	v_exp_f32_e32 v33, v33
	v_exp_f32_e32 v34, v34
	v_add_f32_e32 v32, 1.0, v32
	v_add_f32_e32 v35, 1.0, v33
	v_add_f32_e32 v33, 1.0, v34
	v_rcp_f32_e32 v32, v32
	v_rcp_f32_e32 v33, v33
	v_mul_f32_e32 v34, 0xbfb8aa3b, v25
	v_exp_f32_e32 v36, v34
	v_rcp_f32_e32 v34, v35
	v_pk_mul_f32 v[28:29], v[28:29], v[32:33]
	v_mul_f32_e32 v32, 0xbfb8aa3b, v31
	v_pk_mul_f32 v[20:21], v[28:29], v[20:21]
	v_add_f32_e32 v28, 1.0, v36
	v_rcp_f32_e32 v35, v28
	v_mul_f32_e32 v29, 0xbfb8aa3b, v26
	v_mul_f32_e32 v28, 0xbfb8aa3b, v30
	v_exp_f32_e32 v29, v29
	v_exp_f32_e32 v28, v28
	v_exp_f32_e32 v33, v32
	v_mul_f32_e32 v32, 0xbfb8aa3b, v27
	v_pk_mul_f32 v[24:25], v[24:25], v[34:35]
	v_exp_f32_e32 v34, v32
	v_add_f32_e32 v29, 1.0, v29
	v_add_f32_e32 v28, 1.0, v28
	v_rcp_f32_e32 v32, v29
	v_add_f32_e32 v29, 1.0, v33
	v_rcp_f32_e32 v28, v28
	v_rcp_f32_e32 v29, v29
	v_add_f32_e32 v33, 1.0, v34
	v_rcp_f32_e32 v33, v33
	v_pk_mul_f32 v[24:25], v[24:25], v[16:17]
	v_pk_mul_f32 v[16:17], v[30:31], v[28:29]
	s_nop 0
	v_pk_mul_f32 v[22:23], v[16:17], v[22:23]
	v_pk_mul_f32 v[16:17], v[26:27], v[32:33]
	s_nop 0
	v_pk_mul_f32 v[26:27], v[16:17], v[18:19]
	v_cvt_pk_bf16_f32 v16, v20, v21
	v_add_u32_e32 v20, 0xa0, v150
	v_mad_i64_i32 v[20:21], s[10:11], v20, s64, v[112:113]
	v_cvt_pk_bf16_f32 v17, v22, v23
	v_cvt_pk_bf16_f32 v18, v24, v25
	v_cvt_pk_bf16_f32 v19, v26, v27
	v_lshl_add_u64 v[20:21], v[20:21], 0, v[114:115]
	global_store_dwordx4 v[20:21], v[16:19], off
	s_nop 1
	v_mul_f32_e32 v16, 0xbfb8aa3b, v12
	v_mul_f32_e32 v17, 0xbfb8aa3b, v8
	v_mul_f32_e32 v18, 0xbfb8aa3b, v13
	v_exp_f32_e32 v16, v16
	v_exp_f32_e32 v17, v17
	v_exp_f32_e32 v18, v18
	v_add_f32_e32 v16, 1.0, v16
	v_add_f32_e32 v19, 1.0, v17
	v_add_f32_e32 v17, 1.0, v18
	v_rcp_f32_e32 v16, v16
	v_rcp_f32_e32 v17, v17
	v_mul_f32_e32 v18, 0xbfb8aa3b, v9
	v_exp_f32_e32 v20, v18
	v_rcp_f32_e32 v18, v19
	v_pk_mul_f32 v[12:13], v[12:13], v[16:17]
	v_mul_f32_e32 v16, 0xbfb8aa3b, v15
	v_pk_mul_f32 v[4:5], v[12:13], v[4:5]
	v_add_f32_e32 v12, 1.0, v20
	v_rcp_f32_e32 v19, v12
	v_mul_f32_e32 v13, 0xbfb8aa3b, v10
	v_mul_f32_e32 v12, 0xbfb8aa3b, v14
	v_exp_f32_e32 v13, v13
	v_exp_f32_e32 v12, v12
	v_exp_f32_e32 v17, v16
	v_mul_f32_e32 v16, 0xbfb8aa3b, v11
	v_pk_mul_f32 v[8:9], v[8:9], v[18:19]
	v_exp_f32_e32 v18, v16
	v_add_f32_e32 v13, 1.0, v13
	v_add_f32_e32 v12, 1.0, v12
	v_rcp_f32_e32 v16, v13
	v_add_f32_e32 v13, 1.0, v17
	v_rcp_f32_e32 v12, v12
	v_rcp_f32_e32 v13, v13
	v_add_f32_e32 v17, 1.0, v18
	v_rcp_f32_e32 v17, v17
	v_pk_mul_f32 v[8:9], v[8:9], v[0:1]
	v_pk_mul_f32 v[0:1], v[14:15], v[12:13]
	s_nop 0
	v_pk_mul_f32 v[6:7], v[0:1], v[6:7]
	v_pk_mul_f32 v[0:1], v[10:11], v[16:17]
	s_nop 0
	v_pk_mul_f32 v[10:11], v[0:1], v[2:3]
	v_cvt_pk_bf16_f32 v0, v4, v5
	v_add_u32_e32 v4, 0xb0, v150
	v_mad_i64_i32 v[4:5], s[10:11], v4, s64, v[112:113]
	v_cvt_pk_bf16_f32 v1, v6, v7
	v_cvt_pk_bf16_f32 v2, v8, v9
	v_cvt_pk_bf16_f32 v3, v10, v11
	v_lshl_add_u64 v[4:5], v[4:5], 0, v[114:115]
	global_store_dwordx4 v[4:5], v[0:3], off
	s_cbranch_vccz .LBB0_800
	s_waitcnt vmcnt(0)
	s_cmpk_gt_u32 s34, 0xff
	s_cbranch_scc1 .LBB0_807
	s_barrier

; #define PG8_STAGE(bufoff, gbase, voff) do { _Pragma("unroll") for (int _i = 0; _i < 2; ++_i) \
;         __builtin_amdgcn_global_load_lds((const unsigned*)((const char*)(gbase) + (voff)[_i]), (PG8_LAS unsigned*)(lds + (bufoff) + ldsw + _i * 8192), 16, 0, 0); } while (0)
; #define PG8_LDA(dst, b, h) do { _Pragma("unroll") for (int m = 0; m < 4; ++m) _Pragma("unroll") for (int k = 0; k < 2; ++k) dst[m][k] = *(const PG8_LAS bf16x8*)(lds + PG8_SA(b, h) + aoff + m * 2048 + k * 1024); } while (0)
; #define PG8_LDB(dst, b, h) do { _Pragma("unroll") for (int n = 0; n < 2; ++n) _Pragma("unroll") for (int k = 0; k < 2; ++k) dst[n][k] = *(const PG8_LAS bf16x8*)(lds + PG8_SB(b, h) + boff + n * 2048 + k * 1024); } while (0)
; #define PG8_MMA(ai, bj, At, Bt) do { __builtin_amdgcn_s_setprio(1); _Pragma("unroll") for (int m = 0; m < 4; ++m) _Pragma("unroll") for (int n = 0; n < 2; ++n) _Pragma("unroll") for (int k = 0; k < 2; ++k) \
;         acc[ai][bj][m][n] = __builtin_amdgcn_mfma_f32_16x16x32_bf16(Bt[n][k], At[m][k], acc[ai][bj][m][n], 0, 0, 0); __builtin_amdgcn_s_setprio(0); } while (0)
; #define PG8_WAIT_L(n) asm volatile("s_waitcnt lgkmcnt(" #n ")" ::: "memory")
; #define PG8_BAR __builtin_amdgcn_s_barrier()
; #define PG8_SCHED __builtin_amdgcn_sched_barrier(0)
;     __device__ __forceinline__ bool next(int i, pg8::Unit& u) const { if (i != 0) return false; u.pm = pm; u.pn = pn; return true; }
; template <class Epi, class Sched>
; __device__ __forceinline__ void gemm_phase(PG8_LAS unsigned char* lds, const Gemm g, const Sched& S, const Epi& E) {
;     ...
;         const bool has_next = S.next(ui + 1, nxt);
;         const char* nA = has_next ? (const char*)g.A + (size_t)nxt.pm * tstep : cA; const char* nB = has_next ? (const char*)g.Bt + (size_t)nxt.pn * tstep : cB;
;         for (int t = 0; t < nt; t += 2) {
;             const bool last = (t == nt - 2);
;             const char* a1 = cA + (size_t)(t + 1) * kstep;
;             const char* a2 = last ? nA : cA + (size_t)(t + 2) * kstep; const char* b2 = last ? nB : cB + (size_t)(t + 2) * kstep;
;             const char* a3 = a2 + kstep; const char* b3 = b2 + kstep;
;             if (last && has_next) S.a_ready(nxt);
;             PG8_LDB(B0, 0, 0); PG8_SCHED; PG8_LDA(At, 0, 0); PG8_STAGE(PG8_SA(1, 1), a1 + hstep, voffA);
;             PG8_WAIT_L(8); PG8_BAR; PG8_WAIT_L(0); PG8_MMA(0, 0, At, B0); PG8_BAR; PG8_SCHED;
.LBB0_881:
	s_add_u32 s26, s26, 0x160080
	s_addc_u32 s27, s27, 0
	s_add_u32 s67, s28, 0x100
	s_addc_u32 s68, s29, 0
	s_mov_b32 s69, -2
	s_setprio 0
	ds_read_b128 v[108:111], v247
	ds_read_b128 v[112:115], v247 offset:1024
	ds_read_b128 v[124:127], v247 offset:2048
	ds_read_b128 v[128:131], v247 offset:3072
	ds_read_b128 v[144:147], v248
	ds_read_b128 v[148:151], v248 offset:1024
	ds_read_b128 v[152:155], v248 offset:2048
	ds_read_b128 v[156:159], v248 offset:3072
	ds_read_b128 v[160:163], v248 offset:4096
	ds_read_b128 v[164:167], v248 offset:5120
	ds_read_b128 v[168:171], v248 offset:6144
	ds_read_b128 v[172:175], v248 offset:7168
	s_waitcnt lgkmcnt(11)
	ds_read_b128 v[188:191], v249
	ds_read_b128 v[192:195], v249 offset:1024
	ds_read_b128 v[196:199], v249 offset:2048
	ds_read_b128 v[200:203], v249 offset:3072
	s_add_u32 s10, s26, 0xffea0080
	s_addc_u32 s11, s27, -1
	s_cmpk_eq_i32 s69, 0x54
	s_cselect_b32 s31, s1, s11
	s_cselect_b32 s30, s0, s10
	s_cselect_b32 s29, s5, s68
	s_cselect_b32 s28, s4, s67
	v_lshl_add_u64 v[252:253], s[26:27], 0, v[184:185]
	s_add_i32 m0, s40, 0xc000
	s_nop 0
	global_load_lds_dwordx4 v[252:253], off
	v_lshl_add_u64 v[252:253], s[26:27], 0, v[186:187]
	s_add_i32 m0, s40, 0xe000
	s_nop 0
	global_load_lds_dwordx4 v[252:253], off
	s_waitcnt vmcnt(8)
	s_waitcnt lgkmcnt(0)
	s_setprio 1
	s_barrier
	v_mfma_f32_16x16x32_bf16 v[140:143], v[108:111], v[144:147], 0
	v_mfma_f32_16x16x32_bf16 v[136:139], v[124:127], v[144:147], 0
	v_mfma_f32_16x16x32_bf16 v[116:119], v[108:111], v[152:155], 0
	v_mfma_f32_16x16x32_bf16 v[104:107], v[124:127], v[152:155], 0
	v_mfma_f32_16x16x32_bf16 v[92:95], v[108:111], v[160:163], 0
	v_mfma_f32_16x16x32_bf16 v[88:91], v[124:127], v[160:163], 0
	v_mfma_f32_16x16x32_bf16 v[76:79], v[108:111], v[168:171], 0
	v_mfma_f32_16x16x32_bf16 v[72:75], v[124:127], v[168:171], 0
	v_mfma_f32_16x16x32_bf16 v[140:143], v[112:115], v[148:151], v[140:143]
	v_mfma_f32_16x16x32_bf16 v[136:139], v[128:131], v[148:151], v[136:139]
	v_mfma_f32_16x16x32_bf16 v[116:119], v[112:115], v[156:159], v[116:119]
	v_mfma_f32_16x16x32_bf16 v[104:107], v[128:131], v[156:159], v[104:107]
	v_mfma_f32_16x16x32_bf16 v[92:95], v[112:115], v[164:167], v[92:95]
	v_mfma_f32_16x16x32_bf16 v[88:91], v[128:131], v[164:167], v[88:91]
	v_mfma_f32_16x16x32_bf16 v[76:79], v[112:115], v[172:175], v[76:79]
	v_mfma_f32_16x16x32_bf16 v[72:75], v[128:131], v[172:175], v[72:75]
	v_mfma_f32_16x16x32_bf16 v[132:135], v[188:191], v[144:147], 0
	v_mfma_f32_16x16x32_bf16 v[120:123], v[196:199], v[144:147], 0
	v_mfma_f32_16x16x32_bf16 v[100:103], v[188:191], v[152:155], 0
	v_mfma_f32_16x16x32_bf16 v[96:99], v[196:199], v[152:155], 0
	v_mfma_f32_16x16x32_bf16 v[84:87], v[188:191], v[160:163], 0
	v_mfma_f32_16x16x32_bf16 v[80:83], v[196:199], v[160:163], 0
	v_mfma_f32_16x16x32_bf16 v[68:71], v[188:191], v[168:171], 0
	v_mfma_f32_16x16x32_bf16 v[64:67], v[196:199], v[168:171], 0
	v_mfma_f32_16x16x32_bf16 v[132:135], v[192:195], v[148:151], v[132:135]
	v_mfma_f32_16x16x32_bf16 v[120:123], v[200:203], v[148:151], v[120:123]
	v_mfma_f32_16x16x32_bf16 v[100:103], v[192:195], v[156:159], v[100:103]
	v_mfma_f32_16x16x32_bf16 v[96:99], v[200:203], v[156:159], v[96:99]
	v_mfma_f32_16x16x32_bf16 v[84:87], v[192:195], v[164:167], v[84:87]
	v_mfma_f32_16x16x32_bf16 v[80:83], v[200:203], v[164:167], v[80:83]
	v_mfma_f32_16x16x32_bf16 v[68:71], v[192:195], v[172:175], v[68:71]
	v_mfma_f32_16x16x32_bf16 v[64:67], v[200:203], v[172:175], v[64:67]
	s_barrier
	s_setprio 0
	ds_read_b128 v[144:147], v248 offset:16384
	ds_read_b128 v[148:151], v248 offset:17408
	ds_read_b128 v[152:155], v248 offset:18432
	ds_read_b128 v[156:159], v248 offset:19456
	ds_read_b128 v[160:163], v248 offset:20480
	ds_read_b128 v[164:167], v248 offset:21504
	ds_read_b128 v[168:171], v248 offset:22528
	ds_read_b128 v[172:175], v248 offset:23552
	s_add_i32 s10, s49, s39
	v_lshl_add_u64 v[204:205], s[28:29], 0, v[178:179]
	s_mov_b32 m0, s10
	s_nop 0
	global_load_lds_dwordx4 v[204:205], off
	v_lshl_add_u64 v[206:207], s[28:29], 0, v[182:183]
	s_add_i32 m0, s10, 0x2000
	s_nop 0
	global_load_lds_dwordx4 v[206:207], off
	s_mov_b32 m0, s40
	v_lshl_add_u64 v[208:209], s[30:31], 0, v[176:177]
	global_load_lds_dwordx4 v[208:209], off
	v_lshl_add_u64 v[210:211], s[30:31], 0, v[180:181]
	s_mov_b32 m0, s41
	s_nop 0
	global_load_lds_dwordx4 v[210:211], off
	s_add_u32 s10, s28, 0x160000
	s_addc_u32 s11, s29, 0
	s_add_i32 s33, s50, s39
	v_lshl_add_u64 v[252:253], s[10:11], 0, v[178:179]
	s_mov_b32 m0, s33
	s_nop 0
	global_load_lds_dwordx4 v[252:253], off
	v_lshl_add_u64 v[252:253], s[10:11], 0, v[182:183]
	s_add_i32 m0, s33, 0x2000
	s_nop 0
	global_load_lds_dwordx4 v[252:253], off
	s_waitcnt vmcnt(8)
	s_waitcnt lgkmcnt(0)
	s_setprio 1
	s_barrier
; #define PG8_STAGE(bufoff, gbase, voff) do { _Pragma("unroll") for (int _i = 0; _i < 2; ++_i) \
;         __builtin_amdgcn_global_load_lds((const unsigned*)((const char*)(gbase) + (voff)[_i]), (PG8_LAS unsigned*)(lds + (bufoff) + ldsw + _i * 8192), 16, 0, 0); } while (0)
; #define PG8_LDA(dst, b, h) do { _Pragma("unroll") for (int m = 0; m < 4; ++m) _Pragma("unroll") for (int k = 0; k < 2; ++k) dst[m][k] = *(const PG8_LAS bf16x8*)(lds + PG8_SA(b, h) + aoff + m * 2048 + k * 1024); } while (0)
; #define PG8_LDB(dst, b, h) do { _Pragma("unroll") for (int n = 0; n < 2; ++n) _Pragma("unroll") for (int k = 0; k < 2; ++k) dst[n][k] = *(const PG8_LAS bf16x8*)(lds + PG8_SB(b, h) + boff + n * 2048 + k * 1024); } while (0)
; #define PG8_MMA(ai, bj, At, Bt) do { __builtin_amdgcn_s_setprio(1); _Pragma("unroll") for (int m = 0; m < 4; ++m) _Pragma("unroll") for (int n = 0; n < 2; ++n) _Pragma("unroll") for (int k = 0; k < 2; ++k) \
;         acc[ai][bj][m][n] = __builtin_amdgcn_mfma_f32_16x16x32_bf16(Bt[n][k], At[m][k], acc[ai][bj][m][n], 0, 0, 0); __builtin_amdgcn_s_setprio(0); } while (0)
; #define PG8_WAIT_V(n) asm volatile("s_waitcnt vmcnt(" #n ")" ::: "memory")
; #define PG8_WAIT_L(n) asm volatile("s_waitcnt lgkmcnt(" #n ")" ::: "memory")
; template <class Epi, class Sched>
; __device__ __forceinline__ void gemm_phase(PG8_LAS unsigned char* lds, const Gemm g, const Sched& S, const Epi& E) {
;     ...
;             PG8_LDB(B0, 0, 0); PG8_SCHED; PG8_LDA(At, 0, 0); PG8_STAGE(PG8_SA(1, 1), a1 + hstep, voffA);
;             PG8_WAIT_L(8); PG8_BAR; PG8_WAIT_L(0); PG8_MMA(0, 0, At, B0); PG8_BAR; PG8_SCHED;
;             PG8_LDB(B1, 0, 1); PG8_STAGE(PG8_SB(0, 0), b2, voffB);
;             PG8_BAR; PG8_WAIT_L(0); PG8_MMA(0, 1, At, B1); PG8_BAR;
;             PG8_LDA(At, 0, 1); PG8_STAGE(PG8_SA(0, 0), a2, voffA);
;             PG8_BAR; PG8_WAIT_L(0); PG8_MMA(1, 0, At, B0); PG8_BAR; PG8_SCHED;
;             PG8_STAGE(PG8_SB(0, 1), b2 + hstep, voffB);
;             PG8_WAIT_V(6); PG8_BAR; PG8_MMA(1, 1, At, B1); PG8_BAR;
;             PG8_LDB(B0, 1, 0); PG8_SCHED; PG8_LDA(At, 1, 0); PG8_STAGE(PG8_SA(0, 1), a2 + hstep, voffA);
;             PG8_WAIT_L(8); PG8_BAR; PG8_WAIT_L(0); PG8_MMA(0, 0, At, B0); PG8_BAR; PG8_SCHED;
;             PG8_LDB(B1, 1, 1); PG8_STAGE(PG8_SB(1, 0), b3, voffB);
;             PG8_BAR; PG8_WAIT_L(0); PG8_MMA(0, 1, At, B1); PG8_BAR;
	v_mfma_f32_16x16x32_bf16 v[60:63], v[108:111], v[144:147], 0
	v_mfma_f32_16x16x32_bf16 v[56:59], v[124:127], v[144:147], 0
	v_mfma_f32_16x16x32_bf16 v[44:47], v[108:111], v[152:155], 0
	v_mfma_f32_16x16x32_bf16 v[40:43], v[124:127], v[152:155], 0
	v_mfma_f32_16x16x32_bf16 v[28:31], v[108:111], v[160:163], 0
	v_mfma_f32_16x16x32_bf16 v[24:27], v[124:127], v[160:163], 0
	v_mfma_f32_16x16x32_bf16 v[12:15], v[108:111], v[168:171], 0
	v_mfma_f32_16x16x32_bf16 v[8:11], v[124:127], v[168:171], 0
	s_add_i32 s33, 0, 0x18000
	v_mfma_f32_16x16x32_bf16 v[60:63], v[112:115], v[148:151], v[60:63]
	v_mfma_f32_16x16x32_bf16 v[56:59], v[128:131], v[148:151], v[56:59]
	v_mfma_f32_16x16x32_bf16 v[44:47], v[112:115], v[156:159], v[44:47]
	v_mfma_f32_16x16x32_bf16 v[40:43], v[128:131], v[156:159], v[40:43]
	v_mfma_f32_16x16x32_bf16 v[28:31], v[112:115], v[164:167], v[28:31]
	v_mfma_f32_16x16x32_bf16 v[24:27], v[128:131], v[164:167], v[24:27]
	v_mfma_f32_16x16x32_bf16 v[12:15], v[112:115], v[172:175], v[12:15]
	v_mfma_f32_16x16x32_bf16 v[8:11], v[128:131], v[172:175], v[8:11]
	v_mfma_f32_16x16x32_bf16 v[52:55], v[188:191], v[144:147], 0
	v_mfma_f32_16x16x32_bf16 v[48:51], v[196:199], v[144:147], 0
	v_mfma_f32_16x16x32_bf16 v[36:39], v[188:191], v[152:155], 0
	v_mfma_f32_16x16x32_bf16 v[32:35], v[196:199], v[152:155], 0
	v_mfma_f32_16x16x32_bf16 v[20:23], v[188:191], v[160:163], 0
	v_mfma_f32_16x16x32_bf16 v[16:19], v[196:199], v[160:163], 0
	v_mfma_f32_16x16x32_bf16 v[4:7], v[188:191], v[168:171], 0
	v_mfma_f32_16x16x32_bf16 v[0:3], v[196:199], v[168:171], 0
	v_mfma_f32_16x16x32_bf16 v[52:55], v[192:195], v[148:151], v[52:55]
	v_mfma_f32_16x16x32_bf16 v[48:51], v[200:203], v[148:151], v[48:51]
	v_mfma_f32_16x16x32_bf16 v[36:39], v[192:195], v[156:159], v[36:39]
	v_mfma_f32_16x16x32_bf16 v[32:35], v[200:203], v[156:159], v[32:35]
	v_mfma_f32_16x16x32_bf16 v[20:23], v[192:195], v[164:167], v[20:23]
	v_mfma_f32_16x16x32_bf16 v[16:19], v[200:203], v[164:167], v[16:19]
	v_mfma_f32_16x16x32_bf16 v[4:7], v[192:195], v[172:175], v[4:7]
	v_mfma_f32_16x16x32_bf16 v[0:3], v[200:203], v[172:175], v[0:3]
	s_barrier
	s_setprio 0
	ds_read_b128 v[108:111], v247 offset:32768
	ds_read_b128 v[112:115], v247 offset:33792
	ds_read_b128 v[124:127], v247 offset:34816
	ds_read_b128 v[128:131], v247 offset:35840
	ds_read_b128 v[144:147], v248 offset:32768
	ds_read_b128 v[148:151], v248 offset:33792
	ds_read_b128 v[152:155], v248 offset:34816
	ds_read_b128 v[156:159], v248 offset:35840
	ds_read_b128 v[160:163], v248 offset:36864
	ds_read_b128 v[164:167], v248 offset:37888
	ds_read_b128 v[168:171], v248 offset:38912
	ds_read_b128 v[172:175], v248 offset:39936
	s_waitcnt lgkmcnt(11)
	ds_read_b128 v[188:191], v249 offset:32768
	ds_read_b128 v[192:195], v249 offset:33792
	ds_read_b128 v[196:199], v249 offset:34816
	ds_read_b128 v[200:203], v249 offset:35840
	s_add_u32 s10, s30, 0x160000
	s_addc_u32 s11, s31, 0
	s_mov_b32 m0, s42
	v_lshl_add_u64 v[252:253], s[10:11], 0, v[176:177]
	global_load_lds_dwordx4 v[252:253], off
	v_lshl_add_u64 v[252:253], s[10:11], 0, v[180:181]
	s_mov_b32 m0, s43
	s_nop 0
	global_load_lds_dwordx4 v[252:253], off
	s_waitcnt vmcnt(8)
	s_waitcnt lgkmcnt(0)
	s_setprio 1
	s_barrier
	v_mfma_f32_16x16x32_bf16 v[140:143], v[108:111], v[144:147], v[140:143]
	v_mfma_f32_16x16x32_bf16 v[136:139], v[124:127], v[144:147], v[136:139]
	v_mfma_f32_16x16x32_bf16 v[116:119], v[108:111], v[152:155], v[116:119]
	v_mfma_f32_16x16x32_bf16 v[104:107], v[124:127], v[152:155], v[104:107]
	v_mfma_f32_16x16x32_bf16 v[92:95], v[108:111], v[160:163], v[92:95]
	v_mfma_f32_16x16x32_bf16 v[88:91], v[124:127], v[160:163], v[88:91]
	v_mfma_f32_16x16x32_bf16 v[76:79], v[108:111], v[168:171], v[76:79]
	v_mfma_f32_16x16x32_bf16 v[72:75], v[124:127], v[168:171], v[72:75]
	v_mfma_f32_16x16x32_bf16 v[140:143], v[112:115], v[148:151], v[140:143]
	v_mfma_f32_16x16x32_bf16 v[136:139], v[128:131], v[148:151], v[136:139]
	v_mfma_f32_16x16x32_bf16 v[116:119], v[112:115], v[156:159], v[116:119]
	v_mfma_f32_16x16x32_bf16 v[104:107], v[128:131], v[156:159], v[104:107]
	v_mfma_f32_16x16x32_bf16 v[92:95], v[112:115], v[164:167], v[92:95]
	v_mfma_f32_16x16x32_bf16 v[88:91], v[128:131], v[164:167], v[88:91]
	v_mfma_f32_16x16x32_bf16 v[76:79], v[112:115], v[172:175], v[76:79]
	v_mfma_f32_16x16x32_bf16 v[72:75], v[128:131], v[172:175], v[72:75]
	v_mfma_f32_16x16x32_bf16 v[132:135], v[188:191], v[144:147], v[132:135]
	v_mfma_f32_16x16x32_bf16 v[120:123], v[196:199], v[144:147], v[120:123]
	v_mfma_f32_16x16x32_bf16 v[100:103], v[188:191], v[152:155], v[100:103]
	v_mfma_f32_16x16x32_bf16 v[96:99], v[196:199], v[152:155], v[96:99]
	v_mfma_f32_16x16x32_bf16 v[84:87], v[188:191], v[160:163], v[84:87]
	v_mfma_f32_16x16x32_bf16 v[80:83], v[196:199], v[160:163], v[80:83]
	v_mfma_f32_16x16x32_bf16 v[68:71], v[188:191], v[168:171], v[68:71]
	v_mfma_f32_16x16x32_bf16 v[64:67], v[196:199], v[168:171], v[64:67]
	v_mfma_f32_16x16x32_bf16 v[132:135], v[192:195], v[148:151], v[132:135]
	v_mfma_f32_16x16x32_bf16 v[120:123], v[200:203], v[148:151], v[120:123]
	v_mfma_f32_16x16x32_bf16 v[100:103], v[192:195], v[156:159], v[100:103]
	v_mfma_f32_16x16x32_bf16 v[96:99], v[200:203], v[156:159], v[96:99]
	v_mfma_f32_16x16x32_bf16 v[84:87], v[192:195], v[164:167], v[84:87]
	v_mfma_f32_16x16x32_bf16 v[80:83], v[200:203], v[164:167], v[80:83]
	v_mfma_f32_16x16x32_bf16 v[68:71], v[192:195], v[172:175], v[68:71]
	v_mfma_f32_16x16x32_bf16 v[64:67], v[200:203], v[172:175], v[64:67]
	s_barrier
; #define PG8_STAGE(bufoff, gbase, voff) do { _Pragma("unroll") for (int _i = 0; _i < 2; ++_i) \
;         __builtin_amdgcn_global_load_lds((const unsigned*)((const char*)(gbase) + (voff)[_i]), (PG8_LAS unsigned*)(lds + (bufoff) + ldsw + _i * 8192), 16, 0, 0); } while (0)
; #define PG8_LDA(dst, b, h) do { _Pragma("unroll") for (int m = 0; m < 4; ++m) _Pragma("unroll") for (int k = 0; k < 2; ++k) dst[m][k] = *(const PG8_LAS bf16x8*)(lds + PG8_SA(b, h) + aoff + m * 2048 + k * 1024); } while (0)
; #define PG8_WAIT_V(n) asm volatile("s_waitcnt vmcnt(" #n ")" ::: "memory")
; template <class Epi, class Sched>
; __device__ __forceinline__ void gemm_phase(PG8_LAS unsigned char* lds, const Gemm g, const Sched& S, const Epi& E) {
;     ...
;         for (int t = 0; t < nt; t += 2) {
;             const bool last = (t == nt - 2);
;             const char* a1 = cA + (size_t)(t + 1) * kstep;
;             const char* a2 = last ? nA : cA + (size_t)(t + 2) * kstep; const char* b2 = last ? nB : cB + (size_t)(t + 2) * kstep;
;             const char* a3 = a2 + kstep; const char* b3 = b2 + kstep;
;             if (last && has_next) S.a_ready(nxt);
;             PG8_LDB(B0, 0, 0); PG8_SCHED; PG8_LDA(At, 0, 0); PG8_STAGE(PG8_SA(1, 1), a1 + hstep, voffA);
;             PG8_WAIT_L(8); PG8_BAR; PG8_WAIT_L(0); PG8_MMA(0, 0, At, B0); PG8_BAR; PG8_SCHED;
;             PG8_LDB(B1, 0, 1); PG8_STAGE(PG8_SB(0, 0), b2, voffB);
;             PG8_BAR; PG8_WAIT_L(0); PG8_MMA(0, 1, At, B1); PG8_BAR;
;             PG8_LDA(At, 0, 1); PG8_STAGE(PG8_SA(0, 0), a2, voffA);
;             PG8_BAR; PG8_WAIT_L(0); PG8_MMA(1, 0, At, B0); PG8_BAR; PG8_SCHED;
;             PG8_STAGE(PG8_SB(0, 1), b2 + hstep, voffB);
;             PG8_WAIT_V(6); PG8_BAR; PG8_MMA(1, 1, At, B1); PG8_BAR;
;             PG8_LDB(B0, 1, 0); PG8_SCHED; PG8_LDA(At, 1, 0); PG8_STAGE(PG8_SA(0, 1), a2 + hstep, voffA);
;             PG8_WAIT_L(8); PG8_BAR; PG8_WAIT_L(0); PG8_MMA(0, 0, At, B0); PG8_BAR; PG8_SCHED;
;             PG8_LDB(B1, 1, 1); PG8_STAGE(PG8_SB(1, 0), b3, voffB);
;             PG8_BAR; PG8_WAIT_L(0); PG8_MMA(0, 1, At, B1); PG8_BAR;
;             PG8_LDA(At, 1, 1); PG8_STAGE(PG8_SA(1, 0), a3, voffA);
;             PG8_BAR; PG8_WAIT_L(0); PG8_MMA(1, 0, At, B0); PG8_BAR; PG8_SCHED;
;             PG8_STAGE(PG8_SB(1, 1), b3 + hstep, voffB);
;             PG8_WAIT_V(6); PG8_BAR; PG8_MMA(1, 1, At, B1); PG8_BAR;
	s_setprio 0
	ds_read_b128 v[144:147], v248 offset:49152
	ds_read_b128 v[148:151], v248 offset:50176
	ds_read_b128 v[152:155], v248 offset:51200
	ds_read_b128 v[156:159], v248 offset:52224
	ds_read_b128 v[160:163], v248 offset:53248
	ds_read_b128 v[164:167], v248 offset:54272
	ds_read_b128 v[168:171], v248 offset:55296
	ds_read_b128 v[172:175], v248 offset:56320
	s_add_i32 s30, 0, 0x1c000
	s_add_i32 s10, s33, s39
	v_lshl_add_u64 v[204:205], v[204:205], 0, s[18:19]
	s_mov_b32 m0, s10
	s_nop 0
	global_load_lds_dwordx4 v[204:205], off
	v_lshl_add_u64 v[204:205], v[206:207], 0, s[18:19]
	s_add_i32 m0, s10, 0x2000
	s_nop 0
	global_load_lds_dwordx4 v[204:205], off
	s_mov_b32 m0, s45
	v_lshl_add_u64 v[204:205], v[208:209], 0, s[18:19]
	global_load_lds_dwordx4 v[204:205], off
	v_lshl_add_u64 v[204:205], v[210:211], 0, s[18:19]
	s_mov_b32 m0, s46
	s_nop 0
	global_load_lds_dwordx4 v[204:205], off
	s_add_u32 s10, s28, 0x160080
	s_addc_u32 s11, s29, 0
	s_add_i32 s28, s30, s39
	v_lshl_add_u64 v[252:253], s[10:11], 0, v[178:179]
	s_mov_b32 m0, s28
	s_nop 0
	global_load_lds_dwordx4 v[252:253], off
	v_lshl_add_u64 v[252:253], s[10:11], 0, v[182:183]
	s_add_i32 m0, s28, 0x2000
	s_nop 0
	global_load_lds_dwordx4 v[252:253], off
	s_waitcnt vmcnt(8)
	s_waitcnt lgkmcnt(0)
	s_setprio 1
	s_barrier
	v_mfma_f32_16x16x32_bf16 v[60:63], v[108:111], v[144:147], v[60:63]
	v_mfma_f32_16x16x32_bf16 v[56:59], v[124:127], v[144:147], v[56:59]
	v_mfma_f32_16x16x32_bf16 v[44:47], v[108:111], v[152:155], v[44:47]
	v_mfma_f32_16x16x32_bf16 v[40:43], v[124:127], v[152:155], v[40:43]
	v_mfma_f32_16x16x32_bf16 v[28:31], v[108:111], v[160:163], v[28:31]
	v_mfma_f32_16x16x32_bf16 v[24:27], v[124:127], v[160:163], v[24:27]
	v_mfma_f32_16x16x32_bf16 v[12:15], v[108:111], v[168:171], v[12:15]
	v_mfma_f32_16x16x32_bf16 v[8:11], v[124:127], v[168:171], v[8:11]
	s_add_i32 s69, s69, 2
	s_add_u32 s26, s26, 0x100
	s_addc_u32 s27, s27, 0
	s_add_u32 s67, s67, 0x100
	s_addc_u32 s68, s68, 0
	s_cmpk_gt_u32 s69, 0x55
	v_mfma_f32_16x16x32_bf16 v[60:63], v[112:115], v[148:151], v[60:63]
	v_mfma_f32_16x16x32_bf16 v[56:59], v[128:131], v[148:151], v[56:59]
	v_mfma_f32_16x16x32_bf16 v[44:47], v[112:115], v[156:159], v[44:47]
	v_mfma_f32_16x16x32_bf16 v[40:43], v[128:131], v[156:159], v[40:43]
	v_mfma_f32_16x16x32_bf16 v[28:31], v[112:115], v[164:167], v[28:31]
	v_mfma_f32_16x16x32_bf16 v[24:27], v[128:131], v[164:167], v[24:27]
	v_mfma_f32_16x16x32_bf16 v[12:15], v[112:115], v[172:175], v[12:15]
	v_mfma_f32_16x16x32_bf16 v[8:11], v[128:131], v[172:175], v[8:11]
	v_mfma_f32_16x16x32_bf16 v[52:55], v[188:191], v[144:147], v[52:55]
	v_mfma_f32_16x16x32_bf16 v[48:51], v[196:199], v[144:147], v[48:51]
	v_mfma_f32_16x16x32_bf16 v[36:39], v[188:191], v[152:155], v[36:39]
	v_mfma_f32_16x16x32_bf16 v[32:35], v[196:199], v[152:155], v[32:35]
	v_mfma_f32_16x16x32_bf16 v[20:23], v[188:191], v[160:163], v[20:23]
	v_mfma_f32_16x16x32_bf16 v[16:19], v[196:199], v[160:163], v[16:19]
	v_mfma_f32_16x16x32_bf16 v[4:7], v[188:191], v[168:171], v[4:7]
	v_mfma_f32_16x16x32_bf16 v[0:3], v[196:199], v[168:171], v[0:3]
	v_mfma_f32_16x16x32_bf16 v[52:55], v[192:195], v[148:151], v[52:55]
	v_mfma_f32_16x16x32_bf16 v[48:51], v[200:203], v[148:151], v[48:51]
	v_mfma_f32_16x16x32_bf16 v[36:39], v[192:195], v[156:159], v[36:39]
	v_mfma_f32_16x16x32_bf16 v[32:35], v[200:203], v[156:159], v[32:35]
	v_mfma_f32_16x16x32_bf16 v[20:23], v[192:195], v[164:167], v[20:23]
	v_mfma_f32_16x16x32_bf16 v[16:19], v[200:203], v[164:167], v[16:19]
	v_mfma_f32_16x16x32_bf16 v[4:7], v[192:195], v[172:175], v[4:7]
	v_mfma_f32_16x16x32_bf16 v[0:3], v[200:203], v[172:175], v[0:3]
	s_barrier
.LBB0_882:
	s_setprio 0
	ds_read_b128 v[108:111], v247
	ds_read_b128 v[112:115], v247 offset:1024
	ds_read_b128 v[124:127], v247 offset:2048
	ds_read_b128 v[128:131], v247 offset:3072
	ds_read_b128 v[144:147], v248
	ds_read_b128 v[148:151], v248 offset:1024
	ds_read_b128 v[152:155], v248 offset:2048
	ds_read_b128 v[156:159], v248 offset:3072
	ds_read_b128 v[160:163], v248 offset:4096
	ds_read_b128 v[164:167], v248 offset:5120
	ds_read_b128 v[168:171], v248 offset:6144
	ds_read_b128 v[172:175], v248 offset:7168
	s_waitcnt lgkmcnt(11)
	ds_read_b128 v[188:191], v249
	ds_read_b128 v[192:195], v249 offset:1024
	ds_read_b128 v[196:199], v249 offset:2048
	ds_read_b128 v[200:203], v249 offset:3072
	s_add_u32 s10, s26, 0xffea0080
	s_addc_u32 s11, s27, -1
	s_cmpk_eq_i32 s69, 0x54
	s_cselect_b32 s31, s1, s11
	s_cselect_b32 s30, s0, s10
	s_cselect_b32 s29, s5, s68
	s_cselect_b32 s28, s4, s67
	v_lshl_add_u64 v[252:253], s[26:27], 0, v[184:185]
	s_add_i32 m0, s40, 0xc000
	s_nop 0
	global_load_lds_dwordx4 v[252:253], off
	v_lshl_add_u64 v[252:253], s[26:27], 0, v[186:187]
	s_add_i32 m0, s40, 0xe000
	s_nop 0
	global_load_lds_dwordx4 v[252:253], off
	s_waitcnt vmcnt(8)
	s_waitcnt lgkmcnt(0)
	s_setprio 1
	s_barrier
; #define PG8_STAGE(bufoff, gbase, voff) do { _Pragma("unroll") for (int _i = 0; _i < 2; ++_i) \
;         __builtin_amdgcn_global_load_lds((const unsigned*)((const char*)(gbase) + (voff)[_i]), (PG8_LAS unsigned*)(lds + (bufoff) + ldsw + _i * 8192), 16, 0, 0); } while (0)
; #define PG8_LDA(dst, b, h) do { _Pragma("unroll") for (int m = 0; m < 4; ++m) _Pragma("unroll") for (int k = 0; k < 2; ++k) dst[m][k] = *(const PG8_LAS bf16x8*)(lds + PG8_SA(b, h) + aoff + m * 2048 + k * 1024); } while (0)
; #define PG8_LDB(dst, b, h) do { _Pragma("unroll") for (int n = 0; n < 2; ++n) _Pragma("unroll") for (int k = 0; k < 2; ++k) dst[n][k] = *(const PG8_LAS bf16x8*)(lds + PG8_SB(b, h) + boff + n * 2048 + k * 1024); } while (0)
; #define PG8_WAIT_V(n) asm volatile("s_waitcnt vmcnt(" #n ")" ::: "memory")
; #define PG8_WAIT_L(n) asm volatile("s_waitcnt lgkmcnt(" #n ")" ::: "memory")
; #define PG8_BAR __builtin_amdgcn_s_barrier()
; #define PG8_SCHED __builtin_amdgcn_sched_barrier(0)
; template <class Epi, class Sched>
; __device__ __forceinline__ void gemm_phase(PG8_LAS unsigned char* lds, const Gemm g, const Sched& S, const Epi& E) {
;     ...
;             PG8_LDB(B0, 0, 0); PG8_SCHED; PG8_LDA(At, 0, 0); PG8_STAGE(PG8_SA(1, 1), a1 + hstep, voffA);
;             PG8_WAIT_L(8); PG8_BAR; PG8_WAIT_L(0); PG8_MMA(0, 0, At, B0); PG8_BAR; PG8_SCHED;
;             PG8_LDB(B1, 0, 1); PG8_STAGE(PG8_SB(0, 0), b2, voffB);
;             PG8_BAR; PG8_WAIT_L(0); PG8_MMA(0, 1, At, B1); PG8_BAR;
;             PG8_LDA(At, 0, 1); PG8_STAGE(PG8_SA(0, 0), a2, voffA);
;             PG8_BAR; PG8_WAIT_L(0); PG8_MMA(1, 0, At, B0); PG8_BAR; PG8_SCHED;
;             PG8_STAGE(PG8_SB(0, 1), b2 + hstep, voffB);
;             PG8_WAIT_V(6); PG8_BAR; PG8_MMA(1, 1, At, B1); PG8_BAR;
;             PG8_LDB(B0, 1, 0); PG8_SCHED; PG8_LDA(At, 1, 0); PG8_STAGE(PG8_SA(0, 1), a2 + hstep, voffA);
;             PG8_WAIT_L(8); PG8_BAR; PG8_WAIT_L(0); PG8_MMA(0, 0, At, B0); PG8_BAR; PG8_SCHED;
;             PG8_LDB(B1, 1, 1); PG8_STAGE(PG8_SB(1, 0), b3, voffB);
;             PG8_BAR; PG8_WAIT_L(0); PG8_MMA(0, 1, At, B1); PG8_BAR;
;             PG8_LDA(At, 1, 1); PG8_STAGE(PG8_SA(1, 0), a3, voffA);
;             PG8_BAR; PG8_WAIT_L(0); PG8_MMA(1, 0, At, B0); PG8_BAR; PG8_SCHED;
;             PG8_STAGE(PG8_SB(1, 1), b3 + hstep, voffB);
;             PG8_WAIT_V(6); PG8_BAR; PG8_MMA(1, 1, At, B1); PG8_BAR;
	v_mfma_f32_16x16x32_bf16 v[140:143], v[108:111], v[144:147], v[140:143]
	v_mfma_f32_16x16x32_bf16 v[136:139], v[124:127], v[144:147], v[136:139]
	v_mfma_f32_16x16x32_bf16 v[116:119], v[108:111], v[152:155], v[116:119]
	v_mfma_f32_16x16x32_bf16 v[104:107], v[124:127], v[152:155], v[104:107]
	v_mfma_f32_16x16x32_bf16 v[92:95], v[108:111], v[160:163], v[92:95]
	v_mfma_f32_16x16x32_bf16 v[88:91], v[124:127], v[160:163], v[88:91]
	v_mfma_f32_16x16x32_bf16 v[76:79], v[108:111], v[168:171], v[76:79]
	v_mfma_f32_16x16x32_bf16 v[72:75], v[124:127], v[168:171], v[72:75]
	v_mfma_f32_16x16x32_bf16 v[140:143], v[112:115], v[148:151], v[140:143]
	v_mfma_f32_16x16x32_bf16 v[136:139], v[128:131], v[148:151], v[136:139]
	v_mfma_f32_16x16x32_bf16 v[116:119], v[112:115], v[156:159], v[116:119]
	v_mfma_f32_16x16x32_bf16 v[104:107], v[128:131], v[156:159], v[104:107]
	v_mfma_f32_16x16x32_bf16 v[92:95], v[112:115], v[164:167], v[92:95]
	v_mfma_f32_16x16x32_bf16 v[88:91], v[128:131], v[164:167], v[88:91]
	v_mfma_f32_16x16x32_bf16 v[76:79], v[112:115], v[172:175], v[76:79]
	v_mfma_f32_16x16x32_bf16 v[72:75], v[128:131], v[172:175], v[72:75]
	v_mfma_f32_16x16x32_bf16 v[132:135], v[188:191], v[144:147], v[132:135]
	v_mfma_f32_16x16x32_bf16 v[120:123], v[196:199], v[144:147], v[120:123]
	v_mfma_f32_16x16x32_bf16 v[100:103], v[188:191], v[152:155], v[100:103]
	v_mfma_f32_16x16x32_bf16 v[96:99], v[196:199], v[152:155], v[96:99]
	v_mfma_f32_16x16x32_bf16 v[84:87], v[188:191], v[160:163], v[84:87]
	v_mfma_f32_16x16x32_bf16 v[80:83], v[196:199], v[160:163], v[80:83]
	v_mfma_f32_16x16x32_bf16 v[68:71], v[188:191], v[168:171], v[68:71]
	v_mfma_f32_16x16x32_bf16 v[64:67], v[196:199], v[168:171], v[64:67]
	v_mfma_f32_16x16x32_bf16 v[132:135], v[192:195], v[148:151], v[132:135]
	v_mfma_f32_16x16x32_bf16 v[120:123], v[200:203], v[148:151], v[120:123]
	v_mfma_f32_16x16x32_bf16 v[100:103], v[192:195], v[156:159], v[100:103]
	v_mfma_f32_16x16x32_bf16 v[96:99], v[200:203], v[156:159], v[96:99]
	v_mfma_f32_16x16x32_bf16 v[84:87], v[192:195], v[164:167], v[84:87]
	v_mfma_f32_16x16x32_bf16 v[80:83], v[200:203], v[164:167], v[80:83]
	v_mfma_f32_16x16x32_bf16 v[68:71], v[192:195], v[172:175], v[68:71]
	v_mfma_f32_16x16x32_bf16 v[64:67], v[200:203], v[172:175], v[64:67]
	s_barrier
	s_setprio 0
	ds_read_b128 v[144:147], v248 offset:16384
	ds_read_b128 v[148:151], v248 offset:17408
	ds_read_b128 v[152:155], v248 offset:18432
	ds_read_b128 v[156:159], v248 offset:19456
	ds_read_b128 v[160:163], v248 offset:20480
	ds_read_b128 v[164:167], v248 offset:21504
	ds_read_b128 v[168:171], v248 offset:22528
	ds_read_b128 v[172:175], v248 offset:23552
	s_add_i32 s10, s49, s39
	v_lshl_add_u64 v[204:205], s[28:29], 0, v[178:179]
	s_mov_b32 m0, s10
	s_nop 0
	global_load_lds_dwordx4 v[204:205], off
	v_lshl_add_u64 v[206:207], s[28:29], 0, v[182:183]
	s_add_i32 m0, s10, 0x2000
	s_nop 0
	global_load_lds_dwordx4 v[206:207], off
	s_mov_b32 m0, s40
	v_lshl_add_u64 v[208:209], s[30:31], 0, v[176:177]
	global_load_lds_dwordx4 v[208:209], off
	v_lshl_add_u64 v[210:211], s[30:31], 0, v[180:181]
	s_mov_b32 m0, s41
	s_nop 0
	global_load_lds_dwordx4 v[210:211], off
	s_add_u32 s10, s28, 0x160000
	s_addc_u32 s11, s29, 0
	s_add_i32 s33, s50, s39
	v_lshl_add_u64 v[252:253], s[10:11], 0, v[178:179]
	s_mov_b32 m0, s33
	s_nop 0
	global_load_lds_dwordx4 v[252:253], off
	v_lshl_add_u64 v[252:253], s[10:11], 0, v[182:183]
	s_add_i32 m0, s33, 0x2000
	s_nop 0
	global_load_lds_dwordx4 v[252:253], off
	s_waitcnt vmcnt(8)
	s_waitcnt lgkmcnt(0)
	s_setprio 1
	s_barrier
	v_mfma_f32_16x16x32_bf16 v[60:63], v[108:111], v[144:147], v[60:63]
	v_mfma_f32_16x16x32_bf16 v[56:59], v[124:127], v[144:147], v[56:59]
	v_mfma_f32_16x16x32_bf16 v[44:47], v[108:111], v[152:155], v[44:47]
	v_mfma_f32_16x16x32_bf16 v[40:43], v[124:127], v[152:155], v[40:43]
	v_mfma_f32_16x16x32_bf16 v[28:31], v[108:111], v[160:163], v[28:31]
	v_mfma_f32_16x16x32_bf16 v[24:27], v[124:127], v[160:163], v[24:27]
	v_mfma_f32_16x16x32_bf16 v[12:15], v[108:111], v[168:171], v[12:15]
	v_mfma_f32_16x16x32_bf16 v[8:11], v[124:127], v[168:171], v[8:11]
	s_add_i32 s33, 0, 0x18000
	v_mfma_f32_16x16x32_bf16 v[60:63], v[112:115], v[148:151], v[60:63]
	v_mfma_f32_16x16x32_bf16 v[56:59], v[128:131], v[148:151], v[56:59]
	v_mfma_f32_16x16x32_bf16 v[44:47], v[112:115], v[156:159], v[44:47]
	v_mfma_f32_16x16x32_bf16 v[40:43], v[128:131], v[156:159], v[40:43]
	v_mfma_f32_16x16x32_bf16 v[28:31], v[112:115], v[164:167], v[28:31]
	v_mfma_f32_16x16x32_bf16 v[24:27], v[128:131], v[164:167], v[24:27]
	v_mfma_f32_16x16x32_bf16 v[12:15], v[112:115], v[172:175], v[12:15]
	v_mfma_f32_16x16x32_bf16 v[8:11], v[128:131], v[172:175], v[8:11]
	v_mfma_f32_16x16x32_bf16 v[52:55], v[188:191], v[144:147], v[52:55]
	v_mfma_f32_16x16x32_bf16 v[48:51], v[196:199], v[144:147], v[48:51]
	v_mfma_f32_16x16x32_bf16 v[36:39], v[188:191], v[152:155], v[36:39]
	v_mfma_f32_16x16x32_bf16 v[32:35], v[196:199], v[152:155], v[32:35]
	v_mfma_f32_16x16x32_bf16 v[20:23], v[188:191], v[160:163], v[20:23]
	v_mfma_f32_16x16x32_bf16 v[16:19], v[196:199], v[160:163], v[16:19]
	v_mfma_f32_16x16x32_bf16 v[4:7], v[188:191], v[168:171], v[4:7]
	v_mfma_f32_16x16x32_bf16 v[0:3], v[196:199], v[168:171], v[0:3]
	v_mfma_f32_16x16x32_bf16 v[52:55], v[192:195], v[148:151], v[52:55]
	v_mfma_f32_16x16x32_bf16 v[48:51], v[200:203], v[148:151], v[48:51]
	v_mfma_f32_16x16x32_bf16 v[36:39], v[192:195], v[156:159], v[36:39]
	v_mfma_f32_16x16x32_bf16 v[32:35], v[200:203], v[156:159], v[32:35]
	v_mfma_f32_16x16x32_bf16 v[20:23], v[192:195], v[164:167], v[20:23]
	v_mfma_f32_16x16x32_bf16 v[16:19], v[200:203], v[164:167], v[16:19]
	v_mfma_f32_16x16x32_bf16 v[4:7], v[192:195], v[172:175], v[4:7]
	v_mfma_f32_16x16x32_bf16 v[0:3], v[200:203], v[172:175], v[0:3]
	s_barrier
; #define PG8_STAGE(bufoff, gbase, voff) do { _Pragma("unroll") for (int _i = 0; _i < 2; ++_i) \
;         __builtin_amdgcn_global_load_lds((const unsigned*)((const char*)(gbase) + (voff)[_i]), (PG8_LAS unsigned*)(lds + (bufoff) + ldsw + _i * 8192), 16, 0, 0); } while (0)
; #define PG8_LDA(dst, b, h) do { _Pragma("unroll") for (int m = 0; m < 4; ++m) _Pragma("unroll") for (int k = 0; k < 2; ++k) dst[m][k] = *(const PG8_LAS bf16x8*)(lds + PG8_SA(b, h) + aoff + m * 2048 + k * 1024); } while (0)
; #define PG8_LDB(dst, b, h) do { _Pragma("unroll") for (int n = 0; n < 2; ++n) _Pragma("unroll") for (int k = 0; k < 2; ++k) dst[n][k] = *(const PG8_LAS bf16x8*)(lds + PG8_SB(b, h) + boff + n * 2048 + k * 1024); } while (0)
; #define PG8_WAIT_V(n) asm volatile("s_waitcnt vmcnt(" #n ")" ::: "memory")
; #define PG8_WAIT_L(n) asm volatile("s_waitcnt lgkmcnt(" #n ")" ::: "memory")
; #define PG8_BAR __builtin_amdgcn_s_barrier()
; #define PG8_SCHED __builtin_amdgcn_sched_barrier(0)
; template <class Epi, class Sched>
; __device__ __forceinline__ void gemm_phase(PG8_LAS unsigned char* lds, const Gemm g, const Sched& S, const Epi& E) {
;     ...
;             PG8_LDB(B0, 0, 0); PG8_SCHED; PG8_LDA(At, 0, 0); PG8_STAGE(PG8_SA(1, 1), a1 + hstep, voffA);
;             PG8_WAIT_L(8); PG8_BAR; PG8_WAIT_L(0); PG8_MMA(0, 0, At, B0); PG8_BAR; PG8_SCHED;
;             PG8_LDB(B1, 0, 1); PG8_STAGE(PG8_SB(0, 0), b2, voffB);
;             PG8_BAR; PG8_WAIT_L(0); PG8_MMA(0, 1, At, B1); PG8_BAR;
;             PG8_LDA(At, 0, 1); PG8_STAGE(PG8_SA(0, 0), a2, voffA);
;             PG8_BAR; PG8_WAIT_L(0); PG8_MMA(1, 0, At, B0); PG8_BAR; PG8_SCHED;
;             PG8_STAGE(PG8_SB(0, 1), b2 + hstep, voffB);
;             PG8_WAIT_V(6); PG8_BAR; PG8_MMA(1, 1, At, B1); PG8_BAR;
;             PG8_LDB(B0, 1, 0); PG8_SCHED; PG8_LDA(At, 1, 0); PG8_STAGE(PG8_SA(0, 1), a2 + hstep, voffA);
;             PG8_WAIT_L(8); PG8_BAR; PG8_WAIT_L(0); PG8_MMA(0, 0, At, B0); PG8_BAR; PG8_SCHED;
;             PG8_LDB(B1, 1, 1); PG8_STAGE(PG8_SB(1, 0), b3, voffB);
;             PG8_BAR; PG8_WAIT_L(0); PG8_MMA(0, 1, At, B1); PG8_BAR;
;             PG8_LDA(At, 1, 1); PG8_STAGE(PG8_SA(1, 0), a3, voffA);
;             PG8_BAR; PG8_WAIT_L(0); PG8_MMA(1, 0, At, B0); PG8_BAR; PG8_SCHED;
;             PG8_STAGE(PG8_SB(1, 1), b3 + hstep, voffB);
;             PG8_WAIT_V(6); PG8_BAR; PG8_MMA(1, 1, At, B1); PG8_BAR;
	s_setprio 0
	ds_read_b128 v[108:111], v247 offset:32768
	ds_read_b128 v[112:115], v247 offset:33792
	ds_read_b128 v[124:127], v247 offset:34816
	ds_read_b128 v[128:131], v247 offset:35840
	ds_read_b128 v[144:147], v248 offset:32768
	ds_read_b128 v[148:151], v248 offset:33792
	ds_read_b128 v[152:155], v248 offset:34816
	ds_read_b128 v[156:159], v248 offset:35840
	ds_read_b128 v[160:163], v248 offset:36864
	ds_read_b128 v[164:167], v248 offset:37888
	ds_read_b128 v[168:171], v248 offset:38912
	ds_read_b128 v[172:175], v248 offset:39936
	s_waitcnt lgkmcnt(11)
	ds_read_b128 v[188:191], v249 offset:32768
	ds_read_b128 v[192:195], v249 offset:33792
	ds_read_b128 v[196:199], v249 offset:34816
	ds_read_b128 v[200:203], v249 offset:35840
	s_add_u32 s10, s30, 0x160000
	s_addc_u32 s11, s31, 0
	s_mov_b32 m0, s42
	v_lshl_add_u64 v[252:253], s[10:11], 0, v[176:177]
	global_load_lds_dwordx4 v[252:253], off
	v_lshl_add_u64 v[252:253], s[10:11], 0, v[180:181]
	s_mov_b32 m0, s43
	s_nop 0
	global_load_lds_dwordx4 v[252:253], off
	s_waitcnt vmcnt(8)
	s_waitcnt lgkmcnt(0)
	s_setprio 1
	s_barrier
	v_mfma_f32_16x16x32_bf16 v[140:143], v[108:111], v[144:147], v[140:143]
	v_mfma_f32_16x16x32_bf16 v[136:139], v[124:127], v[144:147], v[136:139]
	v_mfma_f32_16x16x32_bf16 v[116:119], v[108:111], v[152:155], v[116:119]
	v_mfma_f32_16x16x32_bf16 v[104:107], v[124:127], v[152:155], v[104:107]
	v_mfma_f32_16x16x32_bf16 v[92:95], v[108:111], v[160:163], v[92:95]
	v_mfma_f32_16x16x32_bf16 v[88:91], v[124:127], v[160:163], v[88:91]
	v_mfma_f32_16x16x32_bf16 v[76:79], v[108:111], v[168:171], v[76:79]
	v_mfma_f32_16x16x32_bf16 v[72:75], v[124:127], v[168:171], v[72:75]
	v_mfma_f32_16x16x32_bf16 v[140:143], v[112:115], v[148:151], v[140:143]
	v_mfma_f32_16x16x32_bf16 v[136:139], v[128:131], v[148:151], v[136:139]
	v_mfma_f32_16x16x32_bf16 v[116:119], v[112:115], v[156:159], v[116:119]
	v_mfma_f32_16x16x32_bf16 v[104:107], v[128:131], v[156:159], v[104:107]
	v_mfma_f32_16x16x32_bf16 v[92:95], v[112:115], v[164:167], v[92:95]
	v_mfma_f32_16x16x32_bf16 v[88:91], v[128:131], v[164:167], v[88:91]
	v_mfma_f32_16x16x32_bf16 v[76:79], v[112:115], v[172:175], v[76:79]
	v_mfma_f32_16x16x32_bf16 v[72:75], v[128:131], v[172:175], v[72:75]
	v_mfma_f32_16x16x32_bf16 v[132:135], v[188:191], v[144:147], v[132:135]
	v_mfma_f32_16x16x32_bf16 v[120:123], v[196:199], v[144:147], v[120:123]
	v_mfma_f32_16x16x32_bf16 v[100:103], v[188:191], v[152:155], v[100:103]
	v_mfma_f32_16x16x32_bf16 v[96:99], v[196:199], v[152:155], v[96:99]
	v_mfma_f32_16x16x32_bf16 v[84:87], v[188:191], v[160:163], v[84:87]
	v_mfma_f32_16x16x32_bf16 v[80:83], v[196:199], v[160:163], v[80:83]
	v_mfma_f32_16x16x32_bf16 v[68:71], v[188:191], v[168:171], v[68:71]
	v_mfma_f32_16x16x32_bf16 v[64:67], v[196:199], v[168:171], v[64:67]
	v_mfma_f32_16x16x32_bf16 v[132:135], v[192:195], v[148:151], v[132:135]
	v_mfma_f32_16x16x32_bf16 v[120:123], v[200:203], v[148:151], v[120:123]
	v_mfma_f32_16x16x32_bf16 v[100:103], v[192:195], v[156:159], v[100:103]
	v_mfma_f32_16x16x32_bf16 v[96:99], v[200:203], v[156:159], v[96:99]
	v_mfma_f32_16x16x32_bf16 v[84:87], v[192:195], v[164:167], v[84:87]
	v_mfma_f32_16x16x32_bf16 v[80:83], v[200:203], v[164:167], v[80:83]
	v_mfma_f32_16x16x32_bf16 v[68:71], v[192:195], v[172:175], v[68:71]
	v_mfma_f32_16x16x32_bf16 v[64:67], v[200:203], v[172:175], v[64:67]
	s_barrier
	s_setprio 0
	ds_read_b128 v[144:147], v248 offset:49152
	ds_read_b128 v[148:151], v248 offset:50176
	ds_read_b128 v[152:155], v248 offset:51200
	ds_read_b128 v[156:159], v248 offset:52224
	ds_read_b128 v[160:163], v248 offset:53248
	ds_read_b128 v[164:167], v248 offset:54272
	ds_read_b128 v[168:171], v248 offset:55296
	ds_read_b128 v[172:175], v248 offset:56320
	s_add_i32 s30, 0, 0x1c000
	s_add_i32 s10, s33, s39
	v_lshl_add_u64 v[204:205], v[204:205], 0, s[18:19]
	s_mov_b32 m0, s10
	s_nop 0
	global_load_lds_dwordx4 v[204:205], off
	v_lshl_add_u64 v[204:205], v[206:207], 0, s[18:19]
	s_add_i32 m0, s10, 0x2000
	s_nop 0
	global_load_lds_dwordx4 v[204:205], off
	s_mov_b32 m0, s45
	v_lshl_add_u64 v[204:205], v[208:209], 0, s[18:19]
	global_load_lds_dwordx4 v[204:205], off
	v_lshl_add_u64 v[204:205], v[210:211], 0, s[18:19]
	s_mov_b32 m0, s46
	s_nop 0
	global_load_lds_dwordx4 v[204:205], off
	s_add_u32 s10, s28, 0x160080
	s_addc_u32 s11, s29, 0
	s_add_i32 s28, s30, s39
	v_lshl_add_u64 v[252:253], s[10:11], 0, v[178:179]
	s_mov_b32 m0, s28
	s_nop 0
	global_load_lds_dwordx4 v[252:253], off
	v_lshl_add_u64 v[252:253], s[10:11], 0, v[182:183]
	s_add_i32 m0, s28, 0x2000
	s_nop 0
	global_load_lds_dwordx4 v[252:253], off
	s_waitcnt vmcnt(8)
	s_waitcnt lgkmcnt(0)
	s_setprio 1
	s_barrier
; #define PG8_WAIT_V(n) asm volatile("s_waitcnt vmcnt(" #n ")" ::: "memory")
; #define PG8_WAIT_L(n) asm volatile("s_waitcnt lgkmcnt(" #n ")" ::: "memory")
; template <class Epi, class Sched>
; __device__ __forceinline__ void gemm_phase(PG8_LAS unsigned char* lds, const Gemm g, const Sched& S, const Epi& E) {
;     ...
;         for (int t = 0; t < nt; t += 2) {
;             const bool last = (t == nt - 2);
;             const char* a1 = cA + (size_t)(t + 1) * kstep;
;             const char* a2 = last ? nA : cA + (size_t)(t + 2) * kstep; const char* b2 = last ? nB : cB + (size_t)(t + 2) * kstep;
;             const char* a3 = a2 + kstep; const char* b3 = b2 + kstep;
;             if (last && has_next) S.a_ready(nxt);
;             PG8_LDB(B0, 0, 0); PG8_SCHED; PG8_LDA(At, 0, 0); PG8_STAGE(PG8_SA(1, 1), a1 + hstep, voffA);
;             PG8_WAIT_L(8); PG8_BAR; PG8_WAIT_L(0); PG8_MMA(0, 0, At, B0); PG8_BAR; PG8_SCHED;
;             PG8_LDB(B1, 0, 1); PG8_STAGE(PG8_SB(0, 0), b2, voffB);
;             PG8_BAR; PG8_WAIT_L(0); PG8_MMA(0, 1, At, B1); PG8_BAR;
;             PG8_LDA(At, 0, 1); PG8_STAGE(PG8_SA(0, 0), a2, voffA);
;             PG8_BAR; PG8_WAIT_L(0); PG8_MMA(1, 0, At, B0); PG8_BAR; PG8_SCHED;
;             PG8_STAGE(PG8_SB(0, 1), b2 + hstep, voffB);
;             PG8_WAIT_V(6); PG8_BAR; PG8_MMA(1, 1, At, B1); PG8_BAR;
;             PG8_LDB(B0, 1, 0); PG8_SCHED; PG8_LDA(At, 1, 0); PG8_STAGE(PG8_SA(0, 1), a2 + hstep, voffA);
;             PG8_WAIT_L(8); PG8_BAR; PG8_WAIT_L(0); PG8_MMA(0, 0, At, B0); PG8_BAR; PG8_SCHED;
;             PG8_LDB(B1, 1, 1); PG8_STAGE(PG8_SB(1, 0), b3, voffB);
;             PG8_BAR; PG8_WAIT_L(0); PG8_MMA(0, 1, At, B1); PG8_BAR;
;             PG8_LDA(At, 1, 1); PG8_STAGE(PG8_SA(1, 0), a3, voffA);
;             PG8_BAR; PG8_WAIT_L(0); PG8_MMA(1, 0, At, B0); PG8_BAR; PG8_SCHED;
;             PG8_STAGE(PG8_SB(1, 1), b3 + hstep, voffB);
;             PG8_WAIT_V(6); PG8_BAR; PG8_MMA(1, 1, At, B1); PG8_BAR;
;         }
;     __device__ __forceinline__ void operator()(const AccT& acc, const pg8::Unit& u, int wr, int wc, int fr, int fq) const {
;         const int row0 = u.pm * 256 + wr * 64 + fr, col0 = u.pn * 256 + wc * 32 + 8 * fq;
;         const float* ga = mod + (u.pm >= 64 ? 12288 : 0) + 5 * 2048;
;         f32x4 gv[2][2], lg[2][2], lbv[2][2];
; #pragma unroll
;         for (int bj = 0; bj < 2; ++bj)
; #pragma unroll
	v_mfma_f32_16x16x32_bf16 v[60:63], v[108:111], v[144:147], v[60:63]
	v_mfma_f32_16x16x32_bf16 v[56:59], v[124:127], v[144:147], v[56:59]
	v_mfma_f32_16x16x32_bf16 v[44:47], v[108:111], v[152:155], v[44:47]
	v_mfma_f32_16x16x32_bf16 v[40:43], v[124:127], v[152:155], v[40:43]
	v_mfma_f32_16x16x32_bf16 v[28:31], v[108:111], v[160:163], v[28:31]
	v_mfma_f32_16x16x32_bf16 v[24:27], v[124:127], v[160:163], v[24:27]
	v_mfma_f32_16x16x32_bf16 v[12:15], v[108:111], v[168:171], v[12:15]
	v_mfma_f32_16x16x32_bf16 v[8:11], v[124:127], v[168:171], v[8:11]
	s_add_i32 s69, s69, 2
	s_add_u32 s26, s26, 0x100
	s_addc_u32 s27, s27, 0
	s_add_u32 s67, s67, 0x100
	s_addc_u32 s68, s68, 0
	s_cmpk_gt_u32 s69, 0x55
	v_mfma_f32_16x16x32_bf16 v[60:63], v[112:115], v[148:151], v[60:63]
	v_mfma_f32_16x16x32_bf16 v[56:59], v[128:131], v[148:151], v[56:59]
	v_mfma_f32_16x16x32_bf16 v[44:47], v[112:115], v[156:159], v[44:47]
	v_mfma_f32_16x16x32_bf16 v[40:43], v[128:131], v[156:159], v[40:43]
	v_mfma_f32_16x16x32_bf16 v[28:31], v[112:115], v[164:167], v[28:31]
	v_mfma_f32_16x16x32_bf16 v[24:27], v[128:131], v[164:167], v[24:27]
	v_mfma_f32_16x16x32_bf16 v[12:15], v[112:115], v[172:175], v[12:15]
	v_mfma_f32_16x16x32_bf16 v[8:11], v[128:131], v[172:175], v[8:11]
	v_mfma_f32_16x16x32_bf16 v[52:55], v[188:191], v[144:147], v[52:55]
	v_mfma_f32_16x16x32_bf16 v[48:51], v[196:199], v[144:147], v[48:51]
	v_mfma_f32_16x16x32_bf16 v[36:39], v[188:191], v[152:155], v[36:39]
	v_mfma_f32_16x16x32_bf16 v[32:35], v[196:199], v[152:155], v[32:35]
	v_mfma_f32_16x16x32_bf16 v[20:23], v[188:191], v[160:163], v[20:23]
	v_mfma_f32_16x16x32_bf16 v[16:19], v[196:199], v[160:163], v[16:19]
	v_mfma_f32_16x16x32_bf16 v[4:7], v[188:191], v[168:171], v[4:7]
	v_mfma_f32_16x16x32_bf16 v[0:3], v[196:199], v[168:171], v[0:3]
	v_mfma_f32_16x16x32_bf16 v[52:55], v[192:195], v[148:151], v[52:55]
	v_mfma_f32_16x16x32_bf16 v[48:51], v[200:203], v[148:151], v[48:51]
	v_mfma_f32_16x16x32_bf16 v[36:39], v[192:195], v[156:159], v[36:39]
	v_mfma_f32_16x16x32_bf16 v[32:35], v[200:203], v[156:159], v[32:35]
	v_mfma_f32_16x16x32_bf16 v[20:23], v[192:195], v[164:167], v[20:23]
	v_mfma_f32_16x16x32_bf16 v[16:19], v[200:203], v[164:167], v[16:19]
	v_mfma_f32_16x16x32_bf16 v[4:7], v[192:195], v[172:175], v[4:7]
	v_mfma_f32_16x16x32_bf16 v[0:3], v[200:203], v[172:175], v[0:3]
	s_barrier
	s_cbranch_scc0 .LBB0_882
	s_setprio 0
	s_cmp_gt_i32 s65, 63
	s_cselect_b32 s10, 0xc000, 0
	s_add_u32 s10, s58, s10
	v_lshl_or_b32 v156, s66, 8, v246
	s_addc_u32 s11, s59, 0
	s_add_u32 s10, s10, 0x6a0a000
	v_ashrrev_i32_e32 v157, 31, v156
	s_addc_u32 s11, s11, 0
	v_lshlrev_b64 v[144:145], 2, v[156:157]
	v_lshl_add_u64 v[108:109], s[10:11], 0, v[144:145]
	v_lshl_add_u64 v[148:149], s[22:23], 0, v[144:145]
	global_load_dwordx4 v[112:115], v[108:109], off offset:16
	global_load_dwordx4 v[128:131], v[108:109], off
	s_nop 0
	global_load_dwordx4 v[108:111], v[148:149], off offset:16
	global_load_dwordx4 v[124:127], v[148:149], off
	v_lshl_add_u64 v[152:153], s[24:25], 0, v[144:145]
	v_lshl_add_u32 v224, s65, 8, v244
	v_lshlrev_b64 v[220:221], 1, v[156:157]
	v_ashrrev_i32_e32 v225, 31, v224
	v_lshl_add_u64 v[222:223], s[6:7], 0, v[220:221]
	v_lshlrev_b64 v[240:241], 12, v[224:225]
	s_and_b64 vcc, exec, s[2:3]
	s_mov_b32 s66, s51
	s_mov_b32 s65, s64
	s_mov_b64 s[28:29], s[4:5]
	s_mov_b64 s[26:27], s[0:1]
	s_waitcnt vmcnt(0)
	v_pk_mul_f32 v[210:211], v[108:109], s[20:21] op_sel_hi:[1,0]
	v_pk_mul_f32 v[204:205], v[126:127], s[20:21] op_sel_hi:[1,0]
	v_pk_mul_f32 v[206:207], v[124:125], s[20:21] op_sel_hi:[1,0]
	global_load_dwordx4 v[124:127], v[152:153], off offset:16
	global_load_dwordx4 v[144:147], v[152:153], off
	v_or_b32_e32 v108, 0x80, v156
	v_ashrrev_i32_e32 v109, 31, v108
	v_pk_mul_f32 v[208:209], v[110:111], s[20:21] op_sel_hi:[1,0]
	v_or_b32_e32 v156, 48, v224
	v_ashrrev_i32_e32 v157, 31, v156
	v_lshlrev_b32_e32 v158, 1, v156
	v_ashrrev_i32_e32 v159, 31, v158
	v_lshlrev_b64 v[232:233], 12, v[156:157]
	v_lshl_add_u64 v[158:159], v[158:159], 2, s[8:9]
	v_lshl_add_u64 v[156:157], v[222:223], 0, v[232:233]
	s_waitcnt vmcnt(0)
	v_pk_mul_f32 v[214:215], v[124:125], s[20:21] op_sel_hi:[1,0]
	v_lshl_add_u64 v[124:125], v[108:109], 2, s[10:11]
	v_pk_mul_f32 v[216:217], v[146:147], s[20:21] op_sel_hi:[1,0]
	v_pk_mul_f32 v[218:219], v[144:145], s[20:21] op_sel_hi:[1,0]
	v_pk_mul_f32 v[212:213], v[126:127], s[20:21] op_sel_hi:[1,0]
	global_load_dwordx4 v[108:111], v[124:125], off offset:16
	s_nop 0
	global_load_dwordx4 v[124:127], v[124:125], off
	s_nop 0
	global_load_dwordx4 v[144:147], v[148:149], off offset:528
	s_nop 0
	global_load_dwordx4 v[148:151], v[148:149], off offset:512
	s_waitcnt vmcnt(0)
	v_pk_mul_f32 v[190:191], v[144:145], s[20:21] op_sel_hi:[1,0]
	v_pk_mul_f32 v[196:197], v[150:151], s[20:21] op_sel_hi:[1,0]
	v_pk_mul_f32 v[198:199], v[148:149], s[20:21] op_sel_hi:[1,0]
	global_load_dwordx4 v[148:151], v[152:153], off offset:528
	s_nop 0
	global_load_dwordx4 v[152:155], v[152:153], off offset:512
	v_lshlrev_b32_e32 v144, 1, v224
	v_ashrrev_i32_e32 v145, 31, v144
	v_lshl_add_u64 v[144:145], v[144:145], 2, s[8:9]
	global_load_dwordx2 v[234:235], v[144:145], off
	v_lshl_add_u64 v[144:145], v[222:223], 0, v[240:241]
	global_load_dwordx4 v[172:175], v[144:145], off
	global_load_dwordx4 v[160:163], v[144:145], off offset:256
	v_or_b32_e32 v144, 16, v224
	v_pk_mul_f32 v[188:189], v[146:147], s[20:21] op_sel_hi:[1,0]
	v_ashrrev_i32_e32 v145, 31, v144
	v_lshlrev_b32_e32 v146, 1, v144
	v_ashrrev_i32_e32 v147, 31, v146
	v_lshlrev_b64 v[238:239], 12, v[144:145]
	v_lshl_add_u64 v[146:147], v[146:147], 2, s[8:9]
	v_lshl_add_u64 v[144:145], v[222:223], 0, v[238:239]
	global_load_dwordx2 v[236:237], v[146:147], off
	s_waitcnt vmcnt(0)
;     __device__ __forceinline__ void operator()(const AccT& acc, const pg8::Unit& u, int wr, int wc, int fr, int fq) const {
;     ...
;         for (int ai = 0; ai < 2; ++ai) {
;             u32x4 uraw[4][2]; f32x2 stv[4];
; #pragma unroll
;             for (int m = 0; m < 4; ++m) { const int row = row0 + ai * 128 + m * 16; const size_t off = (size_t)row * D + col0; stv[m] = *(const f32x2*)(stats + 2 * row);
; #pragma unroll
;                 for (int bj = 0; bj < 2; ++bj) uraw[m][bj] = *(const u32x4*)(U1 + off + bj * 128); }
; #pragma unroll
;             for (int m = 0; m < 4; ++m) { const int row = row0 + ai * 128 + m * 16; const size_t off = (size_t)row * D + col0; const f32x2 st = stv[m];
; #pragma unroll
;                 for (int bj = 0; bj < 2; ++bj) { float uf[8]; unpack_h8(uraw[m][bj], uf);
;                     const f32x4 ua = {uf[0], uf[1], uf[2], uf[3]}, ub = {uf[4], uf[5], uf[6], uf[7]};
;                     const f32x4 a = ((ua - st.x) * st.y) * lg[bj][0] + lbv[bj][0] + gv[bj][0] * acc[ai][bj][m][0], b = ((ub - st.x) * st.y) * lg[bj][1] + lbv[bj][1] + gv[bj][1] * acc[ai][bj][m][1];
;                     u32x4 w; w.x = pk_h2(a[0], a[1]); w.y = pk_h2(a[2], a[3]); w.z = pk_h2(b[0], b[1]); w.w = pk_h2(b[2], b[3]);
;                     *(u32x4*)(U2 + off + bj * 128) = w; } }
	v_pk_mul_f32 v[192:193], v[150:151], s[20:21] op_sel_hi:[1,0]
	v_pk_mul_f32 v[194:195], v[148:149], s[20:21] op_sel_hi:[1,0]
	global_load_dwordx4 v[164:167], v[144:145], off
	global_load_dwordx4 v[148:151], v[144:145], off offset:256
	v_or_b32_e32 v144, 32, v224
	v_ashrrev_i32_e32 v145, 31, v144
	v_lshlrev_b32_e32 v146, 1, v144
	v_ashrrev_i32_e32 v147, 31, v146
	v_lshlrev_b64 v[230:231], 12, v[144:145]
	v_lshl_add_u64 v[146:147], v[146:147], 2, s[8:9]
	v_lshl_add_u64 v[144:145], v[222:223], 0, v[230:231]
	v_pk_mul_f32 v[200:201], v[154:155], s[20:21] op_sel_hi:[1,0]
	v_pk_mul_f32 v[202:203], v[152:153], s[20:21] op_sel_hi:[1,0]
	global_load_dwordx2 v[228:229], v[146:147], off
	global_load_dwordx4 v[152:155], v[144:145], off
	s_nop 0
	global_load_dwordx4 v[144:147], v[144:145], off offset:256
	v_cvt_f32_f16_sdwa v225, v172 dst_sel:DWORD dst_unused:UNUSED_PAD src0_sel:WORD_1
	global_load_dwordx2 v[226:227], v[158:159], off
	global_load_dwordx4 v[168:171], v[156:157], off
	s_nop 0
	global_load_dwordx4 v[156:159], v[156:157], off offset:256
	v_cvt_f32_f16_e32 v172, v172
	v_cvt_f32_f16_sdwa v250, v173 dst_sel:DWORD dst_unused:UNUSED_PAD src0_sel:WORD_1
	v_cvt_f32_f16_e32 v251, v173
	v_cvt_f32_f16_sdwa v252, v174 dst_sel:DWORD dst_unused:UNUSED_PAD src0_sel:WORD_1
	v_cvt_f32_f16_e32 v253, v174
	v_cvt_f32_f16_sdwa v254, v175 dst_sel:DWORD dst_unused:UNUSED_PAD src0_sel:WORD_1
	v_cvt_f32_f16_e32 v243, v175
	v_sub_f32_e32 v172, v172, v234
	v_sub_f32_e32 v173, v225, v234
	v_sub_f32_e32 v174, v251, v234
	v_sub_f32_e32 v175, v250, v234
	v_pk_mul_f32 v[174:175], v[234:235], v[174:175] op_sel:[1,0]
	v_pk_mul_f32 v[172:173], v[234:235], v[172:173] op_sel:[1,0]
	v_pk_fma_f32 v[174:175], v[204:205], v[174:175], v[216:217]
	v_pk_fma_f32 v[172:173], v[206:207], v[172:173], v[218:219]
	v_pk_fma_f32 v[142:143], v[142:143], v[130:131], v[174:175]
	v_pk_fma_f32 v[140:141], v[140:141], v[128:129], v[172:173]
	v_sub_f32_e32 v172, v253, v234
	v_sub_f32_e32 v173, v252, v234
	v_sub_f32_e32 v174, v243, v234
	v_sub_f32_e32 v175, v254, v234
	v_pk_mul_f32 v[174:175], v[234:235], v[174:175] op_sel:[1,0]
	v_pk_mul_f32 v[172:173], v[234:235], v[172:173] op_sel:[1,0]
	v_pk_fma_f32 v[174:175], v[208:209], v[174:175], v[212:213]
	v_pk_fma_f32 v[172:173], v[210:211], v[172:173], v[214:215]
	v_pk_fma_f32 v[174:175], v[138:139], v[114:115], v[174:175]
	v_pk_fma_f32 v[138:139], v[136:137], v[112:113], v[172:173]
	v_cvt_pk_f16_f32 v136, v140, v141
	v_lshl_add_u64 v[140:141], s[16:17], 0, v[240:241]
	v_cvt_pk_f16_f32 v137, v142, v143
	v_cvt_pk_f16_f32 v138, v138, v139
	v_cvt_pk_f16_f32 v139, v174, v175
	v_lshl_add_u64 v[140:141], v[140:141], 0, v[220:221]
	global_store_dwordx4 v[140:141], v[136:139], off
	v_cvt_f32_f16_sdwa v142, v162 dst_sel:DWORD dst_unused:UNUSED_PAD src0_sel:WORD_1
	v_cvt_f32_f16_e32 v143, v162
	v_cvt_f32_f16_sdwa v137, v160 dst_sel:DWORD dst_unused:UNUSED_PAD src0_sel:WORD_1
	v_cvt_f32_f16_e32 v136, v160
	v_cvt_f32_f16_sdwa v139, v161 dst_sel:DWORD dst_unused:UNUSED_PAD src0_sel:WORD_1
	v_cvt_f32_f16_e32 v138, v161
	v_cvt_f32_f16_sdwa v160, v163 dst_sel:DWORD dst_unused:UNUSED_PAD src0_sel:WORD_1
	v_cvt_f32_f16_e32 v161, v163
	v_sub_f32_e32 v136, v136, v234
	v_sub_f32_e32 v137, v137, v234
	v_sub_f32_e32 v138, v138, v234
	v_sub_f32_e32 v139, v139, v234
	v_pk_mul_f32 v[138:139], v[234:235], v[138:139] op_sel:[1,0]
	v_pk_mul_f32 v[136:137], v[234:235], v[136:137] op_sel:[1,0]
	v_pk_fma_f32 v[138:139], v[196:197], v[138:139], v[200:201]
	v_pk_fma_f32 v[136:137], v[198:199], v[136:137], v[202:203]
	v_pk_fma_f32 v[134:135], v[134:135], v[126:127], v[138:139]
	v_pk_fma_f32 v[132:133], v[132:133], v[124:125], v[136:137]
	v_sub_f32_e32 v136, v143, v234
	v_sub_f32_e32 v137, v142, v234
	v_sub_f32_e32 v138, v161, v234
	v_sub_f32_e32 v139, v160, v234
	v_pk_mul_f32 v[138:139], v[234:235], v[138:139] op_sel:[1,0]
	v_pk_mul_f32 v[136:137], v[234:235], v[136:137] op_sel:[1,0]
	v_pk_fma_f32 v[138:139], v[188:189], v[138:139], v[192:193]
	v_pk_fma_f32 v[136:137], v[190:191], v[136:137], v[194:195]
	v_pk_fma_f32 v[138:139], v[122:123], v[110:111], v[138:139]
	v_pk_fma_f32 v[122:123], v[120:121], v[108:109], v[136:137]
	v_cvt_pk_f16_f32 v120, v132, v133
	v_cvt_pk_f16_f32 v121, v134, v135
	v_cvt_pk_f16_f32 v122, v122, v123
	v_cvt_pk_f16_f32 v123, v138, v139
	global_store_dwordx4 v[140:141], v[120:123], off offset:256
	s_waitcnt vmcnt(0)
;     __device__ __forceinline__ void operator()(const AccT& acc, const pg8::Unit& u, int wr, int wc, int fr, int fq) const {
;     ...
;         for (int ai = 0; ai < 2; ++ai) {
;             u32x4 uraw[4][2]; f32x2 stv[4];
; #pragma unroll
;             for (int m = 0; m < 4; ++m) { const int row = row0 + ai * 128 + m * 16; const size_t off = (size_t)row * D + col0; stv[m] = *(const f32x2*)(stats + 2 * row);
; #pragma unroll
;                 for (int bj = 0; bj < 2; ++bj) uraw[m][bj] = *(const u32x4*)(U1 + off + bj * 128); }
; #pragma unroll
;             for (int m = 0; m < 4; ++m) { const int row = row0 + ai * 128 + m * 16; const size_t off = (size_t)row * D + col0; const f32x2 st = stv[m];
; #pragma unroll
;                 for (int bj = 0; bj < 2; ++bj) { float uf[8]; unpack_h8(uraw[m][bj], uf);
;                     const f32x4 ua = {uf[0], uf[1], uf[2], uf[3]}, ub = {uf[4], uf[5], uf[6], uf[7]};
;                     const f32x4 a = ((ua - st.x) * st.y) * lg[bj][0] + lbv[bj][0] + gv[bj][0] * acc[ai][bj][m][0], b = ((ub - st.x) * st.y) * lg[bj][1] + lbv[bj][1] + gv[bj][1] * acc[ai][bj][m][1];
;                     u32x4 w; w.x = pk_h2(a[0], a[1]); w.y = pk_h2(a[2], a[3]); w.z = pk_h2(b[0], b[1]); w.w = pk_h2(b[2], b[3]);
;                     *(u32x4*)(U2 + off + bj * 128) = w; } }
	v_cvt_f32_f16_sdwa v132, v166 dst_sel:DWORD dst_unused:UNUSED_PAD src0_sel:WORD_1
	v_cvt_f32_f16_e32 v133, v166
	v_cvt_f32_f16_sdwa v121, v164 dst_sel:DWORD dst_unused:UNUSED_PAD src0_sel:WORD_1
	v_cvt_f32_f16_e32 v120, v164
	v_cvt_f32_f16_sdwa v123, v165 dst_sel:DWORD dst_unused:UNUSED_PAD src0_sel:WORD_1
	v_cvt_f32_f16_e32 v122, v165
	v_cvt_f32_f16_sdwa v134, v167 dst_sel:DWORD dst_unused:UNUSED_PAD src0_sel:WORD_1
	v_cvt_f32_f16_e32 v135, v167
	v_sub_f32_e32 v120, v120, v236
	v_sub_f32_e32 v121, v121, v236
	v_sub_f32_e32 v122, v122, v236
	v_sub_f32_e32 v123, v123, v236
	v_pk_mul_f32 v[122:123], v[236:237], v[122:123] op_sel:[1,0]
	v_pk_mul_f32 v[120:121], v[236:237], v[120:121] op_sel:[1,0]
	v_pk_fma_f32 v[122:123], v[204:205], v[122:123], v[216:217]
	v_pk_fma_f32 v[120:121], v[206:207], v[120:121], v[218:219]
	v_pk_fma_f32 v[118:119], v[118:119], v[130:131], v[122:123]
	v_pk_fma_f32 v[116:117], v[116:117], v[128:129], v[120:121]
	v_sub_f32_e32 v120, v133, v236
	v_sub_f32_e32 v121, v132, v236
	v_sub_f32_e32 v122, v135, v236
	v_sub_f32_e32 v123, v134, v236
	v_pk_mul_f32 v[122:123], v[236:237], v[122:123] op_sel:[1,0]
	v_pk_mul_f32 v[120:121], v[236:237], v[120:121] op_sel:[1,0]
	v_pk_fma_f32 v[122:123], v[208:209], v[122:123], v[212:213]
	v_pk_fma_f32 v[120:121], v[210:211], v[120:121], v[214:215]
	v_pk_fma_f32 v[122:123], v[106:107], v[114:115], v[122:123]
	v_pk_fma_f32 v[106:107], v[104:105], v[112:113], v[120:121]
	v_cvt_pk_f16_f32 v104, v116, v117
	v_lshl_add_u64 v[116:117], s[16:17], 0, v[238:239]
	v_cvt_pk_f16_f32 v105, v118, v119
	v_cvt_pk_f16_f32 v106, v106, v107
	v_cvt_pk_f16_f32 v107, v122, v123
	v_lshl_add_u64 v[116:117], v[116:117], 0, v[220:221]
	global_store_dwordx4 v[116:117], v[104:107], off
	v_cvt_f32_f16_sdwa v118, v150 dst_sel:DWORD dst_unused:UNUSED_PAD src0_sel:WORD_1
	v_cvt_f32_f16_e32 v119, v150
	v_cvt_f32_f16_sdwa v105, v148 dst_sel:DWORD dst_unused:UNUSED_PAD src0_sel:WORD_1
	v_cvt_f32_f16_e32 v104, v148
	v_cvt_f32_f16_sdwa v107, v149 dst_sel:DWORD dst_unused:UNUSED_PAD src0_sel:WORD_1
	v_cvt_f32_f16_e32 v106, v149
	v_cvt_f32_f16_sdwa v120, v151 dst_sel:DWORD dst_unused:UNUSED_PAD src0_sel:WORD_1
	v_cvt_f32_f16_e32 v121, v151
	v_sub_f32_e32 v104, v104, v236
	v_sub_f32_e32 v105, v105, v236
	v_sub_f32_e32 v106, v106, v236
	v_sub_f32_e32 v107, v107, v236
	v_pk_mul_f32 v[106:107], v[236:237], v[106:107] op_sel:[1,0]
	v_pk_mul_f32 v[104:105], v[236:237], v[104:105] op_sel:[1,0]
	v_pk_fma_f32 v[106:107], v[196:197], v[106:107], v[200:201]
	v_pk_fma_f32 v[104:105], v[198:199], v[104:105], v[202:203]
	v_pk_fma_f32 v[102:103], v[102:103], v[126:127], v[106:107]
	v_pk_fma_f32 v[100:101], v[100:101], v[124:125], v[104:105]
	v_sub_f32_e32 v104, v119, v236
	v_sub_f32_e32 v105, v118, v236
	v_sub_f32_e32 v106, v121, v236
	v_sub_f32_e32 v107, v120, v236
	v_pk_mul_f32 v[106:107], v[236:237], v[106:107] op_sel:[1,0]
	v_pk_mul_f32 v[104:105], v[236:237], v[104:105] op_sel:[1,0]
	v_pk_fma_f32 v[106:107], v[188:189], v[106:107], v[192:193]
	v_pk_fma_f32 v[104:105], v[190:191], v[104:105], v[194:195]
	v_pk_fma_f32 v[106:107], v[98:99], v[110:111], v[106:107]
	v_pk_fma_f32 v[98:99], v[96:97], v[108:109], v[104:105]
	v_cvt_pk_f16_f32 v96, v100, v101
	v_cvt_pk_f16_f32 v97, v102, v103
	v_cvt_pk_f16_f32 v98, v98, v99
	v_cvt_pk_f16_f32 v99, v106, v107
	global_store_dwordx4 v[116:117], v[96:99], off offset:256
	v_cvt_f32_f16_sdwa v100, v154 dst_sel:DWORD dst_unused:UNUSED_PAD src0_sel:WORD_1
	v_cvt_f32_f16_e32 v101, v154
	v_cvt_f32_f16_sdwa v97, v152 dst_sel:DWORD dst_unused:UNUSED_PAD src0_sel:WORD_1
	v_cvt_f32_f16_e32 v96, v152
	v_cvt_f32_f16_sdwa v99, v153 dst_sel:DWORD dst_unused:UNUSED_PAD src0_sel:WORD_1
	v_cvt_f32_f16_e32 v98, v153
	v_cvt_f32_f16_sdwa v102, v155 dst_sel:DWORD dst_unused:UNUSED_PAD src0_sel:WORD_1
	v_cvt_f32_f16_e32 v103, v155
	v_sub_f32_e32 v96, v96, v228
	v_sub_f32_e32 v97, v97, v228
	v_sub_f32_e32 v98, v98, v228
	v_sub_f32_e32 v99, v99, v228
	v_pk_mul_f32 v[98:99], v[228:229], v[98:99] op_sel:[1,0]
	v_pk_mul_f32 v[96:97], v[228:229], v[96:97] op_sel:[1,0]
	v_pk_fma_f32 v[98:99], v[204:205], v[98:99], v[216:217]
	v_pk_fma_f32 v[96:97], v[206:207], v[96:97], v[218:219]
	v_pk_fma_f32 v[94:95], v[94:95], v[130:131], v[98:99]
	v_pk_fma_f32 v[92:93], v[92:93], v[128:129], v[96:97]
	v_sub_f32_e32 v96, v101, v228
	v_sub_f32_e32 v97, v100, v228
	v_sub_f32_e32 v98, v103, v228
	v_sub_f32_e32 v99, v102, v228
	v_pk_mul_f32 v[98:99], v[228:229], v[98:99] op_sel:[1,0]
	v_pk_mul_f32 v[96:97], v[228:229], v[96:97] op_sel:[1,0]
	v_pk_fma_f32 v[98:99], v[208:209], v[98:99], v[212:213]
	v_pk_fma_f32 v[96:97], v[210:211], v[96:97], v[214:215]
	v_pk_fma_f32 v[98:99], v[90:91], v[114:115], v[98:99]
	v_pk_fma_f32 v[90:91], v[88:89], v[112:113], v[96:97]
	v_cvt_pk_f16_f32 v88, v92, v93
	v_lshl_add_u64 v[92:93], s[16:17], 0, v[230:231]
	v_cvt_pk_f16_f32 v89, v94, v95
	v_cvt_pk_f16_f32 v90, v90, v91
	v_cvt_pk_f16_f32 v91, v98, v99
	v_lshl_add_u64 v[92:93], v[92:93], 0, v[220:221]
	global_store_dwordx4 v[92:93], v[88:91], off
	v_cvt_f32_f16_sdwa v94, v146 dst_sel:DWORD dst_unused:UNUSED_PAD src0_sel:WORD_1
	v_cvt_f32_f16_e32 v95, v146
	v_cvt_f32_f16_sdwa v89, v144 dst_sel:DWORD dst_unused:UNUSED_PAD src0_sel:WORD_1
	v_cvt_f32_f16_e32 v88, v144
	v_cvt_f32_f16_sdwa v91, v145 dst_sel:DWORD dst_unused:UNUSED_PAD src0_sel:WORD_1
	v_cvt_f32_f16_e32 v90, v145
	v_cvt_f32_f16_sdwa v96, v147 dst_sel:DWORD dst_unused:UNUSED_PAD src0_sel:WORD_1
	v_cvt_f32_f16_e32 v97, v147
	v_sub_f32_e32 v88, v88, v228
	v_sub_f32_e32 v89, v89, v228
	v_sub_f32_e32 v90, v90, v228
	v_sub_f32_e32 v91, v91, v228
	v_pk_mul_f32 v[90:91], v[228:229], v[90:91] op_sel:[1,0]
;     __device__ __forceinline__ void operator()(const AccT& acc, const pg8::Unit& u, int wr, int wc, int fr, int fq) const {
;     ...
;         for (int ai = 0; ai < 2; ++ai) {
;             u32x4 uraw[4][2]; f32x2 stv[4];
; #pragma unroll
;             for (int m = 0; m < 4; ++m) { const int row = row0 + ai * 128 + m * 16; const size_t off = (size_t)row * D + col0; stv[m] = *(const f32x2*)(stats + 2 * row);
; #pragma unroll
;                 for (int bj = 0; bj < 2; ++bj) uraw[m][bj] = *(const u32x4*)(U1 + off + bj * 128); }
; #pragma unroll
;             for (int m = 0; m < 4; ++m) { const int row = row0 + ai * 128 + m * 16; const size_t off = (size_t)row * D + col0; const f32x2 st = stv[m];
; #pragma unroll
;                 for (int bj = 0; bj < 2; ++bj) { float uf[8]; unpack_h8(uraw[m][bj], uf);
;                     const f32x4 ua = {uf[0], uf[1], uf[2], uf[3]}, ub = {uf[4], uf[5], uf[6], uf[7]};
;                     const f32x4 a = ((ua - st.x) * st.y) * lg[bj][0] + lbv[bj][0] + gv[bj][0] * acc[ai][bj][m][0], b = ((ub - st.x) * st.y) * lg[bj][1] + lbv[bj][1] + gv[bj][1] * acc[ai][bj][m][1];
;                     u32x4 w; w.x = pk_h2(a[0], a[1]); w.y = pk_h2(a[2], a[3]); w.z = pk_h2(b[0], b[1]); w.w = pk_h2(b[2], b[3]);
;                     *(u32x4*)(U2 + off + bj * 128) = w; } }
	v_pk_mul_f32 v[88:89], v[228:229], v[88:89] op_sel:[1,0]
	v_pk_fma_f32 v[90:91], v[196:197], v[90:91], v[200:201]
	v_pk_fma_f32 v[88:89], v[198:199], v[88:89], v[202:203]
	v_pk_fma_f32 v[86:87], v[86:87], v[126:127], v[90:91]
	v_pk_fma_f32 v[84:85], v[84:85], v[124:125], v[88:89]
	v_sub_f32_e32 v88, v95, v228
	v_sub_f32_e32 v89, v94, v228
	v_sub_f32_e32 v90, v97, v228
	v_sub_f32_e32 v91, v96, v228
	v_pk_mul_f32 v[90:91], v[228:229], v[90:91] op_sel:[1,0]
	v_pk_mul_f32 v[88:89], v[228:229], v[88:89] op_sel:[1,0]
	v_pk_fma_f32 v[90:91], v[188:189], v[90:91], v[192:193]
	v_pk_fma_f32 v[88:89], v[190:191], v[88:89], v[194:195]
	v_pk_fma_f32 v[90:91], v[82:83], v[110:111], v[90:91]
	v_pk_fma_f32 v[82:83], v[80:81], v[108:109], v[88:89]
	v_cvt_pk_f16_f32 v80, v84, v85
	v_cvt_pk_f16_f32 v81, v86, v87
	v_cvt_pk_f16_f32 v82, v82, v83
	v_cvt_pk_f16_f32 v83, v90, v91
	global_store_dwordx4 v[92:93], v[80:83], off offset:256
	v_cvt_f32_f16_sdwa v84, v170 dst_sel:DWORD dst_unused:UNUSED_PAD src0_sel:WORD_1
	v_cvt_f32_f16_e32 v85, v170
	v_cvt_f32_f16_sdwa v81, v168 dst_sel:DWORD dst_unused:UNUSED_PAD src0_sel:WORD_1
	v_cvt_f32_f16_e32 v80, v168
	v_cvt_f32_f16_sdwa v83, v169 dst_sel:DWORD dst_unused:UNUSED_PAD src0_sel:WORD_1
	v_cvt_f32_f16_e32 v82, v169
	v_cvt_f32_f16_sdwa v86, v171 dst_sel:DWORD dst_unused:UNUSED_PAD src0_sel:WORD_1
	v_cvt_f32_f16_e32 v87, v171
	v_sub_f32_e32 v80, v80, v226
	v_sub_f32_e32 v81, v81, v226
	v_sub_f32_e32 v82, v82, v226
	v_sub_f32_e32 v83, v83, v226
	v_pk_mul_f32 v[82:83], v[226:227], v[82:83] op_sel:[1,0]
	v_pk_mul_f32 v[80:81], v[226:227], v[80:81] op_sel:[1,0]
	v_pk_fma_f32 v[82:83], v[204:205], v[82:83], v[216:217]
	v_pk_fma_f32 v[80:81], v[206:207], v[80:81], v[218:219]
	v_pk_fma_f32 v[78:79], v[78:79], v[130:131], v[82:83]
	v_pk_fma_f32 v[76:77], v[76:77], v[128:129], v[80:81]
	v_sub_f32_e32 v80, v85, v226
	v_sub_f32_e32 v81, v84, v226
	v_sub_f32_e32 v82, v87, v226
	v_sub_f32_e32 v83, v86, v226
	v_pk_mul_f32 v[82:83], v[226:227], v[82:83] op_sel:[1,0]
	v_pk_mul_f32 v[80:81], v[226:227], v[80:81] op_sel:[1,0]
	v_pk_fma_f32 v[82:83], v[208:209], v[82:83], v[212:213]
	v_pk_fma_f32 v[80:81], v[210:211], v[80:81], v[214:215]
	v_pk_fma_f32 v[82:83], v[74:75], v[114:115], v[82:83]
	v_pk_fma_f32 v[74:75], v[72:73], v[112:113], v[80:81]
	v_cvt_pk_f16_f32 v72, v76, v77
	v_lshl_add_u64 v[76:77], s[16:17], 0, v[232:233]
	v_cvt_pk_f16_f32 v73, v78, v79
	v_cvt_pk_f16_f32 v74, v74, v75
	v_cvt_pk_f16_f32 v75, v82, v83
	v_lshl_add_u64 v[76:77], v[76:77], 0, v[220:221]
	global_store_dwordx4 v[76:77], v[72:75], off
	v_cvt_f32_f16_sdwa v78, v158 dst_sel:DWORD dst_unused:UNUSED_PAD src0_sel:WORD_1
	v_cvt_f32_f16_e32 v79, v158
	v_cvt_f32_f16_sdwa v73, v156 dst_sel:DWORD dst_unused:UNUSED_PAD src0_sel:WORD_1
	v_cvt_f32_f16_e32 v72, v156
	v_cvt_f32_f16_sdwa v75, v157 dst_sel:DWORD dst_unused:UNUSED_PAD src0_sel:WORD_1
	v_cvt_f32_f16_e32 v74, v157
	v_cvt_f32_f16_sdwa v80, v159 dst_sel:DWORD dst_unused:UNUSED_PAD src0_sel:WORD_1
	v_cvt_f32_f16_e32 v81, v159
	v_sub_f32_e32 v72, v72, v226
	v_sub_f32_e32 v73, v73, v226
	v_sub_f32_e32 v74, v74, v226
	v_sub_f32_e32 v75, v75, v226
	v_pk_mul_f32 v[74:75], v[226:227], v[74:75] op_sel:[1,0]
	v_pk_mul_f32 v[72:73], v[226:227], v[72:73] op_sel:[1,0]
	v_pk_fma_f32 v[74:75], v[196:197], v[74:75], v[200:201]
	v_pk_fma_f32 v[72:73], v[198:199], v[72:73], v[202:203]
	v_pk_fma_f32 v[70:71], v[70:71], v[126:127], v[74:75]
	v_pk_fma_f32 v[68:69], v[68:69], v[124:125], v[72:73]
	v_sub_f32_e32 v72, v79, v226
	v_sub_f32_e32 v73, v78, v226
	v_sub_f32_e32 v74, v81, v226
	v_sub_f32_e32 v75, v80, v226
	v_pk_mul_f32 v[74:75], v[226:227], v[74:75] op_sel:[1,0]
	v_pk_mul_f32 v[72:73], v[226:227], v[72:73] op_sel:[1,0]
	v_pk_fma_f32 v[74:75], v[188:189], v[74:75], v[192:193]
	v_pk_fma_f32 v[72:73], v[190:191], v[72:73], v[194:195]
	v_pk_fma_f32 v[74:75], v[66:67], v[110:111], v[74:75]
	v_pk_fma_f32 v[66:67], v[64:65], v[108:109], v[72:73]
	v_cvt_pk_f16_f32 v64, v68, v69
	v_cvt_pk_f16_f32 v65, v70, v71
	v_cvt_pk_f16_f32 v66, v66, v67
	v_cvt_pk_f16_f32 v67, v74, v75
	global_store_dwordx4 v[76:77], v[64:67], off offset:256
	s_nop 1
	v_add_u32_e32 v64, 0x80, v224
	v_ashrrev_i32_e32 v65, 31, v64
	v_lshlrev_b32_e32 v66, 1, v64
	v_ashrrev_i32_e32 v67, 31, v66
	v_lshlrev_b64 v[106:107], 12, v[64:65]
	v_lshl_add_u64 v[66:67], v[66:67], 2, s[8:9]
	v_lshl_add_u64 v[64:65], v[222:223], 0, v[106:107]
	global_load_dwordx2 v[104:105], v[66:67], off
	global_load_dwordx4 v[84:87], v[64:65], off
	global_load_dwordx4 v[88:91], v[64:65], off offset:256
	v_add_u32_e32 v64, 0x90, v224
	v_ashrrev_i32_e32 v65, 31, v64
	v_lshlrev_b32_e32 v66, 1, v64
	v_ashrrev_i32_e32 v67, 31, v66
	v_lshlrev_b64 v[118:119], 12, v[64:65]
	v_lshl_add_u64 v[66:67], v[66:67], 2, s[8:9]
	v_lshl_add_u64 v[64:65], v[222:223], 0, v[118:119]
	global_load_dwordx2 v[116:117], v[66:67], off
	global_load_dwordx4 v[92:95], v[64:65], off
	global_load_dwordx4 v[96:99], v[64:65], off offset:256
	v_add_u32_e32 v64, 0xa0, v224
	v_ashrrev_i32_e32 v65, 31, v64
	v_lshlrev_b32_e32 v66, 1, v64
	v_ashrrev_i32_e32 v67, 31, v66
	v_lshlrev_b64 v[82:83], 12, v[64:65]
	v_lshl_add_u64 v[66:67], v[66:67], 2, s[8:9]
	v_lshl_add_u64 v[64:65], v[222:223], 0, v[82:83]
	global_load_dwordx2 v[80:81], v[66:67], off
	global_load_dwordx4 v[100:103], v[64:65], off
	global_load_dwordx4 v[72:75], v[64:65], off offset:256
	v_add_u32_e32 v64, 0xb0, v224
	v_ashrrev_i32_e32 v65, 31, v64
	v_lshlrev_b32_e32 v66, 1, v64
	v_ashrrev_i32_e32 v67, 31, v66
	v_lshlrev_b64 v[78:79], 12, v[64:65]
	v_lshl_add_u64 v[66:67], v[66:67], 2, s[8:9]
	v_lshl_add_u64 v[64:65], v[222:223], 0, v[78:79]
	global_load_dwordx2 v[76:77], v[66:67], off
	global_load_dwordx4 v[68:71], v[64:65], off
	s_nop 0
	global_load_dwordx4 v[64:67], v[64:65], off offset:256
	s_waitcnt vmcnt(0)
;     __device__ __forceinline__ void operator()(const AccT& acc, const pg8::Unit& u, int wr, int wc, int fr, int fq) const {
;     ...
;         for (int ai = 0; ai < 2; ++ai) {
;             u32x4 uraw[4][2]; f32x2 stv[4];
; #pragma unroll
;             for (int m = 0; m < 4; ++m) { const int row = row0 + ai * 128 + m * 16; const size_t off = (size_t)row * D + col0; stv[m] = *(const f32x2*)(stats + 2 * row);
; #pragma unroll
;                 for (int bj = 0; bj < 2; ++bj) uraw[m][bj] = *(const u32x4*)(U1 + off + bj * 128); }
; #pragma unroll
;             for (int m = 0; m < 4; ++m) { const int row = row0 + ai * 128 + m * 16; const size_t off = (size_t)row * D + col0; const f32x2 st = stv[m];
; #pragma unroll
;                 for (int bj = 0; bj < 2; ++bj) { float uf[8]; unpack_h8(uraw[m][bj], uf);
;                     const f32x4 ua = {uf[0], uf[1], uf[2], uf[3]}, ub = {uf[4], uf[5], uf[6], uf[7]};
;                     const f32x4 a = ((ua - st.x) * st.y) * lg[bj][0] + lbv[bj][0] + gv[bj][0] * acc[ai][bj][m][0], b = ((ub - st.x) * st.y) * lg[bj][1] + lbv[bj][1] + gv[bj][1] * acc[ai][bj][m][1];
;                     u32x4 w; w.x = pk_h2(a[0], a[1]); w.y = pk_h2(a[2], a[3]); w.z = pk_h2(b[0], b[1]); w.w = pk_h2(b[2], b[3]);
;                     *(u32x4*)(U2 + off + bj * 128) = w; } }
	v_cvt_f32_f16_e32 v120, v84
	v_cvt_f32_f16_sdwa v84, v84 dst_sel:DWORD dst_unused:UNUSED_PAD src0_sel:WORD_1
	v_cvt_f32_f16_e32 v121, v85
	v_cvt_f32_f16_sdwa v122, v85 dst_sel:DWORD dst_unused:UNUSED_PAD src0_sel:WORD_1
	v_cvt_f32_f16_e32 v123, v86
	v_cvt_f32_f16_sdwa v132, v86 dst_sel:DWORD dst_unused:UNUSED_PAD src0_sel:WORD_1
	v_cvt_f32_f16_e32 v133, v87
	v_cvt_f32_f16_sdwa v134, v87 dst_sel:DWORD dst_unused:UNUSED_PAD src0_sel:WORD_1
	v_sub_f32_e32 v85, v84, v104
	v_sub_f32_e32 v84, v120, v104
	v_sub_f32_e32 v87, v122, v104
	v_sub_f32_e32 v86, v121, v104
	v_pk_mul_f32 v[86:87], v[104:105], v[86:87] op_sel:[1,0]
	v_pk_mul_f32 v[84:85], v[104:105], v[84:85] op_sel:[1,0]
	v_pk_fma_f32 v[86:87], v[204:205], v[86:87], v[216:217]
	v_pk_fma_f32 v[84:85], v[206:207], v[84:85], v[218:219]
	v_pk_fma_f32 v[62:63], v[62:63], v[130:131], v[86:87]
	v_pk_fma_f32 v[60:61], v[60:61], v[128:129], v[84:85]
	v_sub_f32_e32 v85, v132, v104
	v_sub_f32_e32 v84, v123, v104
	v_sub_f32_e32 v87, v134, v104
	v_sub_f32_e32 v86, v133, v104
	v_pk_mul_f32 v[86:87], v[104:105], v[86:87] op_sel:[1,0]
	v_pk_mul_f32 v[84:85], v[104:105], v[84:85] op_sel:[1,0]
	v_pk_fma_f32 v[86:87], v[208:209], v[86:87], v[212:213]
	v_pk_fma_f32 v[84:85], v[210:211], v[84:85], v[214:215]
	v_pk_fma_f32 v[86:87], v[58:59], v[114:115], v[86:87]
	v_pk_fma_f32 v[58:59], v[56:57], v[112:113], v[84:85]
	v_cvt_pk_f16_f32 v56, v60, v61
	v_lshl_add_u64 v[60:61], s[16:17], 0, v[106:107]
	v_cvt_pk_f16_f32 v57, v62, v63
	v_cvt_pk_f16_f32 v58, v58, v59
	v_cvt_pk_f16_f32 v59, v86, v87
	v_lshl_add_u64 v[60:61], v[60:61], 0, v[220:221]
	global_store_dwordx4 v[60:61], v[56:59], off
	v_cvt_f32_f16_e32 v62, v90
	v_cvt_f32_f16_sdwa v63, v90 dst_sel:DWORD dst_unused:UNUSED_PAD src0_sel:WORD_1
	v_cvt_f32_f16_e32 v56, v88
	v_cvt_f32_f16_sdwa v57, v88 dst_sel:DWORD dst_unused:UNUSED_PAD src0_sel:WORD_1
	v_cvt_f32_f16_e32 v58, v89
	v_cvt_f32_f16_sdwa v59, v89 dst_sel:DWORD dst_unused:UNUSED_PAD src0_sel:WORD_1
	v_cvt_f32_f16_e32 v84, v91
	v_cvt_f32_f16_sdwa v85, v91 dst_sel:DWORD dst_unused:UNUSED_PAD src0_sel:WORD_1
	v_sub_f32_e32 v57, v57, v104
	v_sub_f32_e32 v56, v56, v104
	v_sub_f32_e32 v59, v59, v104
	v_sub_f32_e32 v58, v58, v104
	v_pk_mul_f32 v[58:59], v[104:105], v[58:59] op_sel:[1,0]
	v_pk_mul_f32 v[56:57], v[104:105], v[56:57] op_sel:[1,0]
	v_pk_fma_f32 v[58:59], v[196:197], v[58:59], v[200:201]
	v_pk_fma_f32 v[56:57], v[198:199], v[56:57], v[202:203]
	v_pk_fma_f32 v[54:55], v[54:55], v[126:127], v[58:59]
	v_pk_fma_f32 v[52:53], v[52:53], v[124:125], v[56:57]
	v_sub_f32_e32 v57, v63, v104
	v_sub_f32_e32 v56, v62, v104
	v_sub_f32_e32 v59, v85, v104
	v_sub_f32_e32 v58, v84, v104
	v_pk_mul_f32 v[58:59], v[104:105], v[58:59] op_sel:[1,0]
	v_pk_mul_f32 v[56:57], v[104:105], v[56:57] op_sel:[1,0]
	v_pk_fma_f32 v[58:59], v[188:189], v[58:59], v[192:193]
	v_pk_fma_f32 v[56:57], v[190:191], v[56:57], v[194:195]
	v_pk_fma_f32 v[58:59], v[50:51], v[110:111], v[58:59]
	v_pk_fma_f32 v[50:51], v[48:49], v[108:109], v[56:57]
	v_cvt_pk_f16_f32 v48, v52, v53
	v_cvt_pk_f16_f32 v49, v54, v55
	v_cvt_pk_f16_f32 v50, v50, v51
	v_cvt_pk_f16_f32 v51, v58, v59
	global_store_dwordx4 v[60:61], v[48:51], off offset:256
	v_cvt_f32_f16_e32 v52, v94
	v_cvt_f32_f16_sdwa v53, v94 dst_sel:DWORD dst_unused:UNUSED_PAD src0_sel:WORD_1
	v_cvt_f32_f16_e32 v48, v92
	v_cvt_f32_f16_sdwa v49, v92 dst_sel:DWORD dst_unused:UNUSED_PAD src0_sel:WORD_1
	v_cvt_f32_f16_e32 v50, v93
	v_cvt_f32_f16_sdwa v51, v93 dst_sel:DWORD dst_unused:UNUSED_PAD src0_sel:WORD_1
	v_cvt_f32_f16_e32 v54, v95
	v_cvt_f32_f16_sdwa v55, v95 dst_sel:DWORD dst_unused:UNUSED_PAD src0_sel:WORD_1
	v_sub_f32_e32 v49, v49, v116
	v_sub_f32_e32 v48, v48, v116
	v_sub_f32_e32 v51, v51, v116
	v_sub_f32_e32 v50, v50, v116
	v_pk_mul_f32 v[50:51], v[116:117], v[50:51] op_sel:[1,0]
	v_pk_mul_f32 v[48:49], v[116:117], v[48:49] op_sel:[1,0]
	v_pk_fma_f32 v[50:51], v[204:205], v[50:51], v[216:217]
	v_pk_fma_f32 v[48:49], v[206:207], v[48:49], v[218:219]
	v_pk_fma_f32 v[46:47], v[46:47], v[130:131], v[50:51]
	v_pk_fma_f32 v[44:45], v[44:45], v[128:129], v[48:49]
	v_sub_f32_e32 v49, v53, v116
	v_sub_f32_e32 v48, v52, v116
	v_sub_f32_e32 v51, v55, v116
	v_sub_f32_e32 v50, v54, v116
	v_pk_mul_f32 v[50:51], v[116:117], v[50:51] op_sel:[1,0]
	v_pk_mul_f32 v[48:49], v[116:117], v[48:49] op_sel:[1,0]
	v_pk_fma_f32 v[50:51], v[208:209], v[50:51], v[212:213]
	v_pk_fma_f32 v[48:49], v[210:211], v[48:49], v[214:215]
	v_pk_fma_f32 v[50:51], v[42:43], v[114:115], v[50:51]
	v_pk_fma_f32 v[42:43], v[40:41], v[112:113], v[48:49]
	v_cvt_pk_f16_f32 v40, v44, v45
	v_lshl_add_u64 v[44:45], s[16:17], 0, v[118:119]
	v_cvt_pk_f16_f32 v41, v46, v47
	v_cvt_pk_f16_f32 v42, v42, v43
	v_cvt_pk_f16_f32 v43, v50, v51
	v_lshl_add_u64 v[44:45], v[44:45], 0, v[220:221]
	global_store_dwordx4 v[44:45], v[40:43], off
	v_cvt_f32_f16_e32 v46, v98
	v_cvt_f32_f16_sdwa v47, v98 dst_sel:DWORD dst_unused:UNUSED_PAD src0_sel:WORD_1
	v_cvt_f32_f16_e32 v40, v96
	v_cvt_f32_f16_sdwa v41, v96 dst_sel:DWORD dst_unused:UNUSED_PAD src0_sel:WORD_1
	v_cvt_f32_f16_e32 v42, v97
	v_cvt_f32_f16_sdwa v43, v97 dst_sel:DWORD dst_unused:UNUSED_PAD src0_sel:WORD_1
	v_cvt_f32_f16_e32 v48, v99
	v_cvt_f32_f16_sdwa v49, v99 dst_sel:DWORD dst_unused:UNUSED_PAD src0_sel:WORD_1
	v_sub_f32_e32 v41, v41, v116
	v_sub_f32_e32 v40, v40, v116
	v_sub_f32_e32 v43, v43, v116
	v_sub_f32_e32 v42, v42, v116
	v_pk_mul_f32 v[42:43], v[116:117], v[42:43] op_sel:[1,0]
	v_pk_mul_f32 v[40:41], v[116:117], v[40:41] op_sel:[1,0]
	v_pk_fma_f32 v[42:43], v[196:197], v[42:43], v[200:201]
	v_pk_fma_f32 v[40:41], v[198:199], v[40:41], v[202:203]
	v_pk_fma_f32 v[38:39], v[38:39], v[126:127], v[42:43]
; template <class Epi, class Sched>
; __device__ __forceinline__ void gemm_phase(PG8_LAS unsigned char* lds, const Gemm g, const Sched& S, const Epi& E) {
;     ...
;         E(acc, cur, wr, wc, fr, fq); S.done(cur);
;         if (!has_next) break;
; #pragma unroll
;         for (int a = 0; a < 2; ++a)
; #pragma unroll
;             for (int b = 0; b < 2; ++b)
; #pragma unroll
;                 for (int m = 0; m < 4; ++m)
; #pragma unroll
;                     for (int n = 0; n < 2; ++n) acc[a][b][m][n] = (f32x4){0.f, 0.f, 0.f, 0.f};
;         cur = nxt; cA = nA; cB = nB; ++ui;
;     }
;     __device__ __forceinline__ void operator()(const AccT& acc, const pg8::Unit& u, int wr, int wc, int fr, int fq) const {
;     ...
;             for (int m = 0; m < 4; ++m) { const int row = row0 + ai * 128 + m * 16; const size_t off = (size_t)row * D + col0; const f32x2 st = stv[m];
; #pragma unroll
;                 for (int bj = 0; bj < 2; ++bj) { float uf[8]; unpack_h8(uraw[m][bj], uf);
;                     const f32x4 ua = {uf[0], uf[1], uf[2], uf[3]}, ub = {uf[4], uf[5], uf[6], uf[7]};
;                     const f32x4 a = ((ua - st.x) * st.y) * lg[bj][0] + lbv[bj][0] + gv[bj][0] * acc[ai][bj][m][0], b = ((ub - st.x) * st.y) * lg[bj][1] + lbv[bj][1] + gv[bj][1] * acc[ai][bj][m][1];
;                     u32x4 w; w.x = pk_h2(a[0], a[1]); w.y = pk_h2(a[2], a[3]); w.z = pk_h2(b[0], b[1]); w.w = pk_h2(b[2], b[3]);
;                     *(u32x4*)(U2 + off + bj * 128) = w; } }
	v_pk_fma_f32 v[36:37], v[36:37], v[124:125], v[40:41]
	v_sub_f32_e32 v41, v47, v116
	v_sub_f32_e32 v40, v46, v116
	v_sub_f32_e32 v43, v49, v116
	v_sub_f32_e32 v42, v48, v116
	v_pk_mul_f32 v[42:43], v[116:117], v[42:43] op_sel:[1,0]
	v_pk_mul_f32 v[40:41], v[116:117], v[40:41] op_sel:[1,0]
	v_pk_fma_f32 v[42:43], v[188:189], v[42:43], v[192:193]
	v_pk_fma_f32 v[40:41], v[190:191], v[40:41], v[194:195]
	v_pk_fma_f32 v[42:43], v[34:35], v[110:111], v[42:43]
	v_pk_fma_f32 v[34:35], v[32:33], v[108:109], v[40:41]
	v_cvt_pk_f16_f32 v32, v36, v37
	v_cvt_pk_f16_f32 v33, v38, v39
	v_cvt_pk_f16_f32 v34, v34, v35
	v_cvt_pk_f16_f32 v35, v42, v43
	global_store_dwordx4 v[44:45], v[32:35], off offset:256
	v_cvt_f32_f16_e32 v36, v102
	v_cvt_f32_f16_sdwa v37, v102 dst_sel:DWORD dst_unused:UNUSED_PAD src0_sel:WORD_1
	v_cvt_f32_f16_e32 v32, v100
	v_cvt_f32_f16_sdwa v33, v100 dst_sel:DWORD dst_unused:UNUSED_PAD src0_sel:WORD_1
	v_cvt_f32_f16_e32 v34, v101
	v_cvt_f32_f16_sdwa v35, v101 dst_sel:DWORD dst_unused:UNUSED_PAD src0_sel:WORD_1
	v_cvt_f32_f16_e32 v38, v103
	v_cvt_f32_f16_sdwa v39, v103 dst_sel:DWORD dst_unused:UNUSED_PAD src0_sel:WORD_1
	v_sub_f32_e32 v33, v33, v80
	v_sub_f32_e32 v32, v32, v80
	v_sub_f32_e32 v35, v35, v80
	v_sub_f32_e32 v34, v34, v80
	v_pk_mul_f32 v[34:35], v[80:81], v[34:35] op_sel:[1,0]
	v_pk_mul_f32 v[32:33], v[80:81], v[32:33] op_sel:[1,0]
	v_pk_fma_f32 v[34:35], v[204:205], v[34:35], v[216:217]
	v_pk_fma_f32 v[32:33], v[206:207], v[32:33], v[218:219]
	v_pk_fma_f32 v[30:31], v[30:31], v[130:131], v[34:35]
	v_pk_fma_f32 v[28:29], v[28:29], v[128:129], v[32:33]
	v_sub_f32_e32 v33, v37, v80
	v_sub_f32_e32 v32, v36, v80
	v_sub_f32_e32 v35, v39, v80
	v_sub_f32_e32 v34, v38, v80
	v_pk_mul_f32 v[34:35], v[80:81], v[34:35] op_sel:[1,0]
	v_pk_mul_f32 v[32:33], v[80:81], v[32:33] op_sel:[1,0]
	v_pk_fma_f32 v[34:35], v[208:209], v[34:35], v[212:213]
	v_pk_fma_f32 v[32:33], v[210:211], v[32:33], v[214:215]
	v_pk_fma_f32 v[34:35], v[26:27], v[114:115], v[34:35]
	v_pk_fma_f32 v[26:27], v[24:25], v[112:113], v[32:33]
	v_cvt_pk_f16_f32 v24, v28, v29
	v_lshl_add_u64 v[28:29], s[16:17], 0, v[82:83]
	v_cvt_pk_f16_f32 v25, v30, v31
	v_cvt_pk_f16_f32 v26, v26, v27
	v_cvt_pk_f16_f32 v27, v34, v35
	v_lshl_add_u64 v[28:29], v[28:29], 0, v[220:221]
	global_store_dwordx4 v[28:29], v[24:27], off
	v_cvt_f32_f16_e32 v30, v74
	v_cvt_f32_f16_sdwa v31, v74 dst_sel:DWORD dst_unused:UNUSED_PAD src0_sel:WORD_1
	v_cvt_f32_f16_e32 v24, v72
	v_cvt_f32_f16_sdwa v25, v72 dst_sel:DWORD dst_unused:UNUSED_PAD src0_sel:WORD_1
	v_cvt_f32_f16_e32 v26, v73
	v_cvt_f32_f16_sdwa v27, v73 dst_sel:DWORD dst_unused:UNUSED_PAD src0_sel:WORD_1
	v_cvt_f32_f16_e32 v32, v75
	v_cvt_f32_f16_sdwa v33, v75 dst_sel:DWORD dst_unused:UNUSED_PAD src0_sel:WORD_1
	v_sub_f32_e32 v25, v25, v80
	v_sub_f32_e32 v24, v24, v80
	v_sub_f32_e32 v27, v27, v80
	v_sub_f32_e32 v26, v26, v80
	v_pk_mul_f32 v[26:27], v[80:81], v[26:27] op_sel:[1,0]
	v_pk_mul_f32 v[24:25], v[80:81], v[24:25] op_sel:[1,0]
	v_pk_fma_f32 v[26:27], v[196:197], v[26:27], v[200:201]
	v_pk_fma_f32 v[24:25], v[198:199], v[24:25], v[202:203]
	v_pk_fma_f32 v[22:23], v[22:23], v[126:127], v[26:27]
	v_pk_fma_f32 v[20:21], v[20:21], v[124:125], v[24:25]
	v_sub_f32_e32 v25, v31, v80
	v_sub_f32_e32 v24, v30, v80
	v_sub_f32_e32 v27, v33, v80
	v_sub_f32_e32 v26, v32, v80
	v_pk_mul_f32 v[26:27], v[80:81], v[26:27] op_sel:[1,0]
	v_pk_mul_f32 v[24:25], v[80:81], v[24:25] op_sel:[1,0]
	v_pk_fma_f32 v[26:27], v[188:189], v[26:27], v[192:193]
	v_pk_fma_f32 v[24:25], v[190:191], v[24:25], v[194:195]
	v_pk_fma_f32 v[26:27], v[18:19], v[110:111], v[26:27]
	v_pk_fma_f32 v[18:19], v[16:17], v[108:109], v[24:25]
	v_cvt_pk_f16_f32 v16, v20, v21
	v_cvt_pk_f16_f32 v17, v22, v23
	v_cvt_pk_f16_f32 v18, v18, v19
	v_cvt_pk_f16_f32 v19, v26, v27
	global_store_dwordx4 v[28:29], v[16:19], off offset:256
	v_cvt_f32_f16_e32 v20, v70
	v_cvt_f32_f16_sdwa v21, v70 dst_sel:DWORD dst_unused:UNUSED_PAD src0_sel:WORD_1
	v_cvt_f32_f16_e32 v16, v68
	v_cvt_f32_f16_sdwa v17, v68 dst_sel:DWORD dst_unused:UNUSED_PAD src0_sel:WORD_1
	v_cvt_f32_f16_e32 v18, v69
	v_cvt_f32_f16_sdwa v19, v69 dst_sel:DWORD dst_unused:UNUSED_PAD src0_sel:WORD_1
	v_cvt_f32_f16_e32 v22, v71
	v_cvt_f32_f16_sdwa v23, v71 dst_sel:DWORD dst_unused:UNUSED_PAD src0_sel:WORD_1
	v_sub_f32_e32 v17, v17, v76
	v_sub_f32_e32 v16, v16, v76
	v_sub_f32_e32 v19, v19, v76
	v_sub_f32_e32 v18, v18, v76
	v_pk_mul_f32 v[18:19], v[76:77], v[18:19] op_sel:[1,0]
	v_pk_mul_f32 v[16:17], v[76:77], v[16:17] op_sel:[1,0]
	v_pk_fma_f32 v[18:19], v[204:205], v[18:19], v[216:217]
	v_pk_fma_f32 v[16:17], v[206:207], v[16:17], v[218:219]
	v_pk_fma_f32 v[14:15], v[14:15], v[130:131], v[18:19]
	v_pk_fma_f32 v[12:13], v[12:13], v[128:129], v[16:17]
	v_sub_f32_e32 v17, v21, v76
	v_sub_f32_e32 v16, v20, v76
	v_sub_f32_e32 v19, v23, v76
	v_sub_f32_e32 v18, v22, v76
	v_pk_mul_f32 v[18:19], v[76:77], v[18:19] op_sel:[1,0]
	v_pk_mul_f32 v[16:17], v[76:77], v[16:17] op_sel:[1,0]
	v_pk_fma_f32 v[18:19], v[208:209], v[18:19], v[212:213]
	v_pk_fma_f32 v[16:17], v[210:211], v[16:17], v[214:215]
	v_pk_fma_f32 v[18:19], v[10:11], v[114:115], v[18:19]
	v_pk_fma_f32 v[10:11], v[8:9], v[112:113], v[16:17]
	v_cvt_pk_f16_f32 v8, v12, v13
	v_lshl_add_u64 v[12:13], s[16:17], 0, v[78:79]
	v_cvt_pk_f16_f32 v9, v14, v15
	v_cvt_pk_f16_f32 v10, v10, v11
	v_cvt_pk_f16_f32 v11, v18, v19
	v_lshl_add_u64 v[12:13], v[12:13], 0, v[220:221]
	global_store_dwordx4 v[12:13], v[8:11], off
	v_cvt_f32_f16_e32 v14, v66
	v_cvt_f32_f16_sdwa v15, v66 dst_sel:DWORD dst_unused:UNUSED_PAD src0_sel:WORD_1
	v_cvt_f32_f16_e32 v8, v64
	v_cvt_f32_f16_sdwa v9, v64 dst_sel:DWORD dst_unused:UNUSED_PAD src0_sel:WORD_1
	v_cvt_f32_f16_e32 v10, v65
	v_cvt_f32_f16_sdwa v11, v65 dst_sel:DWORD dst_unused:UNUSED_PAD src0_sel:WORD_1
	v_cvt_f32_f16_e32 v16, v67
	v_cvt_f32_f16_sdwa v17, v67 dst_sel:DWORD dst_unused:UNUSED_PAD src0_sel:WORD_1
	v_sub_f32_e32 v9, v9, v76
	v_sub_f32_e32 v8, v8, v76
	v_sub_f32_e32 v11, v11, v76
	v_sub_f32_e32 v10, v10, v76
	v_pk_mul_f32 v[10:11], v[76:77], v[10:11] op_sel:[1,0]
	v_pk_mul_f32 v[8:9], v[76:77], v[8:9] op_sel:[1,0]
	v_pk_fma_f32 v[10:11], v[196:197], v[10:11], v[200:201]
	v_pk_fma_f32 v[8:9], v[198:199], v[8:9], v[202:203]
	v_pk_fma_f32 v[6:7], v[6:7], v[126:127], v[10:11]
	v_pk_fma_f32 v[4:5], v[4:5], v[124:125], v[8:9]
	v_sub_f32_e32 v9, v15, v76
	v_sub_f32_e32 v8, v14, v76
	v_sub_f32_e32 v11, v17, v76
	v_sub_f32_e32 v10, v16, v76
	v_pk_mul_f32 v[10:11], v[76:77], v[10:11] op_sel:[1,0]
	v_pk_mul_f32 v[8:9], v[76:77], v[8:9] op_sel:[1,0]
	v_pk_fma_f32 v[10:11], v[188:189], v[10:11], v[192:193]
	v_pk_fma_f32 v[8:9], v[190:191], v[8:9], v[194:195]
	v_pk_fma_f32 v[10:11], v[2:3], v[110:111], v[10:11]
	v_pk_fma_f32 v[2:3], v[0:1], v[108:109], v[8:9]
	v_cvt_pk_f16_f32 v0, v4, v5
	v_cvt_pk_f16_f32 v1, v6, v7
	v_cvt_pk_f16_f32 v2, v2, v3
	v_cvt_pk_f16_f32 v3, v10, v11
	global_store_dwordx4 v[12:13], v[0:3], off offset:256
	s_cbranch_vccz .LBB0_871
	s_waitcnt vmcnt(0)
	s_cmpk_gt_u32 s21, 0xff
	s_cbranch_scc1 .LBB0_886
	s_barrier
